# attention loops (DA, GQA): packed f32 mul/add split into plain f32 ops
# baseline (speedup 1.0000x reference)
; #define MFMA32(a, b, c) __builtin_amdgcn_mfma_f32_32x32x16_bf16((a), (b), (c), 0, 0, 0)
; template <int D>
; DI void attn_pass(const bfr* __restrict__ P, int b, int tq_wave, int qcol, int kcol, int vcol, int key0, int nkt, char* smem, f32x16 (&o)[2]) {
;     ...
;     { int c = gt, row = c >> 3, kc = c & 7; *(u32x4*)(sK + row * KP + kc * 8) = kreg[0]; }
;     for (int i = 0; i < 1; ++i) {
;       int c = gt, row = c >> 3, kc = c & 7;
;       unsigned wds[4] = {vreg[i].x, vreg[i].y, vreg[i].z, vreg[i].w};
; #pragma unroll
;       for (int e = 0; e < 4; ++e) {
;         sV[(kc * 8 + 2 * e) * 72 + (row ^ (kc << 3))] = (bfr)(wds[e] & 0xffffu);
;         sV[(kc * 8 + 2 * e + 1) * 72 + (row ^ (kc << 3))] = (bfr)(wds[e] >> 16);
;       }
;     }
;     __syncthreads();
;     if (kt + 1 < nkt) {
;       const bfr* Pn = Pb + (size_t)(kt + 1) * 64 * PW;
;       { int c = gt, row = c >> 3, kc = c & 7; kreg[0] = *(const u32x4*)(Pn + (size_t)row * PW + kcol + kc * 8); vreg[0] = *(const u32x4*)(Pn + (size_t)row * PW + vcol + kc * 8); }
;     }
;     f32x16 s[2];
; #pragma unroll
;     for (int t2 = 0; t2 < 2; ++t2) {
; #pragma unroll
;       for (int i = 0; i < 16; ++i) s[t2][i] = 0.f;
; #pragma unroll
;       for (int ks = 0; ks < KS; ++ks) {
;         bf16x8 a = *(const bf16x8*)(sK + (t2 * 32 + r) * KP + ks * 16 + h * 8);
;         s[t2] = MFMA32(a, qf[ks], s[t2]);
;       }
;     }
;     float mx = s[0][0];
; #pragma unroll
;     for (int i = 0; i < 16; ++i) { mx = fmaxf(mx, s[0][i]); mx = fmaxf(mx, s[1][i]); }
;     mx = fmaxf(mx, __shfl_xor(mx, 32));
;     float mnew = fmaxf(mrun, mx);
;     float alpha = __builtin_amdgcn_exp2f(mrun - mnew);
;     mrun = mnew;
;     float ps = 0.f;
; #pragma unroll
;     for (int i = 0; i < 16; ++i) {
;       s[0][i] = __builtin_amdgcn_exp2f(s[0][i] - mnew); ps += s[0][i];
;       s[1][i] = __builtin_amdgcn_exp2f(s[1][i] - mnew); ps += s[1][i];
;     }
;     lsum = lsum * alpha + ps;
; #pragma unroll
;     for (int i = 0; i < 16; ++i) { accO[0][i] *= alpha; accO[1][i] *= alpha; }
; #pragma unroll
;     for (int t2 = 0; t2 < 2; ++t2)
; #pragma unroll
;       for (int j = 0; j < 2; ++j) {
;         unsigned pk[4];
; #pragma unroll
;         for (int e = 0; e < 4; ++e) pk[e] = pack2(s[t2][8 * j + 2 * e], s[t2][8 * j + 2 * e + 1]);
;         u32x4 pku = {pk[0], pk[1], pk[2], pk[3]};
;         bf16x8 pf = __builtin_bit_cast(bf16x8, pku);
.LBB0_400:
	s_bitcmp1_b32 s10, 0
	s_cselect_b32 s11, 0x4800, 0
	s_add_i32 s11, s11, 0
	v_add3_u32 v32, s11, v115, v90
	v_add_u32_e32 v121, s11, v114
	v_mov_b32_e32 v120, v113
	s_waitcnt vmcnt(1)
	ds_write_b128 v32, v[84:87]
	v_add3_u32 v32, s11, v117, v118
	v_add3_u32 v33, s11, v118, v117
	v_add_u32_e32 v113, v121, v152
	s_waitcnt vmcnt(0)
	ds_write_b16 v32, v80 offset:9216
	ds_write_b16_d16_hi v33, v80 offset:9360
	ds_write_b16 v32, v81 offset:9504
	ds_write_b16_d16_hi v33, v81 offset:9648
	ds_write_b16 v32, v82 offset:9792
	ds_write_b16_d16_hi v33, v82 offset:9936
	ds_write_b16 v32, v83 offset:10080
	ds_write_b16_d16_hi v33, v83 offset:10224
	s_waitcnt lgkmcnt(0)
	s_barrier
	global_load_dwordx4 v[84:87], v[92:93], off
	global_load_dwordx4 v[80:83], v[94:95], off
	ds_read_b128 v[32:35], v113
	ds_read_b128 v[48:51], v113 offset:32
	s_waitcnt lgkmcnt(1)
	v_mfma_f32_32x32x16_bf16 v[32:47], v[32:35], v[76:79], 0
	ds_read_b128 v[122:125], v113 offset:4640
	v_mov_b32_e32 v96, v119
	s_add_i32 s10, s10, 1
	v_lshl_add_u64 v[92:93], v[92:93], 0, s[12:13]
	v_lshl_add_u64 v[94:95], v[94:95], 0, s[12:13]
	s_cmp_lg_u32 s10, 3
	s_waitcnt lgkmcnt(1)
	v_mfma_f32_32x32x16_bf16 v[32:47], v[48:51], v[72:75], v[32:47]
	ds_read_b128 v[48:51], v113 offset:64
	s_waitcnt lgkmcnt(0)
	v_mfma_f32_32x32x16_bf16 v[32:47], v[48:51], v[68:71], v[32:47]
	ds_read_b128 v[48:51], v113 offset:96
	s_waitcnt lgkmcnt(0)
	v_mfma_f32_32x32x16_bf16 v[32:47], v[48:51], v[64:67], v[32:47]
	ds_read_b128 v[48:51], v113 offset:4608
	s_waitcnt lgkmcnt(0)
	v_mfma_f32_32x32x16_bf16 v[48:63], v[48:51], v[76:79], 0
	s_nop 8
	v_max_f32_e32 v119, v32, v32
	v_mfma_f32_32x32x16_bf16 v[48:63], v[122:125], v[72:75], v[48:63]
	ds_read_b128 v[122:125], v113 offset:4672
	s_waitcnt lgkmcnt(0)
	v_mfma_f32_32x32x16_bf16 v[48:63], v[122:125], v[68:71], v[48:63]
	ds_read_b128 v[122:125], v113 offset:4704
	s_waitcnt lgkmcnt(0)
	v_mfma_f32_32x32x16_bf16 v[48:63], v[122:125], v[64:67], v[48:63]
	s_nop 11
	v_max_f32_e32 v113, v48, v48
	v_max_f32_e32 v113, v119, v113
	v_max3_f32 v113, v113, v33, v49
	v_max3_f32 v113, v113, v34, v50
	v_max3_f32 v113, v113, v35, v51
	v_max3_f32 v113, v113, v36, v52
	v_max3_f32 v113, v113, v37, v53
	v_max3_f32 v113, v113, v38, v54
	v_max3_f32 v113, v113, v39, v55
	v_max3_f32 v113, v113, v40, v56
	v_max3_f32 v113, v113, v41, v57
	v_max3_f32 v113, v113, v42, v58
	v_max3_f32 v113, v113, v43, v59
	v_max3_f32 v113, v113, v44, v60
	v_max3_f32 v113, v113, v45, v61
	v_max3_f32 v113, v113, v46, v62
	v_max3_f32 v113, v113, v47, v63
	ds_bpermute_b32 v119, v91, v113
	s_waitcnt lgkmcnt(0)
	v_max3_f32 v119, v96, v113, v119
	v_sub_f32_e32 v32, v32, v119
	v_sub_f32_e32 v38, v38, v119
	v_exp_f32_e32 v32, v32
	v_sub_f32_e32 v48, v48, v119
	v_sub_f32_e32 v36, v36, v119
	v_exp_f32_e32 v124, v38
	v_sub_f32_e32 v38, v54, v119
	v_exp_f32_e32 v48, v48
	v_sub_f32_e32 v33, v33, v119
	v_exp_f32_e32 v122, v36
	v_sub_f32_e32 v36, v52, v119
	v_exp_f32_e32 v52, v38
	v_sub_f32_e32 v38, v39, v119
	v_exp_f32_e32 v33, v33
	v_sub_f32_e32 v49, v49, v119
	v_sub_f32_e32 v37, v37, v119
	v_exp_f32_e32 v125, v38
	v_sub_f32_e32 v38, v55, v119
	v_exp_f32_e32 v49, v49
	v_sub_f32_e32 v34, v34, v119
	v_exp_f32_e32 v123, v37
	v_sub_f32_e32 v37, v53, v119
	v_exp_f32_e32 v53, v38
	v_sub_f32_e32 v38, v40, v119
	v_sub_f32_e32 v40, v42, v119
	v_sub_f32_e32 v42, v44, v119
	v_exp_f32_e32 v34, v34
	v_sub_f32_e32 v50, v50, v119
	v_exp_f32_e32 v54, v38
	v_sub_f32_e32 v38, v56, v119
	v_exp_f32_e32 v56, v40
	v_sub_f32_e32 v40, v58, v119
	v_exp_f32_e32 v58, v42
	v_sub_f32_e32 v42, v60, v119
	v_add_f32_e32 v60, 0, v32
	v_exp_f32_e32 v50, v50
	v_sub_f32_e32 v35, v35, v119
	v_add_f32_e32 v60, v48, v60
	v_exp_f32_e32 v35, v35
	v_sub_f32_e32 v51, v51, v119
	v_add_f32_e32 v60, v33, v60
	v_exp_f32_e32 v51, v51
	v_add_f32_e32 v60, v49, v60
	v_add_f32_e32 v60, v34, v60
	v_exp_f32_e32 v36, v36
	v_add_f32_e32 v60, v50, v60
	v_add_f32_e32 v60, v35, v60
	v_exp_f32_e32 v37, v37
	v_add_f32_e32 v60, v51, v60
	v_add_f32_e32 v60, v122, v60
	v_add_f32_e32 v60, v36, v60
	v_add_f32_e32 v60, v123, v60
	v_add_f32_e32 v60, v37, v60
	v_add_f32_e32 v60, v124, v60
	v_exp_f32_e32 v38, v38
	v_sub_f32_e32 v39, v41, v119
	v_add_f32_e32 v60, v52, v60
	v_exp_f32_e32 v55, v39
	v_sub_f32_e32 v39, v57, v119
	v_add_f32_e32 v60, v125, v60
	v_exp_f32_e32 v39, v39
	v_add_f32_e32 v60, v53, v60
	v_add_f32_e32 v60, v54, v60
	v_exp_f32_e32 v40, v40
	v_sub_f32_e32 v41, v43, v119
	v_add_f32_e32 v60, v38, v60
	v_exp_f32_e32 v57, v41
	v_sub_f32_e32 v41, v59, v119
	v_add_f32_e32 v60, v55, v60
	v_exp_f32_e32 v41, v41
	v_add_f32_e32 v60, v39, v60
	v_add_f32_e32 v60, v56, v60
	v_exp_f32_e32 v42, v42
	v_sub_f32_e32 v43, v45, v119
	v_add_f32_e32 v60, v40, v60
	v_exp_f32_e32 v59, v43
	v_sub_f32_e32 v43, v61, v119
	v_add_f32_e32 v60, v57, v60
	v_exp_f32_e32 v43, v43
	v_sub_f32_e32 v44, v46, v119
	v_add_f32_e32 v60, v41, v60
	v_exp_f32_e32 v46, v44
	v_sub_f32_e32 v44, v62, v119
	v_add_f32_e32 v60, v58, v60
	v_exp_f32_e32 v44, v44
	v_sub_f32_e32 v45, v47, v119
	v_add_f32_e32 v60, v42, v60
	v_exp_f32_e32 v47, v45
	v_sub_f32_e32 v45, v63, v119
	v_add_f32_e32 v60, v59, v60
	v_exp_f32_e32 v45, v45
	v_add_f32_e32 v60, v43, v60
	v_add_f32_e32 v60, v46, v60
	v_add_f32_e32 v60, v44, v60
	v_add_f32_e32 v60, v47, v60
	v_add_f32_e32 v113, v45, v60
	v_lshl_add_u32 v60, v112, 1, v121
	v_lshl_add_u32 v61, v111, 1, v121
	v_cvt_pk_bf16_f32 v32, v32, v33
	v_cvt_pk_bf16_f32 v33, v34, v35
	v_cvt_pk_bf16_f32 v34, v122, v123
	v_cvt_pk_bf16_f32 v35, v124, v125
	ds_read_b64 v[122:123], v60 offset:9216
	ds_read_b64 v[124:125], v61 offset:9216
	v_sub_f32_e32 v96, v96, v119
	v_exp_f32_e32 v96, v96
	v_add_u32_e32 v61, s11, v116
	v_lshl_add_u32 v62, v110, 1, v61
	v_mul_f32_e32 v30, v30, v96
	v_mul_f32_e32 v31, v31, v96
	v_mul_f32_e32 v28, v28, v96
	v_mul_f32_e32 v29, v29, v96
	v_mul_f32_e32 v26, v26, v96
	v_mul_f32_e32 v27, v27, v96
	v_mul_f32_e32 v24, v24, v96
	v_mul_f32_e32 v25, v25, v96
	v_mul_f32_e32 v22, v22, v96
	v_mul_f32_e32 v23, v23, v96
	v_mul_f32_e32 v20, v20, v96
	v_mul_f32_e32 v21, v21, v96
	v_mul_f32_e32 v18, v18, v96
	v_mul_f32_e32 v19, v19, v96
	v_mul_f32_e32 v16, v16, v96
	v_mul_f32_e32 v17, v17, v96
	v_mul_f32_e32 v14, v14, v96
	v_mul_f32_e32 v15, v15, v96
	v_mul_f32_e32 v12, v12, v96
	v_mul_f32_e32 v13, v13, v96
	s_waitcnt lgkmcnt(0)
; template <int D>
; DI void attn_pass(const bfr* __restrict__ P, int b, int tq_wave, int qcol, int kcol, int vcol, int key0, int nkt, char* smem, f32x16 (&o)[2]) {
;     ...
;     { int c = gt, row = c >> 3, kc = c & 7; *(u32x4*)(sK + row * KP + kc * 8) = kreg[0]; }
;     for (int i = 0; i < 1; ++i) {
;       int c = gt, row = c >> 3, kc = c & 7;
;       unsigned wds[4] = {vreg[i].x, vreg[i].y, vreg[i].z, vreg[i].w};
; #pragma unroll
;       for (int e = 0; e < 4; ++e) {
;         sV[(kc * 8 + 2 * e) * 72 + (row ^ (kc << 3))] = (bfr)(wds[e] & 0xffffu);
;         sV[(kc * 8 + 2 * e + 1) * 72 + (row ^ (kc << 3))] = (bfr)(wds[e] >> 16);
;       }
;     }
;     __syncthreads();
;     if (kt + 1 < nkt) {
;       const bfr* Pn = Pb + (size_t)(kt + 1) * 64 * PW;
;       { int c = gt, row = c >> 3, kc = c & 7; kreg[0] = *(const u32x4*)(Pn + (size_t)row * PW + kcol + kc * 8); vreg[0] = *(const u32x4*)(Pn + (size_t)row * PW + vcol + kc * 8); }
;     }
;     f32x16 s[2];
; #pragma unroll
;     for (int t2 = 0; t2 < 2; ++t2) {
; #pragma unroll
;       for (int i = 0; i < 16; ++i) s[t2][i] = 0.f;
; #pragma unroll
;       for (int ks = 0; ks < KS; ++ks) {
;         bf16x8 a = *(const bf16x8*)(sK + (t2 * 32 + r) * KP + ks * 16 + h * 8);
;         s[t2] = MFMA32(a, qf[ks], s[t2]);
;       }
;     }
;     float mx = s[0][0];
; #pragma unroll
;     for (int i = 0; i < 16; ++i) { mx = fmaxf(mx, s[0][i]); mx = fmaxf(mx, s[1][i]); }
;     ...
;     for (int i = 0; i < 16; ++i) { accO[0][i] *= alpha; accO[1][i] *= alpha; }
; #pragma unroll
;     for (int t2 = 0; t2 < 2; ++t2)
; #pragma unroll
;       for (int j = 0; j < 2; ++j) {
;         unsigned pk[4];
; #pragma unroll
;         for (int e = 0; e < 4; ++e) pk[e] = pack2(s[t2][8 * j + 2 * e], s[t2][8 * j + 2 * e + 1]);
;         u32x4 pku = {pk[0], pk[1], pk[2], pk[3]};
;         bf16x8 pf = __builtin_bit_cast(bf16x8, pku);
; #pragma unroll
;         for (int dt = 0; dt < 2; ++dt) {
;           const int vsw = (((dt * 32 + r) >> 3) & 7) << 3;
;           const bfr* vrow = sV + (dt * 32 + r) * 72;
;           s16x4 lo = *(const s16x4*)(vrow + ((t2 * 32 + 16 * j + 4 * h) ^ vsw));
;           s16x4 hi = *(const s16x4*)(vrow + ((t2 * 32 + 16 * j + 4 * h + 8) ^ vsw));
;           bf16x8 vf = __builtin_shufflevector(lo, hi, 0, 1, 2, 3, 4, 5, 6, 7);
;           accO[dt] = MFMA32(vf, pf, accO[dt]);
;         }
;       }
	v_mfma_f32_32x32x16_bf16 v[16:31], v[122:125], v[32:35], v[16:31]
	ds_read_b64 v[122:123], v62 offset:9216
	v_lshl_add_u32 v62, v109, 1, v61
	ds_read_b64 v[124:125], v62 offset:9216
	v_mul_f32_e64 v10, v10, v96
	v_mul_f32_e64 v11, v11, v96
	v_mul_f32_e32 v8, v8, v96
	v_mul_f32_e32 v9, v9, v96
	v_mul_f32_e32 v6, v6, v96
	v_mul_f32_e32 v7, v7, v96
	v_mul_f32_e32 v4, v4, v96
	v_mul_f32_e32 v5, v5, v96
	v_mul_f32_e32 v2, v2, v96
	v_mul_f32_e32 v3, v3, v96
	v_mul_f32_e32 v0, v0, v96
	v_mul_f32_e32 v1, v1, v96
	v_fmac_f32_e32 v113, v120, v96
	s_waitcnt lgkmcnt(0)
	v_mfma_f32_32x32x16_bf16 v[0:15], v[122:125], v[32:35], v[0:15]
	v_cvt_pk_bf16_f32 v32, v54, v55
	v_cvt_pk_bf16_f32 v33, v56, v57
	v_cvt_pk_bf16_f32 v34, v58, v59
	v_cvt_pk_bf16_f32 v35, v46, v47
	v_lshl_add_u32 v46, v108, 1, v121
	ds_read_b64 v[54:55], v46 offset:9216
	v_lshl_add_u32 v46, v107, 1, v121
	ds_read_b64 v[56:57], v46 offset:9216
	v_lshl_add_u32 v46, v106, 1, v61
	s_waitcnt lgkmcnt(0)
	v_mfma_f32_32x32x16_bf16 v[16:31], v[54:57], v[32:35], v[16:31]
	ds_read_b64 v[54:55], v46 offset:9216
	v_lshl_add_u32 v46, v105, 1, v61
	ds_read_b64 v[56:57], v46 offset:9216
	s_waitcnt lgkmcnt(0)
	v_mfma_f32_32x32x16_bf16 v[0:15], v[54:57], v[32:35], v[0:15]
	v_cvt_pk_bf16_f32 v32, v48, v49
	v_cvt_pk_bf16_f32 v33, v50, v51
	v_cvt_pk_bf16_f32 v34, v36, v37
	v_lshl_add_u32 v36, v104, 1, v121
	v_cvt_pk_bf16_f32 v35, v52, v53
	ds_read_b64 v[46:47], v60 offset:9280
	ds_read_b64 v[48:49], v36 offset:9216
	v_lshl_add_u32 v36, v103, 1, v61
	s_waitcnt lgkmcnt(0)
	v_mfma_f32_32x32x16_bf16 v[16:31], v[46:49], v[32:35], v[16:31]
	ds_read_b64 v[46:47], v36 offset:9216
	v_lshl_add_u32 v36, v102, 1, v61
	ds_read_b64 v[48:49], v36 offset:9216
	v_lshl_add_u32 v36, v100, 1, v121
	s_waitcnt lgkmcnt(0)
	v_mfma_f32_32x32x16_bf16 v[0:15], v[46:49], v[32:35], v[0:15]
	v_cvt_pk_bf16_f32 v32, v38, v39
	v_lshl_add_u32 v38, v101, 1, v121
	v_cvt_pk_bf16_f32 v33, v40, v41
	v_cvt_pk_bf16_f32 v34, v42, v43
	v_cvt_pk_bf16_f32 v35, v44, v45
	ds_read_b64 v[36:37], v36 offset:9216
	ds_read_b64 v[38:39], v38 offset:9216
	s_waitcnt lgkmcnt(0)
	v_mfma_f32_32x32x16_bf16 v[16:31], v[36:39], v[32:35], v[16:31]
	v_lshl_add_u32 v36, v99, 1, v61
	v_lshl_add_u32 v38, v98, 1, v61
	ds_read_b64 v[36:37], v36 offset:9216
	ds_read_b64 v[38:39], v38 offset:9216
	s_waitcnt lgkmcnt(0)
	v_mfma_f32_32x32x16_bf16 v[0:15], v[36:39], v[32:35], v[0:15]
	s_cbranch_scc1 .LBB0_400
	v_add3_u32 v32, 0, v115, v90
	s_waitcnt vmcnt(1)
	ds_write_b128 v32, v[84:87] offset:18432
	v_add3_u32 v32, 0, v117, v118
	v_add3_u32 v33, 0, v118, v117
	s_waitcnt vmcnt(0)
	ds_write_b16 v32, v80 offset:27648
	ds_write_b16_d16_hi v33, v80 offset:27792
	ds_write_b16 v32, v81 offset:27936
	ds_write_b16_d16_hi v33, v81 offset:28080
	ds_write_b16 v32, v82 offset:28224
	ds_write_b16_d16_hi v33, v82 offset:28368
	ds_write_b16 v32, v83 offset:28512
	ds_write_b16_d16_hi v33, v83 offset:28656
	v_add_u32_e32 v80, 0, v114
	v_add_u32_e32 v81, v80, v152
	s_waitcnt lgkmcnt(0)
	s_barrier
	ds_read_b128 v[32:35], v81 offset:18432
	ds_read_b128 v[48:51], v81 offset:18464
	s_waitcnt lgkmcnt(1)
	v_mfma_f32_32x32x16_bf16 v[32:47], v[32:35], v[76:79], 0
	v_lshlrev_b32_e32 v152, 1, v88
	s_waitcnt lgkmcnt(0)
	v_mfma_f32_32x32x16_bf16 v[32:47], v[48:51], v[72:75], v[32:47]
	ds_read_b128 v[48:51], v81 offset:18496
	s_waitcnt lgkmcnt(0)
	v_mfma_f32_32x32x16_bf16 v[32:47], v[48:51], v[68:71], v[32:47]
	ds_read_b128 v[48:51], v81 offset:18528
	s_waitcnt lgkmcnt(0)
	v_mfma_f32_32x32x16_bf16 v[32:47], v[48:51], v[64:67], v[32:47]
	ds_read_b128 v[48:51], v81 offset:23040
	s_waitcnt lgkmcnt(0)
	v_mfma_f32_32x32x16_bf16 v[48:63], v[48:51], v[76:79], 0
	ds_read_b128 v[76:79], v81 offset:23072
	s_waitcnt lgkmcnt(0)
	v_mfma_f32_32x32x16_bf16 v[48:63], v[76:79], v[72:75], v[48:63]
	ds_read_b128 v[72:75], v81 offset:23104
	s_waitcnt lgkmcnt(0)
	v_mfma_f32_32x32x16_bf16 v[48:63], v[72:75], v[68:71], v[48:63]
	ds_read_b128 v[68:71], v81 offset:23136
	s_waitcnt lgkmcnt(0)
	v_mfma_f32_32x32x16_bf16 v[48:63], v[68:71], v[64:67], v[48:63]
	v_max_f32_e32 v65, v32, v32
	v_lshl_add_u32 v66, v112, 1, v80
	v_add_u32_e32 v67, 0x1200, v80
	s_nop 8
	v_max_f32_e32 v64, v48, v48
	v_max_f32_e32 v64, v65, v64
	v_max3_f32 v64, v64, v33, v49
	v_max3_f32 v64, v64, v34, v50
	v_max3_f32 v64, v64, v35, v51
	v_max3_f32 v64, v64, v36, v52
	v_max3_f32 v64, v64, v37, v53
	v_max3_f32 v64, v64, v38, v54
	v_max3_f32 v64, v64, v39, v55
	v_max3_f32 v64, v64, v40, v56
	v_max3_f32 v64, v64, v41, v57
	v_max3_f32 v64, v64, v42, v58
	v_max3_f32 v64, v64, v43, v59
	v_max3_f32 v64, v64, v44, v60
	v_max3_f32 v64, v64, v45, v61
	v_max3_f32 v64, v64, v46, v62
	v_max3_f32 v64, v64, v47, v63
	ds_bpermute_b32 v65, v91, v64
	s_waitcnt lgkmcnt(0)
; #define MFMA32(a, b, c) __builtin_amdgcn_mfma_f32_32x32x16_bf16((a), (b), (c), 0, 0, 0)
; DI unsigned pack2(float a, float b) { unsigned r; asm volatile("v_cvt_pk_bf16_f32 %0, %1, %2" : "=v"(r) : "v"(a), "v"(b)); return r; }
; template <int D>
; DI void attn_pass(const bfr* __restrict__ P, int b, int tq_wave, int qcol, int kcol, int vcol, int key0, int nkt, char* smem, f32x16 (&o)[2]) {
;     ...
;     mx = fmaxf(mx, __shfl_xor(mx, 32));
;     float mnew = fmaxf(mrun, mx);
;     float alpha = __builtin_amdgcn_exp2f(mrun - mnew);
;     mrun = mnew;
;     float ps = 0.f;
; #pragma unroll
;     for (int i = 0; i < 16; ++i) {
;       s[0][i] = __builtin_amdgcn_exp2f(s[0][i] - mnew); ps += s[0][i];
;       s[1][i] = __builtin_amdgcn_exp2f(s[1][i] - mnew); ps += s[1][i];
;     }
;     lsum = lsum * alpha + ps;
; #pragma unroll
;     for (int i = 0; i < 16; ++i) { accO[0][i] *= alpha; accO[1][i] *= alpha; }
; #pragma unroll
;     for (int t2 = 0; t2 < 2; ++t2)
; #pragma unroll
;       for (int j = 0; j < 2; ++j) {
;         unsigned pk[4];
; #pragma unroll
;         for (int e = 0; e < 4; ++e) pk[e] = pack2(s[t2][8 * j + 2 * e], s[t2][8 * j + 2 * e + 1]);
;         u32x4 pku = {pk[0], pk[1], pk[2], pk[3]};
;         bf16x8 pf = __builtin_bit_cast(bf16x8, pku);
; #pragma unroll
;         for (int dt = 0; dt < 2; ++dt) {
;           const int vsw = (((dt * 32 + r) >> 3) & 7) << 3;
;           const bfr* vrow = sV + (dt * 32 + r) * 72;
;           s16x4 lo = *(const s16x4*)(vrow + ((t2 * 32 + 16 * j + 4 * h) ^ vsw));
;           s16x4 hi = *(const s16x4*)(vrow + ((t2 * 32 + 16 * j + 4 * h + 8) ^ vsw));
;           bf16x8 vf = __builtin_shufflevector(lo, hi, 0, 1, 2, 3, 4, 5, 6, 7);
;           accO[dt] = MFMA32(vf, pf, accO[dt]);
;         }
;       }
	v_max3_f32 v65, v119, v64, v65
	v_sub_f32_e32 v64, v119, v65
	v_sub_f32_e32 v32, v32, v65
	v_exp_f32_e32 v64, v64
	v_exp_f32_e32 v32, v32
	v_sub_f32_e32 v48, v48, v65
	v_exp_f32_e32 v48, v48
	v_sub_f32_e32 v33, v33, v65
	v_exp_f32_e32 v33, v33
	v_sub_f32_e32 v49, v49, v65
	v_exp_f32_e32 v49, v49
	v_sub_f32_e32 v34, v34, v65
	v_exp_f32_e32 v34, v34
	v_sub_f32_e32 v50, v50, v65
	v_sub_f32_e32 v35, v35, v65
	v_sub_f32_e32 v51, v51, v65
	v_sub_f32_e32 v36, v36, v65
	v_sub_f32_e32 v52, v52, v65
	v_sub_f32_e32 v37, v37, v65
	v_sub_f32_e32 v53, v53, v65
	v_sub_f32_e32 v38, v38, v65
	v_sub_f32_e32 v54, v54, v65
	v_sub_f32_e32 v39, v39, v65
	v_sub_f32_e32 v55, v55, v65
	v_sub_f32_e32 v40, v40, v65
	v_sub_f32_e32 v56, v56, v65
	v_sub_f32_e32 v41, v41, v65
	v_sub_f32_e32 v57, v57, v65
	v_sub_f32_e32 v42, v42, v65
	v_sub_f32_e32 v58, v58, v65
	v_sub_f32_e32 v43, v43, v65
	v_sub_f32_e32 v59, v59, v65
	v_sub_f32_e32 v44, v44, v65
	v_sub_f32_e32 v60, v60, v65
	v_sub_f32_e32 v45, v45, v65
	v_sub_f32_e32 v61, v61, v65
	v_sub_f32_e32 v46, v46, v65
	v_sub_f32_e32 v62, v62, v65
	v_sub_f32_e32 v47, v47, v65
	v_sub_f32_e32 v63, v63, v65
	v_pk_mul_f32 v[30:31], v[30:31], v[64:65] op_sel_hi:[1,0]
	v_pk_mul_f32 v[28:29], v[28:29], v[64:65] op_sel_hi:[1,0]
	v_pk_mul_f32 v[26:27], v[26:27], v[64:65] op_sel_hi:[1,0]
	v_pk_mul_f32 v[24:25], v[24:25], v[64:65] op_sel_hi:[1,0]
	v_pk_mul_f32 v[22:23], v[22:23], v[64:65] op_sel_hi:[1,0]
	v_pk_mul_f32 v[20:21], v[20:21], v[64:65] op_sel_hi:[1,0]
	v_pk_mul_f32 v[18:19], v[18:19], v[64:65] op_sel_hi:[1,0]
	v_pk_mul_f32 v[16:17], v[16:17], v[64:65] op_sel_hi:[1,0]
	v_pk_mul_f32 v[14:15], v[14:15], v[64:65] op_sel_hi:[1,0]
	v_pk_mul_f32 v[12:13], v[12:13], v[64:65] op_sel_hi:[1,0]
	v_pk_mul_f32 v[10:11], v[10:11], v[64:65] op_sel_hi:[1,0]
	v_pk_mul_f32 v[8:9], v[8:9], v[64:65] op_sel_hi:[1,0]
	v_pk_mul_f32 v[6:7], v[6:7], v[64:65] op_sel_hi:[1,0]
	v_pk_mul_f32 v[4:5], v[4:5], v[64:65] op_sel_hi:[1,0]
	v_pk_mul_f32 v[2:3], v[2:3], v[64:65] op_sel_hi:[1,0]
	v_pk_mul_f32 v[0:1], v[0:1], v[64:65] op_sel_hi:[1,0]
	v_add_f32_e32 v65, 0, v32
	v_exp_f32_e32 v50, v50
	v_add_f32_e32 v65, v48, v65
	v_exp_f32_e32 v35, v35
	v_add_f32_e32 v65, v33, v65
	v_exp_f32_e32 v51, v51
	v_add_f32_e32 v65, v49, v65
	v_exp_f32_e32 v36, v36
	v_add_f32_e32 v65, v34, v65
	v_exp_f32_e32 v52, v52
	v_add_f32_e32 v65, v50, v65
	v_exp_f32_e32 v37, v37
	v_add_f32_e32 v65, v35, v65
	v_exp_f32_e32 v53, v53
	v_add_f32_e32 v65, v51, v65
	v_exp_f32_e32 v38, v38
	v_add_f32_e32 v65, v36, v65
	v_exp_f32_e32 v54, v54
	v_add_f32_e32 v65, v52, v65
	v_exp_f32_e32 v39, v39
	v_add_f32_e32 v65, v37, v65
	v_add_f32_e32 v65, v53, v65
	v_add_f32_e32 v65, v38, v65
	v_add_f32_e32 v65, v54, v65
	v_cvt_pk_bf16_f32 v32, v32, v33
	v_cvt_pk_bf16_f32 v33, v34, v35
	v_cvt_pk_bf16_f32 v34, v36, v37
	v_cvt_pk_bf16_f32 v35, v38, v39
	v_lshl_add_u32 v38, v111, 1, v80
	v_add_f32_e32 v65, v39, v65
	ds_read_b64 v[36:37], v66 offset:27648
	ds_read_b64 v[38:39], v38 offset:27648
	s_waitcnt lgkmcnt(0)
	v_mfma_f32_32x32x16_bf16 v[16:31], v[36:39], v[32:35], v[16:31]
	v_lshl_add_u32 v36, v110, 1, v67
	v_lshl_add_u32 v38, v109, 1, v67
	ds_read_b64 v[36:37], v36 offset:27648
	ds_read_b64 v[38:39], v38 offset:27648
	v_exp_f32_e32 v40, v40
	v_exp_f32_e32 v41, v41
	v_exp_f32_e32 v42, v42
	s_waitcnt lgkmcnt(0)
	v_mfma_f32_32x32x16_bf16 v[0:15], v[36:39], v[32:35], v[0:15]
	v_lshl_add_u32 v36, v108, 1, v80
	v_lshl_add_u32 v38, v107, 1, v80
	v_exp_f32_e32 v43, v43
	v_exp_f32_e32 v44, v44
	v_exp_f32_e32 v45, v45
	v_exp_f32_e32 v46, v46
	v_exp_f32_e32 v47, v47
	v_cvt_pk_bf16_f32 v32, v40, v41
	v_cvt_pk_bf16_f32 v33, v42, v43
	v_cvt_pk_bf16_f32 v34, v44, v45
	v_cvt_pk_bf16_f32 v35, v46, v47
	ds_read_b64 v[36:37], v36 offset:27648
	ds_read_b64 v[38:39], v38 offset:27648
	s_waitcnt lgkmcnt(0)
	v_mfma_f32_32x32x16_bf16 v[16:31], v[36:39], v[32:35], v[16:31]
	v_lshl_add_u32 v36, v106, 1, v67
	v_lshl_add_u32 v38, v105, 1, v67
	ds_read_b64 v[36:37], v36 offset:27648
	ds_read_b64 v[38:39], v38 offset:27648
	v_exp_f32_e32 v55, v55
	v_exp_f32_e32 v56, v56
	v_exp_f32_e32 v57, v57
	s_waitcnt lgkmcnt(0)
	v_mfma_f32_32x32x16_bf16 v[0:15], v[36:39], v[32:35], v[0:15]
	v_lshl_add_u32 v38, v104, 1, v80
	v_cvt_pk_bf16_f32 v32, v48, v49
	v_cvt_pk_bf16_f32 v33, v50, v51
	v_cvt_pk_bf16_f32 v34, v52, v53
	v_cvt_pk_bf16_f32 v35, v54, v55
	ds_read_b64 v[36:37], v66 offset:27712
	ds_read_b64 v[38:39], v38 offset:27648
	s_waitcnt lgkmcnt(0)
; #define MFMA32(a, b, c) __builtin_amdgcn_mfma_f32_32x32x16_bf16((a), (b), (c), 0, 0, 0)
; DI unsigned pack2(float a, float b) { unsigned r; asm volatile("v_cvt_pk_bf16_f32 %0, %1, %2" : "=v"(r) : "v"(a), "v"(b)); return r; }
; template <int D>
; DI void attn_pass(const bfr* __restrict__ P, int b, int tq_wave, int qcol, int kcol, int vcol, int key0, int nkt, char* smem, f32x16 (&o)[2]) {
;     ...
;         for (int dt = 0; dt < 2; ++dt) {
;           const int vsw = (((dt * 32 + r) >> 3) & 7) << 3;
;           const bfr* vrow = sV + (dt * 32 + r) * 72;
;           s16x4 lo = *(const s16x4*)(vrow + ((t2 * 32 + 16 * j + 4 * h) ^ vsw));
;           s16x4 hi = *(const s16x4*)(vrow + ((t2 * 32 + 16 * j + 4 * h + 8) ^ vsw));
;           bf16x8 vf = __builtin_shufflevector(lo, hi, 0, 1, 2, 3, 4, 5, 6, 7);
;           accO[dt] = MFMA32(vf, pf, accO[dt]);
;         }
;       }
;   }
;   lsum += __shfl_xor(lsum, 32);
;   float inv = 1.f / lsum;
; #pragma unroll
;   for (int i = 0; i < 16; ++i) { o[0][i] = accO[0][i] * inv; o[1][i] = accO[1][i] * inv; }
; DI void store_o(bfr* O, int m, int colbase, int h, const f32x16 (&o)[2]) {
; #pragma unroll
;   for (int dt = 0; dt < 2; ++dt)
; #pragma unroll
;     for (int g4 = 0; g4 < 4; ++g4) {
;       int dv = dt * 32 + 8 * g4 + 4 * h;
;       uint2 pk; pk.x = pack2(o[dt][4 * g4], o[dt][4 * g4 + 1]); pk.y = pack2(o[dt][4 * g4 + 2], o[dt][4 * g4 + 3]);
;       *(uint2*)(O + (size_t)m * DM + colbase + dv) = pk;
;     }
; }
	v_mfma_f32_32x32x16_bf16 v[16:31], v[36:39], v[32:35], v[16:31]
	v_lshl_add_u32 v36, v103, 1, v67
	v_lshl_add_u32 v38, v102, 1, v67
	ds_read_b64 v[36:37], v36 offset:27648
	ds_read_b64 v[38:39], v38 offset:27648
	v_exp_f32_e32 v58, v58
	v_exp_f32_e32 v59, v59
	v_exp_f32_e32 v60, v60
	s_waitcnt lgkmcnt(0)
	v_mfma_f32_32x32x16_bf16 v[0:15], v[36:39], v[32:35], v[0:15]
	v_lshl_add_u32 v36, v100, 1, v80
	v_lshl_add_u32 v38, v101, 1, v80
	v_exp_f32_e32 v61, v61
	v_exp_f32_e32 v62, v62
	v_exp_f32_e32 v63, v63
	v_cvt_pk_bf16_f32 v32, v56, v57
	v_cvt_pk_bf16_f32 v33, v58, v59
	v_cvt_pk_bf16_f32 v34, v60, v61
	v_cvt_pk_bf16_f32 v35, v62, v63
	ds_read_b64 v[36:37], v36 offset:27648
	ds_read_b64 v[38:39], v38 offset:27648
	v_add_f32_e32 v65, v55, v65
	v_add_f32_e32 v65, v40, v65
	v_add_f32_e32 v65, v56, v65
	v_add_f32_e32 v65, v41, v65
	v_add_f32_e32 v65, v57, v65
	v_add_f32_e32 v65, v42, v65
	v_add_f32_e32 v65, v58, v65
	v_add_f32_e32 v65, v43, v65
	v_add_f32_e32 v65, v59, v65
	s_waitcnt lgkmcnt(0)
	v_mfma_f32_32x32x16_bf16 v[16:31], v[36:39], v[32:35], v[16:31]
	v_lshl_add_u32 v36, v99, 1, v67
	v_lshl_add_u32 v38, v98, 1, v67
	v_add_f32_e32 v65, v44, v65
	ds_read_b64 v[36:37], v36 offset:27648
	ds_read_b64 v[38:39], v38 offset:27648
	v_add_f32_e32 v65, v60, v65
	v_add_f32_e32 v65, v45, v65
	v_add_f32_e32 v65, v61, v65
	v_add_f32_e32 v65, v46, v65
	v_add_f32_e32 v65, v62, v65
	v_add_f32_e32 v65, v47, v65
	v_add_f32_e32 v65, v63, v65
	v_fmac_f32_e32 v65, v113, v64
	s_waitcnt lgkmcnt(0)
	v_mfma_f32_32x32x16_bf16 v[0:15], v[36:39], v[32:35], v[0:15]
	ds_bpermute_b32 v32, v91, v65
	s_load_dwordx4 s[12:15], s[0:1], 0x100
	s_waitcnt lgkmcnt(0)
	v_add_f32_e32 v32, v65, v32
	v_div_scale_f32 v33, s[10:11], v32, v32, 1.0
	v_rcp_f32_e32 v34, v33
	s_mov_b64 s[10:11], 0x2b7c700
	v_fma_f32 v35, -v33, v34, 1.0
	v_fmac_f32_e32 v34, v35, v34
	v_div_scale_f32 v35, vcc, 1.0, v32, 1.0
	v_mul_f32_e32 v36, v35, v34
	v_fma_f32 v37, -v33, v36, v35
	v_fmac_f32_e32 v36, v37, v34
	v_fma_f32 v33, -v33, v36, v35
	v_div_fmas_f32 v33, v33, v34, v36
	v_div_fixup_f32 v32, v33, v32, 1.0
	v_mul_f32_e32 v33, v0, v32
	v_and_or_b32 v0, v89, 31, v97
	v_mul_f32_e32 v34, v1, v32
	v_ashrrev_i32_e32 v1, 31, v0
	v_lshlrev_b64 v[0:1], 11, v[0:1]
	v_mul_f32_e32 v37, v4, v32
	v_lshl_add_u64 v[0:1], s[14:15], 0, v[0:1]
	v_lshrrev_b32_e32 v4, 2, v89
	v_lshl_add_u64 v[0:1], v[0:1], 0, v[152:153]
	v_and_b32_e32 v152, 8, v4
	v_lshl_add_u64 v[0:1], v[0:1], 0, v[152:153]
	v_mul_f32_e32 v38, v5, v32
	v_lshl_add_u64 v[4:5], v[0:1], 0, s[10:11]
	s_mov_b32 s10, 0x2b7c000
	v_add_co_u32_e32 v0, vcc, s10, v0
	v_mul_f32_e32 v16, v16, v32
	s_nop 0
	v_addc_co_u32_e32 v1, vcc, 0, v1, vcc
	v_mul_f32_e32 v17, v17, v32
	v_mul_f32_e32 v18, v18, v32
	v_mul_f32_e32 v35, v2, v32
	v_mul_f32_e32 v19, v19, v32
	v_mul_f32_e32 v36, v3, v32
	v_mul_f32_e32 v20, v20, v32
	v_mul_f32_e32 v21, v21, v32
	v_mul_f32_e32 v22, v22, v32
	v_mul_f32_e32 v23, v23, v32
	v_cvt_pk_bf16_f32 v2, v16, v17
	v_cvt_pk_bf16_f32 v3, v18, v19
	global_store_dwordx2 v[0:1], v[2:3], off offset:1792
	v_cvt_pk_bf16_f32 v0, v20, v21
	v_cvt_pk_bf16_f32 v1, v22, v23
	v_mul_f32_e32 v24, v24, v32
	v_mul_f32_e32 v25, v25, v32
	v_mul_f32_e32 v26, v26, v32
	v_mul_f32_e32 v27, v27, v32
	global_store_dwordx2 v[4:5], v[0:1], off offset:16
	v_cvt_pk_bf16_f32 v0, v24, v25
	v_cvt_pk_bf16_f32 v1, v26, v27
	v_mul_f32_e32 v28, v28, v32
	v_mul_f32_e32 v29, v29, v32
	v_mul_f32_e32 v30, v30, v32
	v_mul_f32_e32 v31, v31, v32
	global_store_dwordx2 v[4:5], v[0:1], off offset:32
	v_cvt_pk_bf16_f32 v0, v28, v29
	v_cvt_pk_bf16_f32 v1, v30, v31
	global_store_dwordx2 v[4:5], v[0:1], off offset:48
	v_cvt_pk_bf16_f32 v0, v33, v34
	v_cvt_pk_bf16_f32 v1, v35, v36
	v_mul_f32_e32 v6, v6, v32
	v_mul_f32_e32 v7, v7, v32
	global_store_dwordx2 v[4:5], v[0:1], off offset:64
	v_cvt_pk_bf16_f32 v0, v37, v38
	v_cvt_pk_bf16_f32 v1, v6, v7
	v_mul_f32_e32 v8, v8, v32
	v_mul_f32_e32 v9, v9, v32
	v_mul_f32_e32 v10, v10, v32
	v_mul_f32_e32 v11, v11, v32
	global_store_dwordx2 v[4:5], v[0:1], off offset:80
	v_cvt_pk_bf16_f32 v0, v8, v9
	v_cvt_pk_bf16_f32 v1, v10, v11
	v_mul_f32_e32 v12, v12, v32
	v_mul_f32_e32 v13, v13, v32
	v_mul_f32_e32 v14, v14, v32
	v_mul_f32_e32 v15, v15, v32
	global_store_dwordx2 v[4:5], v[0:1], off offset:96
	v_cvt_pk_bf16_f32 v0, v12, v13
	v_cvt_pk_bf16_f32 v1, v14, v15
	global_store_dwordx2 v[4:5], v[0:1], off offset:112

; DI void attn_pass_da(const bfr* __restrict__ P, int b, int tq_wave, int qcol, int kcol, int vcol, int key0, int nkt, char* smem, f32x16 (&o0)[2], f32x16 (&o1)[2]) {
;     ...
;   for (int kt = 0; kt < nkt; ++kt) {
;     bfr* sK = sbase + (kt & 1) * 9216;
;     bfr* sV = sK + 64 * 72;
;     { int c = gt, row = c >> 3, kc = c & 7; *(u32x4*)(sK + row * KP + kc * 8) = kreg[0]; }
;     for (int i = 0; i < 1; ++i) {
;       int c = gt, row = c >> 3, kc = c & 7;
;       unsigned wds[4] = {vreg[i].x, vreg[i].y, vreg[i].z, vreg[i].w};
; #pragma unroll
;       for (int e = 0; e < 4; ++e) {
;         sV[(kc * 8 + 2 * e) * 72 + (row ^ (kc << 3))] = (bfr)(wds[e] & 0xffffu);
;         sV[(kc * 8 + 2 * e + 1) * 72 + (row ^ (kc << 3))] = (bfr)(wds[e] >> 16);
;       }
;     }
;     __syncthreads();
;     if (kt + 1 < nkt) {
;       const bfr* Pn = Pb + (size_t)(kt + 1) * 64 * PW;
;       { int c = gt, row = c >> 3, kc = c & 7; kreg[0] = *(const u32x4*)(Pn + (size_t)row * PW + kcol + kc * 8); vreg[0] = *(const u32x4*)(Pn + (size_t)row * PW + vcol + kc * 8); }
;     }
;     f32x16 s0[2], s1[2];
; #pragma unroll
;     for (int t2 = 0; t2 < 2; ++t2) {
; #pragma unroll
;       for (int i = 0; i < 16; ++i) { s0[t2][i] = 0.f; s1[t2][i] = 0.f; }
; #pragma unroll
;       for (int ks = 0; ks < 2; ++ks) {
;         bf16x8 a0 = *(const bf16x8*)(sK + (t2 * 32 + r) * KP + ks * 16 + h * 8);
;         bf16x8 a1 = *(const bf16x8*)(sK + (t2 * 32 + r) * KP + 32 + ks * 16 + h * 8);
;         s0[t2] = MFMA32(a0, qf[ks], s0[t2]);
;         s1[t2] = MFMA32(a1, qf[2 + ks], s1[t2]);
;       }
;     }
;     float mx0 = s0[0][0], mx1 = s1[0][0];
; #pragma unroll
;     for (int i = 0; i < 16; ++i) { mx0 = fmaxf(mx0, fmaxf(s0[0][i], s0[1][i])); mx1 = fmaxf(mx1, fmaxf(s1[0][i], s1[1][i])); }
;     mx0 = fmaxf(mx0, __shfl_xor(mx0, 32)); mx1 = fmaxf(mx1, __shfl_xor(mx1, 32));
;     const float mn0 = fmaxf(m0, mx0), mn1 = fmaxf(m1, mx1);
;     const float al0 = __builtin_amdgcn_exp2f(m0 - mn0), al1 = __builtin_amdgcn_exp2f(m1 - mn1);
;     m0 = mn0; m1 = mn1;
;     float ps0 = 0.f, ps1 = 0.f;
; #pragma unroll
;     for (int i = 0; i < 16; ++i) {
;       s0[0][i] = __builtin_amdgcn_exp2f(s0[0][i] - mn0); ps0 += s0[0][i];
;       s0[1][i] = __builtin_amdgcn_exp2f(s0[1][i] - mn0); ps0 += s0[1][i];
;       s1[0][i] = __builtin_amdgcn_exp2f(s1[0][i] - mn1); ps1 += s1[0][i];
.LBB0_408:
	s_bitcmp1_b32 s14, 0
	s_cselect_b32 s15, 0x4800, 0
	s_add_i32 s15, s15, 0
	v_add3_u32 v64, s15, v206, v152
	v_add_u32_e32 v194, s15, v205
	s_waitcnt vmcnt(1)
	ds_write_b128 v64, v[148:151]
	v_add3_u32 v64, s15, v207, v208
	v_add3_u32 v65, s15, v208, v207
	v_add_u32_e32 v100, v194, v204
	s_waitcnt vmcnt(0)
	ds_write_b16 v64, v144 offset:9216
	ds_write_b16_d16_hi v65, v144 offset:9360
	ds_write_b16 v64, v145 offset:9504
	ds_write_b16_d16_hi v65, v145 offset:9648
	ds_write_b16 v64, v146 offset:9792
	ds_write_b16_d16_hi v65, v146 offset:9936
	ds_write_b16 v64, v147 offset:10080
	ds_write_b16_d16_hi v65, v147 offset:10224
	s_waitcnt lgkmcnt(0)
	s_barrier
	global_load_dwordx4 v[148:151], v[158:159], off
	global_load_dwordx4 v[144:147], v[158:159], off offset:512
	ds_read_b128 v[64:67], v100 offset:64
	ds_read_b128 v[68:71], v100
	ds_read_b128 v[96:99], v100 offset:32
	ds_read_b128 v[100:103], v100 offset:96
	s_waitcnt lgkmcnt(2)
	v_mfma_f32_32x32x16_bf16 v[80:95], v[68:71], v[140:143], 0
	v_add_u32_e32 v195, s15, v211
	v_add_u32_e32 v192, v195, v204
	v_mov_b32_e32 v160, v209
	v_mov_b32_e32 v161, v210
	s_add_i32 s14, s14, 1
	v_lshl_add_u64 v[158:159], v[158:159], 0, s[16:17]
	s_cmp_lg_u32 s14, 3
	v_mfma_f32_32x32x16_bf16 v[64:79], v[64:67], v[136:139], 0
	s_waitcnt lgkmcnt(1)
	v_mfma_f32_32x32x16_bf16 v[80:95], v[96:99], v[132:135], v[80:95]
	s_waitcnt lgkmcnt(0)
	v_mfma_f32_32x32x16_bf16 v[64:79], v[100:103], v[128:131], v[64:79]
	ds_read_b128 v[96:99], v192 offset:64
	ds_read_b128 v[100:103], v192
	ds_read_b128 v[212:215], v192 offset:32
	ds_read_b128 v[216:219], v192 offset:96
	s_nop 5
	v_max3_f32 v209, v80, v81, v82
	v_max3_f32 v209, v209, v83, v84
	v_max3_f32 v193, v64, v65, v66
	s_waitcnt lgkmcnt(2)
	v_mfma_f32_32x32x16_bf16 v[112:127], v[100:103], v[140:143], 0
	v_mfma_f32_32x32x16_bf16 v[96:111], v[96:99], v[136:139], 0
	s_waitcnt lgkmcnt(1)
	v_mfma_f32_32x32x16_bf16 v[112:127], v[212:215], v[132:135], v[112:127]
	v_max3_f32 v193, v193, v67, v68
	v_max3_f32 v209, v209, v85, v86
	s_waitcnt lgkmcnt(0)
	v_mfma_f32_32x32x16_bf16 v[96:111], v[216:219], v[128:131], v[96:111]
	v_max3_f32 v193, v193, v69, v70
	v_max3_f32 v209, v209, v87, v88
	v_max3_f32 v193, v193, v71, v72
	v_max3_f32 v209, v209, v89, v90
	v_max3_f32 v193, v193, v73, v74
	v_max3_f32 v209, v209, v91, v92
	v_max3_f32 v193, v193, v75, v76
	v_max3_f32 v209, v209, v93, v94
	v_max3_f32 v193, v193, v77, v78
	v_max3_f32 v209, v209, v95, v112
	v_max3_f32 v209, v209, v113, v114
	v_max3_f32 v209, v209, v115, v116
	v_max3_f32 v209, v209, v117, v118
	v_max3_f32 v209, v209, v119, v120
	v_max3_f32 v209, v209, v121, v122
	v_max3_f32 v209, v209, v123, v124
	v_max3_f32 v209, v209, v125, v126
	v_max_f32_e32 v192, v209, v127
	v_max3_f32 v193, v193, v79, v96
	v_max3_f32 v193, v193, v97, v98
	v_max3_f32 v193, v193, v99, v100
	v_max3_f32 v193, v193, v101, v102
	v_max3_f32 v193, v193, v103, v104
	v_max3_f32 v193, v193, v105, v106
	v_max3_f32 v193, v193, v107, v108
	v_max3_f32 v193, v193, v109, v110
	v_max_f32_e32 v193, v193, v111
	ds_bpermute_b32 v210, v166, v193
	ds_bpermute_b32 v209, v166, v192
	s_waitcnt lgkmcnt(1)
	v_max3_f32 v210, v161, v193, v210
	s_waitcnt lgkmcnt(0)
	v_max3_f32 v209, v160, v192, v209
	v_sub_f32_e32 v64, v64, v210
	v_sub_f32_e32 v80, v80, v209
	v_exp_f32_e32 v193, v64
	v_sub_f32_e32 v64, v96, v210
	v_exp_f32_e32 v192, v80
	v_sub_f32_e32 v80, v112, v209
	v_exp_f32_e32 v213, v64
	v_sub_f32_e32 v64, v81, v209
	v_exp_f32_e32 v212, v80
	v_exp_f32_e32 v80, v64
	v_sub_f32_e32 v64, v113, v209
	v_exp_f32_e32 v96, v64
	v_sub_f32_e32 v64, v65, v210
	v_exp_f32_e32 v81, v64
	v_sub_f32_e32 v64, v97, v210
	v_exp_f32_e32 v97, v64
	v_sub_f32_e32 v64, v82, v209
	v_exp_f32_e32 v112, v64
	v_sub_f32_e32 v64, v114, v209
	v_exp_f32_e32 v214, v64
	v_sub_f32_e32 v64, v66, v210
	v_exp_f32_e32 v113, v64
	v_sub_f32_e32 v64, v98, v210
	v_exp_f32_e32 v215, v64
	v_sub_f32_e32 v64, v83, v209
	v_exp_f32_e32 v82, v64
	v_sub_f32_e32 v64, v115, v209
	v_exp_f32_e32 v98, v64
	v_sub_f32_e32 v64, v67, v210
	v_exp_f32_e32 v83, v64
	v_sub_f32_e32 v64, v99, v210
	v_exp_f32_e32 v99, v64
	v_sub_f32_e32 v64, v84, v209
	v_exp_f32_e32 v114, v64
	v_sub_f32_e32 v64, v116, v209
	v_exp_f32_e32 v216, v64
	v_sub_f32_e32 v64, v68, v210
	v_exp_f32_e32 v115, v64
	v_sub_f32_e32 v64, v100, v210
	v_exp_f32_e32 v217, v64
	v_sub_f32_e32 v64, v85, v209
	v_exp_f32_e32 v84, v64
	v_sub_f32_e32 v64, v117, v209
	v_exp_f32_e32 v100, v64
	v_sub_f32_e32 v64, v69, v210
	v_exp_f32_e32 v85, v64
	v_sub_f32_e32 v64, v101, v210
	v_exp_f32_e32 v101, v64
	v_sub_f32_e32 v64, v86, v209
	v_exp_f32_e32 v116, v64
	v_sub_f32_e32 v64, v118, v209
	v_exp_f32_e32 v218, v64
	v_sub_f32_e32 v64, v70, v210
	v_exp_f32_e32 v117, v64
	v_sub_f32_e32 v64, v102, v210
	v_exp_f32_e32 v219, v64
	v_sub_f32_e32 v64, v87, v209
	v_exp_f32_e32 v70, v64
	v_sub_f32_e32 v64, v119, v209
	v_exp_f32_e32 v86, v64
	v_sub_f32_e32 v64, v71, v210
	v_exp_f32_e32 v71, v64
	v_sub_f32_e32 v64, v103, v210
	v_exp_f32_e32 v87, v64
	v_sub_f32_e32 v64, v88, v209
	v_exp_f32_e32 v102, v64
	v_sub_f32_e32 v64, v120, v209
	v_exp_f32_e32 v118, v64
	v_sub_f32_e32 v64, v72, v210
	v_exp_f32_e32 v103, v64
	v_sub_f32_e32 v64, v104, v210
	v_exp_f32_e32 v119, v64
	v_sub_f32_e32 v64, v89, v209
	v_exp_f32_e32 v88, v64
	v_sub_f32_e32 v64, v121, v209
	v_exp_f32_e32 v104, v64
	v_sub_f32_e32 v64, v73, v210
	v_exp_f32_e32 v89, v64
	v_sub_f32_e32 v64, v105, v210
	v_exp_f32_e32 v105, v64
	v_sub_f32_e32 v64, v90, v209
	v_exp_f32_e32 v120, v64
	v_sub_f32_e32 v64, v122, v209
	v_exp_f32_e32 v220, v64
	v_sub_f32_e32 v64, v74, v210
	v_exp_f32_e32 v121, v64
	v_sub_f32_e32 v64, v106, v210
	v_exp_f32_e32 v221, v64
; #define MFMA32(a, b, c) __builtin_amdgcn_mfma_f32_32x32x16_bf16((a), (b), (c), 0, 0, 0)
; DI unsigned pack2(float a, float b) { unsigned r; asm volatile("v_cvt_pk_bf16_f32 %0, %1, %2" : "=v"(r) : "v"(a), "v"(b)); return r; }
; DI void attn_pass_da(const bfr* __restrict__ P, int b, int tq_wave, int qcol, int kcol, int vcol, int key0, int nkt, char* smem, f32x16 (&o0)[2], f32x16 (&o1)[2]) {
;     ...
;     for (int i = 0; i < 16; ++i) {
;       s0[0][i] = __builtin_amdgcn_exp2f(s0[0][i] - mn0); ps0 += s0[0][i];
;       s0[1][i] = __builtin_amdgcn_exp2f(s0[1][i] - mn0); ps0 += s0[1][i];
;       s1[0][i] = __builtin_amdgcn_exp2f(s1[0][i] - mn1); ps1 += s1[0][i];
;       s1[1][i] = __builtin_amdgcn_exp2f(s1[1][i] - mn1); ps1 += s1[1][i];
;     }
;     l0 = l0 * al0 + ps0; l1 = l1 * al1 + ps1;
; #pragma unroll
;     for (int i = 0; i < 16; ++i) { acc0[0][i] *= al0; acc0[1][i] *= al0; acc1[0][i] *= al1; acc1[1][i] *= al1; }
; #pragma unroll
;     for (int t2 = 0; t2 < 2; ++t2)
; #pragma unroll
;       for (int j = 0; j < 2; ++j) {
;         u32x4 pk0, pk1;
;         pk0.x = pack2(s0[t2][8 * j + 0], s0[t2][8 * j + 1]); pk0.y = pack2(s0[t2][8 * j + 2], s0[t2][8 * j + 3]);
;         pk0.z = pack2(s0[t2][8 * j + 4], s0[t2][8 * j + 5]); pk0.w = pack2(s0[t2][8 * j + 6], s0[t2][8 * j + 7]);
;         pk1.x = pack2(s1[t2][8 * j + 0], s1[t2][8 * j + 1]); pk1.y = pack2(s1[t2][8 * j + 2], s1[t2][8 * j + 3]);
;         pk1.z = pack2(s1[t2][8 * j + 4], s1[t2][8 * j + 5]); pk1.w = pack2(s1[t2][8 * j + 6], s1[t2][8 * j + 7]);
;         const bf16x8 pf0 = __builtin_bit_cast(bf16x8, pk0), pf1 = __builtin_bit_cast(bf16x8, pk1);
; #pragma unroll
;         for (int dt = 0; dt < 2; ++dt) {
;           const int vsw = (((dt * 32 + r) >> 3) & 7) << 3;
;           const bfr* vrow = sV + (dt * 32 + r) * 72;
;           s16x4 lo = *(const s16x4*)(vrow + ((t2 * 32 + 16 * j + 4 * h) ^ vsw));
;           s16x4 hi = *(const s16x4*)(vrow + ((t2 * 32 + 16 * j + 4 * h + 8) ^ vsw));
;           bf16x8 vf = __builtin_shufflevector(lo, hi, 0, 1, 2, 3, 4, 5, 6, 7);
;           acc0[dt] = MFMA32(vf, pf0, acc0[dt]);
;           acc1[dt] = MFMA32(vf, pf1, acc1[dt]);
	v_sub_f32_e32 v64, v91, v209
	v_exp_f32_e32 v90, v64
	v_sub_f32_e32 v64, v123, v209
	v_exp_f32_e32 v106, v64
	v_sub_f32_e32 v64, v75, v210
	v_exp_f32_e32 v91, v64
	v_sub_f32_e32 v64, v107, v210
	v_exp_f32_e32 v107, v64
	v_sub_f32_e32 v64, v92, v209
	v_exp_f32_e32 v122, v64
	v_sub_f32_e32 v64, v124, v209
	v_exp_f32_e32 v222, v64
	v_sub_f32_e32 v64, v76, v210
	v_exp_f32_e32 v123, v64
	v_sub_f32_e32 v64, v108, v210
	v_exp_f32_e32 v223, v64
	v_sub_f32_e32 v64, v93, v209
	v_exp_f32_e32 v92, v64
	v_sub_f32_e32 v64, v125, v209
	v_exp_f32_e32 v108, v64
	v_sub_f32_e32 v64, v77, v210
	v_exp_f32_e32 v93, v64
	v_sub_f32_e32 v64, v109, v210
	v_exp_f32_e32 v109, v64
	v_sub_f32_e32 v64, v94, v209
	v_exp_f32_e32 v124, v64
	v_sub_f32_e32 v64, v126, v209
	v_exp_f32_e32 v224, v64
	v_sub_f32_e32 v64, v78, v210
	v_exp_f32_e32 v125, v64
	v_sub_f32_e32 v64, v110, v210
	v_exp_f32_e32 v225, v64
	v_sub_f32_e32 v64, v95, v209
	v_exp_f32_e32 v94, v64
	v_sub_f32_e32 v64, v127, v209
	v_exp_f32_e32 v110, v64
	v_sub_f32_e32 v64, v79, v210
	v_exp_f32_e32 v95, v64
	v_sub_f32_e32 v64, v111, v210
	v_exp_f32_e32 v111, v64
	v_add_f32_e32 v64, 0, v192
	v_add_f32_e32 v65, 0, v193
	v_sub_f32_e32 v161, v161, v210
	v_add_f32_e32 v64, v212, v64
	v_add_f32_e32 v65, v213, v65
	v_exp_f32_e32 v161, v161
	v_add_f32_e32 v64, v80, v64
	v_add_f32_e32 v65, v81, v65
	v_lshl_add_u32 v74, v180, 1, v194
	v_add_f32_e32 v64, v96, v64
	v_add_f32_e32 v65, v97, v65
	v_lshl_add_u32 v76, v179, 1, v195
	v_add_f32_e32 v64, v112, v64
	v_add_f32_e32 v65, v113, v65
	v_lshl_add_u32 v78, v178, 1, v195
	v_add_f32_e32 v64, v214, v64
	v_add_f32_e32 v65, v215, v65
	v_sub_f32_e32 v160, v160, v209
	v_add_f32_e32 v64, v82, v64
	v_add_f32_e32 v65, v83, v65
	v_exp_f32_e32 v160, v160
	v_add_f32_e32 v64, v98, v64
	v_add_f32_e32 v65, v99, v65
	v_mul_f32_e32 v62, v62, v160
	v_mul_f32_e32 v63, v63, v160
	v_add_f32_e32 v64, v114, v64
	v_add_f32_e32 v65, v115, v65
	v_mul_f32_e32 v60, v60, v160
	v_mul_f32_e32 v61, v61, v160
	v_add_f32_e32 v64, v216, v64
	v_add_f32_e32 v65, v217, v65
	v_mul_f32_e32 v58, v58, v160
	v_mul_f32_e32 v59, v59, v160
	v_add_f32_e32 v64, v84, v64
	v_add_f32_e32 v65, v85, v65
	v_mul_f32_e32 v56, v56, v160
	v_mul_f32_e32 v57, v57, v160
	v_add_f32_e32 v64, v100, v64
	v_add_f32_e32 v65, v101, v65
	v_mul_f32_e32 v54, v54, v160
	v_mul_f32_e32 v55, v55, v160
	v_add_f32_e32 v64, v116, v64
	v_add_f32_e32 v65, v117, v65
	v_mul_f32_e32 v52, v52, v160
	v_mul_f32_e32 v53, v53, v160
	v_add_f32_e32 v64, v218, v64
	v_add_f32_e32 v65, v219, v65
	v_mul_f32_e32 v50, v50, v160
	v_mul_f32_e32 v51, v51, v160
	v_add_f32_e32 v64, v70, v64
	v_add_f32_e32 v65, v71, v65
	v_mul_f32_e32 v48, v48, v160
	v_mul_f32_e32 v49, v49, v160
	v_add_f32_e32 v64, v86, v64
	v_add_f32_e32 v65, v87, v65
	v_mul_f32_e32 v30, v30, v160
	v_mul_f32_e32 v31, v31, v160
	v_add_f32_e32 v64, v102, v64
	v_add_f32_e32 v65, v103, v65
	v_mul_f32_e32 v28, v28, v160
	v_mul_f32_e32 v29, v29, v160
	v_add_f32_e32 v64, v118, v64
	v_add_f32_e32 v65, v119, v65
	v_mul_f32_e32 v26, v26, v160
	v_mul_f32_e32 v27, v27, v160
	v_add_f32_e32 v64, v88, v64
	v_add_f32_e32 v65, v89, v65
	v_mul_f32_e32 v24, v24, v160
	v_mul_f32_e32 v25, v25, v160
	v_add_f32_e32 v64, v104, v64
	v_add_f32_e32 v65, v105, v65
	v_mul_f32_e32 v22, v22, v160
	v_mul_f32_e32 v23, v23, v160
	v_add_f32_e32 v64, v120, v64
	v_add_f32_e32 v65, v121, v65
	v_mul_f32_e32 v20, v20, v160
	v_mul_f32_e32 v21, v21, v160
	v_add_f32_e32 v126, v220, v64
	v_add_f32_e32 v127, v221, v65
	v_cvt_pk_bf16_f32 v64, v192, v80
	v_cvt_pk_bf16_f32 v65, v112, v82
	v_lshl_add_u32 v112, v181, 1, v194
	v_cvt_pk_bf16_f32 v66, v114, v84
	v_cvt_pk_bf16_f32 v67, v116, v70
	v_cvt_pk_bf16_f32 v68, v193, v81
	v_cvt_pk_bf16_f32 v69, v113, v83
	v_cvt_pk_bf16_f32 v70, v115, v85
	v_cvt_pk_bf16_f32 v71, v117, v71
	ds_read_b64 v[72:73], v112 offset:9216
	ds_read_b64 v[74:75], v74 offset:9216
	ds_read_b64 v[76:77], v76 offset:9216
	ds_read_b64 v[78:79], v78 offset:9216
	v_mov_b32_e32 v82, v161
	v_mul_f32_e32 v46, v46, v82
	v_mul_f32_e32 v47, v47, v82
	v_mul_f32_e32 v44, v44, v82
	v_mul_f32_e32 v45, v45, v82
	v_mul_f32_e32 v42, v42, v82
	v_mul_f32_e32 v43, v43, v82
	v_mul_f32_e32 v40, v40, v82
	v_mul_f32_e32 v41, v41, v82
	v_mul_f32_e32 v38, v38, v82
	v_mul_f32_e32 v39, v39, v82
	v_mul_f32_e32 v36, v36, v82
	v_mul_f32_e32 v37, v37, v82
	v_mul_f32_e32 v34, v34, v82
	v_mul_f32_e32 v35, v35, v82
	v_mul_f32_e32 v32, v32, v82
	v_mul_f32_e32 v33, v33, v82
	v_mul_f32_e32 v14, v14, v82
	v_mul_f32_e32 v15, v15, v82
	v_mul_f32_e32 v12, v12, v82
	v_mul_f32_e32 v13, v13, v82
	v_mul_f32_e32 v10, v10, v82
	v_mul_f32_e32 v11, v11, v82
	v_mul_f32_e32 v8, v8, v82
	v_mul_f32_e32 v9, v9, v82
	v_mul_f32_e32 v6, v6, v82
	v_mul_f32_e32 v7, v7, v82
	v_mul_f32_e32 v4, v4, v82
	v_mul_f32_e32 v5, v5, v82
	v_mul_f32_e32 v2, v2, v82
	v_mul_f32_e32 v3, v3, v82
	v_mul_f32_e32 v0, v0, v82
	v_mul_f32_e32 v1, v1, v82
	v_add_f32_e32 v82, v90, v126
	v_add_f32_e32 v83, v91, v127
	s_waitcnt lgkmcnt(2)
	v_mfma_f32_32x32x16_bf16 v[48:63], v[72:75], v[64:67], v[48:63]
	v_add_f32_e64 v82, v106, v82
	v_add_f32_e64 v83, v107, v83
	v_cvt_pk_bf16_f32 v80, v102, v88
	v_lshl_add_u32 v88, v177, 1, v194
	v_add_f32_e64 v82, v122, v82
	v_add_f32_e64 v83, v123, v83
	v_mul_f32_e32 v18, v18, v160
	v_mul_f32_e32 v19, v19, v160
	v_add_f32_e32 v82, v222, v82
	v_add_f32_e32 v83, v223, v83
	v_mul_f32_e32 v16, v16, v160
	v_mul_f32_e32 v17, v17, v160
	v_add_f32_e32 v82, v92, v82
	v_add_f32_e32 v83, v93, v83
	v_mfma_f32_32x32x16_bf16 v[32:47], v[72:75], v[68:71], v[32:47]
	v_add_f32_e64 v82, v108, v82
	v_add_f32_e64 v83, v109, v83
	v_cvt_pk_bf16_f32 v81, v120, v90
	v_lshl_add_u32 v102, v176, 1, v194
	v_add_f32_e64 v82, v124, v82
	v_add_f32_e64 v83, v125, v83
	v_lshl_add_u32 v113, v175, 1, v195
	v_add_f32_e32 v82, v224, v82
	v_add_f32_e32 v83, v225, v83
	v_lshl_add_u32 v114, v174, 1, v195
	v_add_f32_e32 v82, v94, v82
	v_add_f32_e32 v83, v95, v83
	s_waitcnt lgkmcnt(0)
; DI void attn_pass_da(const bfr* __restrict__ P, int b, int tq_wave, int qcol, int kcol, int vcol, int key0, int nkt, char* smem, f32x16 (&o0)[2], f32x16 (&o1)[2]) {
;     ...
;     bfr* sK = sbase + (kt & 1) * 9216;
;     bfr* sV = sK + 64 * 72;
;     { int c = gt, row = c >> 3, kc = c & 7; *(u32x4*)(sK + row * KP + kc * 8) = kreg[0]; }
;     for (int i = 0; i < 1; ++i) {
;       int c = gt, row = c >> 3, kc = c & 7;
;       unsigned wds[4] = {vreg[i].x, vreg[i].y, vreg[i].z, vreg[i].w};
; #pragma unroll
;       for (int e = 0; e < 4; ++e) {
;         sV[(kc * 8 + 2 * e) * 72 + (row ^ (kc << 3))] = (bfr)(wds[e] & 0xffffu);
;         sV[(kc * 8 + 2 * e + 1) * 72 + (row ^ (kc << 3))] = (bfr)(wds[e] >> 16);
;       }
;     }
;     __syncthreads();
;     if (kt + 1 < nkt) {
;       const bfr* Pn = Pb + (size_t)(kt + 1) * 64 * PW;
;       { int c = gt, row = c >> 3, kc = c & 7; kreg[0] = *(const u32x4*)(Pn + (size_t)row * PW + kcol + kc * 8); vreg[0] = *(const u32x4*)(Pn + (size_t)row * PW + vcol + kc * 8); }
;     }
;     f32x16 s0[2], s1[2];
; #pragma unroll
;     for (int t2 = 0; t2 < 2; ++t2) {
; #pragma unroll
;     ...
;     for (int t2 = 0; t2 < 2; ++t2)
; #pragma unroll
;       for (int j = 0; j < 2; ++j) {
;         u32x4 pk0, pk1;
;         pk0.x = pack2(s0[t2][8 * j + 0], s0[t2][8 * j + 1]); pk0.y = pack2(s0[t2][8 * j + 2], s0[t2][8 * j + 3]);
;         pk0.z = pack2(s0[t2][8 * j + 4], s0[t2][8 * j + 5]); pk0.w = pack2(s0[t2][8 * j + 6], s0[t2][8 * j + 7]);
;         pk1.x = pack2(s1[t2][8 * j + 0], s1[t2][8 * j + 1]); pk1.y = pack2(s1[t2][8 * j + 2], s1[t2][8 * j + 3]);
;         pk1.z = pack2(s1[t2][8 * j + 4], s1[t2][8 * j + 5]); pk1.w = pack2(s1[t2][8 * j + 6], s1[t2][8 * j + 7]);
;         const bf16x8 pf0 = __builtin_bit_cast(bf16x8, pk0), pf1 = __builtin_bit_cast(bf16x8, pk1);
; #pragma unroll
;         for (int dt = 0; dt < 2; ++dt) {
;           const int vsw = (((dt * 32 + r) >> 3) & 7) << 3;
;           const bfr* vrow = sV + (dt * 32 + r) * 72;
;           s16x4 lo = *(const s16x4*)(vrow + ((t2 * 32 + 16 * j + 4 * h) ^ vsw));
;           s16x4 hi = *(const s16x4*)(vrow + ((t2 * 32 + 16 * j + 4 * h + 8) ^ vsw));
;           bf16x8 vf = __builtin_shufflevector(lo, hi, 0, 1, 2, 3, 4, 5, 6, 7);
;           acc0[dt] = MFMA32(vf, pf0, acc0[dt]);
;           acc1[dt] = MFMA32(vf, pf1, acc1[dt]);
;         }
;       }
	v_mfma_f32_32x32x16_bf16 v[16:31], v[76:79], v[64:67], v[16:31]
	v_add_f32_e64 v84, v110, v82
	v_add_f32_e64 v85, v111, v83
	v_cvt_pk_bf16_f32 v82, v122, v92
	v_cvt_pk_bf16_f32 v83, v124, v94
	v_cvt_pk_bf16_f32 v64, v103, v89
	v_cvt_pk_bf16_f32 v65, v121, v91
	v_cvt_pk_bf16_f32 v66, v123, v93
	v_cvt_pk_bf16_f32 v67, v125, v95
	v_mfma_f32_32x32x16_bf16 v[0:15], v[76:79], v[68:71], v[0:15]
	ds_read_b64 v[68:69], v88 offset:9216
	ds_read_b64 v[70:71], v102 offset:9216
	v_lshl_add_u32 v115, v173, 1, v194
	v_lshl_add_u32 v116, v172, 1, v195
	v_lshl_add_u32 v117, v171, 1, v195
	v_lshl_add_u32 v120, v169, 1, v194
	v_lshl_add_u32 v192, v170, 1, v194
	v_lshl_add_u32 v193, v168, 1, v195
	s_waitcnt lgkmcnt(0)
	v_mfma_f32_32x32x16_bf16 v[48:63], v[68:71], v[80:83], v[48:63]
	v_lshl_add_u32 v194, v167, 1, v195
	v_fma_f32 v156, v156, v160, v84
	v_fma_f32 v157, v157, v161, v85
	v_mfma_f32_32x32x16_bf16 v[32:47], v[68:71], v[64:67], v[32:47]
	ds_read_b64 v[68:69], v113 offset:9216
	ds_read_b64 v[70:71], v114 offset:9216
	s_waitcnt lgkmcnt(0)
	v_mfma_f32_32x32x16_bf16 v[16:31], v[68:71], v[80:83], v[16:31]
	v_mfma_f32_32x32x16_bf16 v[0:15], v[68:71], v[64:67], v[0:15]
	v_cvt_pk_bf16_f32 v64, v212, v96
	v_cvt_pk_bf16_f32 v65, v214, v98
	v_cvt_pk_bf16_f32 v66, v216, v100
	v_cvt_pk_bf16_f32 v67, v218, v86
	v_cvt_pk_bf16_f32 v68, v213, v97
	v_cvt_pk_bf16_f32 v69, v215, v99
	v_cvt_pk_bf16_f32 v70, v217, v101
	v_cvt_pk_bf16_f32 v71, v219, v87
	ds_read_b64 v[72:73], v112 offset:9280
	ds_read_b64 v[74:75], v115 offset:9216
	s_waitcnt lgkmcnt(0)
	v_mfma_f32_32x32x16_bf16 v[48:63], v[72:75], v[64:67], v[48:63]
	v_mfma_f32_32x32x16_bf16 v[32:47], v[72:75], v[68:71], v[32:47]
	ds_read_b64 v[72:73], v116 offset:9216
	ds_read_b64 v[74:75], v117 offset:9216
	s_waitcnt lgkmcnt(0)
	v_mfma_f32_32x32x16_bf16 v[16:31], v[72:75], v[64:67], v[16:31]
	v_cvt_pk_bf16_f32 v64, v118, v104
	v_cvt_pk_bf16_f32 v65, v220, v106
	v_cvt_pk_bf16_f32 v66, v222, v108
	v_cvt_pk_bf16_f32 v67, v224, v110
	v_mfma_f32_32x32x16_bf16 v[0:15], v[72:75], v[68:71], v[0:15]
	v_cvt_pk_bf16_f32 v68, v119, v105
	v_cvt_pk_bf16_f32 v69, v221, v107
	v_cvt_pk_bf16_f32 v70, v223, v109
	v_cvt_pk_bf16_f32 v71, v225, v111
	ds_read_b64 v[72:73], v120 offset:9216
	ds_read_b64 v[74:75], v192 offset:9216
	s_waitcnt lgkmcnt(0)
	v_mfma_f32_32x32x16_bf16 v[48:63], v[72:75], v[64:67], v[48:63]
	v_mfma_f32_32x32x16_bf16 v[32:47], v[72:75], v[68:71], v[32:47]
	ds_read_b64 v[72:73], v193 offset:9216
	ds_read_b64 v[74:75], v194 offset:9216
	s_waitcnt lgkmcnt(0)
	v_mfma_f32_32x32x16_bf16 v[16:31], v[72:75], v[64:67], v[16:31]
	v_mfma_f32_32x32x16_bf16 v[0:15], v[72:75], v[68:71], v[0:15]
	s_cbranch_scc1 .LBB0_408
	v_add3_u32 v64, 0, v206, v152
	s_waitcnt vmcnt(1)
	ds_write_b128 v64, v[148:151] offset:18432
	v_add3_u32 v64, 0, v207, v208
	v_add3_u32 v65, 0, v208, v207
	s_waitcnt vmcnt(0)
	ds_write_b16 v64, v144 offset:27648
	ds_write_b16_d16_hi v65, v144 offset:27792
	ds_write_b16 v64, v145 offset:27936
	ds_write_b16_d16_hi v65, v145 offset:28080
	ds_write_b16 v64, v146 offset:28224
	ds_write_b16_d16_hi v65, v146 offset:28368
	ds_write_b16 v64, v147 offset:28512
	ds_write_b16_d16_hi v65, v147 offset:28656
	v_add_u32_e32 v144, 0, v205
	v_add_u32_e32 v102, v144, v204
	s_waitcnt lgkmcnt(0)
	s_barrier
	ds_read_b128 v[64:67], v102 offset:18432
	ds_read_b128 v[96:99], v102 offset:18464
	s_waitcnt lgkmcnt(1)
	v_mfma_f32_32x32x16_bf16 v[64:79], v[64:67], v[140:143], 0
	ds_read_b128 v[80:83], v102 offset:18496
	v_readlane_b32 s14, v203, 16
	v_readlane_b32 s15, v203, 48
	v_add_u32_e32 v145, 0x1200, v144
	v_mov_b32_e32 v100, s14
	v_mov_b32_e32 v101, s15
	v_pk_add_f32 v[100:101], s[12:13], v[100:101]
	s_mov_b32 s14, 0x3fb8aa3b
	v_add_f32_e32 v146, v100, v101
	v_mul_f32_e32 v104, 0x3fb8aa3b, v146
	v_fma_f32 v105, v146, s14, -v104
	v_rndne_f32_e32 v106, v104
	s_waitcnt lgkmcnt(1)
	v_mfma_f32_32x32x16_bf16 v[64:79], v[96:99], v[132:135], v[64:79]
	v_fmac_f32_e32 v105, 0x32a5705f, v146
	v_sub_f32_e32 v96, v104, v106
	v_add_u32_e32 v147, v145, v204
	v_add_f32_e32 v104, v96, v105
	ds_read_b128 v[96:99], v147 offset:18432
	ds_read_b128 v[100:103], v102 offset:18528
	ds_read_b128 v[112:115], v147 offset:18496
	s_waitcnt lgkmcnt(3)
	v_mfma_f32_32x32x16_bf16 v[80:95], v[80:83], v[136:139], 0
	v_readlane_b32 s12, v202, 16
	v_readlane_b32 s13, v202, 48
	s_mov_b32 s15, 0xc2ce8ed0
	v_mov_b32_e32 v116, s12
	v_mov_b32_e32 v117, s13
	v_pk_add_f32 v[116:117], s[10:11], v[116:117]
	v_cmp_ngt_f32_e32 vcc, s15, v146
	s_waitcnt lgkmcnt(1)
	v_mfma_f32_32x32x16_bf16 v[80:95], v[100:103], v[128:131], v[80:95]
	v_exp_f32_e32 v100, v104
	v_cvt_i32_f32_e32 v101, v106
	v_add_f32_e32 v149, v116, v117
	v_mul_f32_e32 v150, 0x3fb8aa3b, v149
	v_rndne_f32_e32 v151, v150
	v_ldexp_f32 v148, v100, v101
	s_mov_b32 s10, 0x42b17218
	s_waitcnt lgkmcnt(0)
	v_mfma_f32_32x32x16_bf16 v[112:127], v[112:115], v[136:139], 0
	v_fma_f32 v136, v149, s14, -v150
	v_fmac_f32_e32 v136, 0x32a5705f, v149
	v_sub_f32_e32 v137, v150, v151
	v_add_f32_e32 v136, v137, v136
	v_exp_f32_e32 v150, v136
	ds_read_b128 v[136:139], v147 offset:18528
	v_readlane_b32 s12, v253, 28
	v_mfma_f32_32x32x16_bf16 v[96:111], v[96:99], v[140:143], 0
	ds_read_b128 v[140:143], v147 offset:18464
	v_readlane_b32 s13, v253, 29
	s_waitcnt lgkmcnt(0)
; DI void attn_pass_da(const bfr* __restrict__ P, int b, int tq_wave, int qcol, int kcol, int vcol, int key0, int nkt, char* smem, f32x16 (&o0)[2], f32x16 (&o1)[2]) {
;     ...
;     float mx0 = s0[0][0], mx1 = s1[0][0];
; #pragma unroll
;     for (int i = 0; i < 16; ++i) { mx0 = fmaxf(mx0, fmaxf(s0[0][i], s0[1][i])); mx1 = fmaxf(mx1, fmaxf(s1[0][i], s1[1][i])); }
;     mx0 = fmaxf(mx0, __shfl_xor(mx0, 32)); mx1 = fmaxf(mx1, __shfl_xor(mx1, 32));
;     const float mn0 = fmaxf(m0, mx0), mn1 = fmaxf(m1, mx1);
;     const float al0 = __builtin_amdgcn_exp2f(m0 - mn0), al1 = __builtin_amdgcn_exp2f(m1 - mn1);
;     m0 = mn0; m1 = mn1;
;     float ps0 = 0.f, ps1 = 0.f;
; #pragma unroll
;     for (int i = 0; i < 16; ++i) {
;       s0[0][i] = __builtin_amdgcn_exp2f(s0[0][i] - mn0); ps0 += s0[0][i];
;       s0[1][i] = __builtin_amdgcn_exp2f(s0[1][i] - mn0); ps0 += s0[1][i];
;       s1[0][i] = __builtin_amdgcn_exp2f(s1[0][i] - mn1); ps1 += s1[0][i];
;       s1[1][i] = __builtin_amdgcn_exp2f(s1[1][i] - mn1); ps1 += s1[1][i];
;     }
	v_mfma_f32_32x32x16_bf16 v[96:111], v[140:143], v[132:135], v[96:111]
	v_max_f32_e32 v134, v82, v82
	v_max_f32_e32 v135, v67, v67
	v_cvt_i32_f32_e32 v132, v151
	v_cndmask_b32_e32 v133, 0, v148, vcc
	v_cmp_nlt_f32_e32 vcc, s10, v146
	v_ldexp_f32 v132, v150, v132
	v_mfma_f32_32x32x16_bf16 v[112:127], v[136:139], v[128:131], v[112:127]
	s_nop 4
	v_max_f32_e32 v128, v97, v97
	v_max_f32_e32 v129, v65, v65
	v_max_f32_e32 v128, v129, v128
	v_max_f32_e32 v130, v81, v81
	v_max_f32_e32 v131, v66, v66
	v_max3_f32 v128, v64, v96, v128
	v_cndmask_b32_e32 v133, v201, v133, vcc
	v_max_f32_e32 v129, v113, v113
	v_max_f32_e32 v129, v130, v129
	v_max_f32_e32 v130, v98, v98
	v_max_f32_e32 v130, v131, v130
	v_max_f32_e32 v131, v114, v114
	v_max_f32_e32 v131, v134, v131
	v_max_f32_e32 v134, v99, v99
	v_max_f32_e32 v134, v135, v134
	v_max3_f32 v128, v128, v130, v134
	v_max_f32_e32 v130, v115, v115
	v_max_f32_e32 v134, v83, v83
	v_max3_f32 v129, v80, v112, v129
	v_max_f32_e32 v130, v134, v130
	v_max3_f32 v129, v129, v131, v130
	v_max_f32_e32 v130, v100, v100
	v_max_f32_e32 v131, v68, v68
	v_max_f32_e32 v130, v131, v130
	v_max_f32_e32 v131, v116, v116
	v_max_f32_e32 v134, v84, v84
	v_max_f32_e32 v131, v134, v131
	v_max_f32_e32 v134, v101, v101
	v_max_f32_e32 v135, v69, v69
	v_max_f32_e32 v134, v135, v134
	v_max3_f32 v128, v128, v130, v134
	v_max_f32_e32 v130, v117, v117
	v_max_f32_e32 v134, v85, v85
	v_max_f32_e32 v130, v134, v130
	v_max3_f32 v129, v129, v131, v130
	v_max_f32_e32 v130, v102, v102
	v_max_f32_e32 v131, v70, v70
	v_max_f32_e32 v130, v131, v130
	v_max_f32_e32 v131, v118, v118
	v_max_f32_e32 v134, v86, v86
	v_max_f32_e32 v131, v134, v131
	v_max_f32_e32 v134, v103, v103
	v_max_f32_e32 v135, v71, v71
	v_max_f32_e32 v134, v135, v134
	v_max3_f32 v128, v128, v130, v134
	v_max_f32_e32 v130, v119, v119
	v_max_f32_e32 v134, v87, v87
	v_max_f32_e32 v130, v134, v130
	v_max3_f32 v129, v129, v131, v130
	v_max_f32_e32 v130, v104, v104
	v_max_f32_e32 v131, v72, v72
	v_max_f32_e32 v130, v131, v130
	v_max_f32_e32 v131, v120, v120
	v_max_f32_e32 v134, v88, v88
	v_max_f32_e32 v131, v134, v131
	v_max_f32_e32 v134, v105, v105
	v_max_f32_e32 v135, v73, v73
	v_max_f32_e32 v134, v135, v134
	v_max3_f32 v128, v128, v130, v134
	v_max_f32_e32 v130, v121, v121
	v_max_f32_e32 v134, v89, v89
	v_max_f32_e32 v130, v134, v130
	v_max3_f32 v129, v129, v131, v130
	v_max_f32_e32 v130, v106, v106
	v_max_f32_e32 v131, v74, v74
	v_max_f32_e32 v130, v131, v130
	v_max_f32_e32 v131, v122, v122
	v_max_f32_e32 v134, v90, v90
	v_max_f32_e32 v131, v134, v131
	v_max_f32_e32 v134, v107, v107
	v_max_f32_e32 v135, v75, v75
	v_max_f32_e32 v134, v135, v134
	v_max3_f32 v128, v128, v130, v134
	v_max_f32_e32 v130, v123, v123
	v_max_f32_e32 v134, v91, v91
	v_max_f32_e32 v130, v134, v130
	v_max3_f32 v129, v129, v131, v130
	v_max_f32_e32 v130, v108, v108
	v_max_f32_e32 v131, v76, v76
	v_max_f32_e32 v130, v131, v130
	v_max_f32_e32 v131, v124, v124
	v_max_f32_e32 v134, v92, v92
	v_max_f32_e32 v131, v134, v131
	v_max_f32_e32 v134, v109, v109
	v_max_f32_e32 v135, v77, v77
	v_max_f32_e32 v134, v135, v134
	v_max3_f32 v128, v128, v130, v134
	v_max_f32_e32 v130, v125, v125
	v_max_f32_e32 v134, v93, v93
	v_max_f32_e32 v130, v134, v130
	v_max3_f32 v129, v129, v131, v130
	v_max_f32_e32 v130, v110, v110
	v_max_f32_e32 v131, v78, v78
	v_max_f32_e32 v130, v131, v130
	v_max_f32_e32 v131, v126, v126
	v_max_f32_e32 v134, v94, v94
	v_max_f32_e32 v131, v134, v131
	v_max_f32_e32 v134, v111, v111
	v_max_f32_e32 v135, v79, v79
	v_max_f32_e32 v134, v135, v134
	v_max3_f32 v128, v128, v130, v134
	v_max_f32_e32 v130, v127, v127
	v_max_f32_e32 v134, v95, v95
	v_max_f32_e32 v130, v134, v130
	v_max3_f32 v130, v129, v131, v130
	ds_bpermute_b32 v131, v166, v128
	ds_bpermute_b32 v134, v166, v130
	v_cmp_ngt_f32_e32 vcc, s15, v149
	s_waitcnt lgkmcnt(0)
	v_max3_f32 v150, v210, v130, v134
	v_cndmask_b32_e32 v132, 0, v132, vcc
	v_cmp_nlt_f32_e32 vcc, s10, v149
	v_max3_f32 v149, v209, v128, v131
	v_sub_f32_e32 v64, v64, v149
	v_exp_f32_e32 v148, v64
	v_sub_f32_e32 v64, v96, v149
	v_exp_f32_e32 v131, v64
	v_sub_f32_e32 v64, v80, v150
	v_exp_f32_e32 v151, v64
	v_sub_f32_e32 v64, v112, v150
	v_exp_f32_e32 v96, v64
	v_sub_f32_e32 v64, v65, v149
	v_exp_f32_e32 v152, v64
	v_sub_f32_e32 v64, v97, v149
	v_exp_f32_e32 v112, v64
	v_sub_f32_e32 v64, v81, v150
	v_exp_f32_e32 v158, v64
	v_sub_f32_e32 v64, v113, v150
	v_exp_f32_e32 v97, v64
	v_sub_f32_e32 v64, v66, v149
	v_exp_f32_e32 v143, v64
	v_sub_f32_e32 v64, v98, v149
	v_exp_f32_e32 v113, v64
	v_sub_f32_e32 v64, v82, v150
	v_exp_f32_e32 v146, v64
	v_sub_f32_e32 v64, v114, v150
	v_exp_f32_e32 v98, v64
	v_sub_f32_e32 v64, v67, v149
	v_exp_f32_e32 v147, v64
	v_sub_f32_e32 v64, v99, v149
	v_exp_f32_e32 v114, v64
	v_sub_f32_e32 v64, v83, v150
	v_exp_f32_e32 v138, v64
	v_sub_f32_e32 v64, v115, v150
	v_exp_f32_e32 v99, v64
	v_sub_f32_e32 v64, v68, v149
	v_exp_f32_e32 v139, v64
	v_sub_f32_e32 v64, v100, v149
	v_exp_f32_e32 v115, v64
	v_sub_f32_e32 v64, v84, v150
	v_exp_f32_e32 v140, v64
	v_sub_f32_e32 v64, v116, v150
	v_exp_f32_e32 v100, v64
	v_sub_f32_e32 v64, v69, v149
	v_exp_f32_e32 v141, v64
	v_sub_f32_e32 v64, v101, v149
	v_exp_f32_e32 v116, v64
	v_sub_f32_e32 v64, v85, v150
	v_exp_f32_e32 v142, v64
	v_sub_f32_e32 v64, v117, v150
	v_exp_f32_e32 v101, v64
	v_sub_f32_e32 v64, v70, v149
	v_exp_f32_e32 v134, v64
	v_sub_f32_e32 v64, v102, v149
	v_cndmask_b32_e32 v129, v201, v132, vcc
	v_exp_f32_e32 v132, v64
	v_sub_f32_e32 v64, v86, v150
	v_exp_f32_e32 v135, v64
	v_sub_f32_e32 v64, v118, v150
	v_exp_f32_e32 v117, v64
	v_sub_f32_e32 v64, v71, v149
	v_exp_f32_e32 v136, v64
	v_sub_f32_e32 v64, v103, v149
; #define MFMA32(a, b, c) __builtin_amdgcn_mfma_f32_32x32x16_bf16((a), (b), (c), 0, 0, 0)
; DI unsigned pack2(float a, float b) { unsigned r; asm volatile("v_cvt_pk_bf16_f32 %0, %1, %2" : "=v"(r) : "v"(a), "v"(b)); return r; }
; DI void attn_pass_da(const bfr* __restrict__ P, int b, int tq_wave, int qcol, int kcol, int vcol, int key0, int nkt, char* smem, f32x16 (&o0)[2], f32x16 (&o1)[2]) {
;     ...
;     for (int i = 0; i < 16; ++i) {
;       s0[0][i] = __builtin_amdgcn_exp2f(s0[0][i] - mn0); ps0 += s0[0][i];
;       s0[1][i] = __builtin_amdgcn_exp2f(s0[1][i] - mn0); ps0 += s0[1][i];
;       s1[0][i] = __builtin_amdgcn_exp2f(s1[0][i] - mn1); ps1 += s1[0][i];
;       s1[1][i] = __builtin_amdgcn_exp2f(s1[1][i] - mn1); ps1 += s1[1][i];
;     }
;     l0 = l0 * al0 + ps0; l1 = l1 * al1 + ps1;
; #pragma unroll
;     for (int i = 0; i < 16; ++i) { acc0[0][i] *= al0; acc0[1][i] *= al0; acc1[0][i] *= al1; acc1[1][i] *= al1; }
; #pragma unroll
;     for (int t2 = 0; t2 < 2; ++t2)
; #pragma unroll
;       for (int j = 0; j < 2; ++j) {
;         u32x4 pk0, pk1;
;         pk0.x = pack2(s0[t2][8 * j + 0], s0[t2][8 * j + 1]); pk0.y = pack2(s0[t2][8 * j + 2], s0[t2][8 * j + 3]);
;         pk0.z = pack2(s0[t2][8 * j + 4], s0[t2][8 * j + 5]); pk0.w = pack2(s0[t2][8 * j + 6], s0[t2][8 * j + 7]);
;         pk1.x = pack2(s1[t2][8 * j + 0], s1[t2][8 * j + 1]); pk1.y = pack2(s1[t2][8 * j + 2], s1[t2][8 * j + 3]);
;         pk1.z = pack2(s1[t2][8 * j + 4], s1[t2][8 * j + 5]); pk1.w = pack2(s1[t2][8 * j + 6], s1[t2][8 * j + 7]);
;         const bf16x8 pf0 = __builtin_bit_cast(bf16x8, pk0), pf1 = __builtin_bit_cast(bf16x8, pk1);
; #pragma unroll
;         for (int dt = 0; dt < 2; ++dt) {
;           const int vsw = (((dt * 32 + r) >> 3) & 7) << 3;
;           const bfr* vrow = sV + (dt * 32 + r) * 72;
;           s16x4 lo = *(const s16x4*)(vrow + ((t2 * 32 + 16 * j + 4 * h) ^ vsw));
;           s16x4 hi = *(const s16x4*)(vrow + ((t2 * 32 + 16 * j + 4 * h + 8) ^ vsw));
;           bf16x8 vf = __builtin_shufflevector(lo, hi, 0, 1, 2, 3, 4, 5, 6, 7);
;           acc0[dt] = MFMA32(vf, pf0, acc0[dt]);
;           acc1[dt] = MFMA32(vf, pf1, acc1[dt]);
;         }
;       }
	v_sub_f32_e32 v129, v133, v129
	v_exp_f32_e32 v133, v64
	v_sub_f32_e32 v64, v87, v150
	v_exp_f32_e32 v137, v64
	v_sub_f32_e32 v64, v119, v150
	v_exp_f32_e32 v102, v64
	v_sub_f32_e32 v64, v72, v149
	v_exp_f32_e32 v103, v64
	v_sub_f32_e32 v64, v104, v149
	v_exp_f32_e32 v71, v64
	v_sub_f32_e32 v64, v88, v150
	v_exp_f32_e32 v104, v64
	v_sub_f32_e32 v64, v120, v150
	v_exp_f32_e32 v70, v64
	v_sub_f32_e32 v64, v73, v149
	v_exp_f32_e32 v118, v64
	v_sub_f32_e32 v64, v105, v149
	v_exp_f32_e32 v73, v64
	v_sub_f32_e32 v64, v89, v150
	v_exp_f32_e32 v105, v64
	v_sub_f32_e32 v64, v121, v150
	v_exp_f32_e32 v72, v64
	v_sub_f32_e32 v64, v74, v149
	v_exp_f32_e32 v119, v64
	v_sub_f32_e32 v64, v106, v149
	v_exp_f32_e32 v81, v64
	v_sub_f32_e32 v64, v90, v150
	v_exp_f32_e32 v89, v64
	v_sub_f32_e32 v64, v122, v150
	v_exp_f32_e32 v80, v64
	v_sub_f32_e32 v64, v75, v149
	v_exp_f32_e32 v90, v64
	v_sub_f32_e32 v64, v107, v149
	v_exp_f32_e32 v87, v64
	v_sub_f32_e32 v64, v91, v150
	v_exp_f32_e32 v91, v64
	v_sub_f32_e32 v64, v123, v150
	v_exp_f32_e32 v86, v64
	v_sub_f32_e32 v64, v76, v149
	v_exp_f32_e32 v74, v64
	v_sub_f32_e32 v64, v108, v149
	v_exp_f32_e32 v75, v64
	v_sub_f32_e32 v64, v92, v150
	v_exp_f32_e32 v76, v64
	v_sub_f32_e32 v64, v124, v150
	v_exp_f32_e32 v82, v64
	v_sub_f32_e32 v64, v77, v149
	v_exp_f32_e32 v77, v64
	v_sub_f32_e32 v64, v109, v149
	v_exp_f32_e32 v83, v64
	v_sub_f32_e32 v64, v93, v150
	v_exp_f32_e32 v84, v64
	v_sub_f32_e32 v64, v125, v150
	v_exp_f32_e32 v85, v64
	v_sub_f32_e32 v64, v78, v149
	v_exp_f32_e32 v78, v64
	v_sub_f32_e32 v64, v110, v149
	v_exp_f32_e32 v88, v64
	v_sub_f32_e32 v64, v94, v150
	v_exp_f32_e32 v66, v64
	v_sub_f32_e32 v64, v126, v150
	v_exp_f32_e32 v67, v64
	v_sub_f32_e32 v64, v79, v149
	v_exp_f32_e32 v68, v64
	v_sub_f32_e32 v64, v111, v149
	v_lshl_add_u32 v79, v181, 1, v144
	v_lshl_add_u32 v110, v180, 1, v144
	v_lshl_add_u32 v124, v179, 1, v145
	v_lshl_add_u32 v126, v178, 1, v145
	v_exp_f32_e32 v69, v64
	v_sub_f32_e32 v64, v95, v150
	v_sub_f32_e32 v65, v127, v150
	v_cvt_pk_bf16_f32 v92, v148, v152
	v_cvt_pk_bf16_f32 v93, v143, v147
	v_cvt_pk_bf16_f32 v94, v139, v141
	v_cvt_pk_bf16_f32 v95, v134, v136
	v_cvt_pk_bf16_f32 v106, v151, v158
	v_cvt_pk_bf16_f32 v107, v146, v138
	v_cvt_pk_bf16_f32 v108, v140, v142
	v_cvt_pk_bf16_f32 v109, v135, v137
	ds_read_b64 v[120:121], v79 offset:27648
	ds_read_b64 v[122:123], v110 offset:27648
	ds_read_b64 v[124:125], v124 offset:27648
	ds_read_b64 v[126:127], v126 offset:27648
	v_sub_f32_e32 v128, v209, v149
	v_exp_f32_e32 v130, v128
	v_sub_f32_e32 v128, v210, v150
	v_add_f32_e32 v111, 0, v151
	v_exp_f32_e32 v128, v128
	v_add_f32_e32 v110, 0, v148
	v_add_f32_e32 v111, v96, v111
	v_add_f32_e32 v110, v131, v110
	v_add_f32_e32 v111, v158, v111
	v_add_f32_e32 v110, v152, v110
	v_add_f32_e32 v111, v97, v111
	v_add_f32_e32 v110, v112, v110
	v_add_f32_e32 v111, v146, v111
	v_pk_mul_f32 v[46:47], v[46:47], v[128:129] op_sel_hi:[1,0]
	v_pk_mul_f32 v[44:45], v[44:45], v[128:129] op_sel_hi:[1,0]
	v_pk_mul_f32 v[42:43], v[42:43], v[128:129] op_sel_hi:[1,0]
	v_pk_mul_f32 v[40:41], v[40:41], v[128:129] op_sel_hi:[1,0]
	v_pk_mul_f32 v[38:39], v[38:39], v[128:129] op_sel_hi:[1,0]
	v_pk_mul_f32 v[36:37], v[36:37], v[128:129] op_sel_hi:[1,0]
	v_pk_mul_f32 v[34:35], v[34:35], v[128:129] op_sel_hi:[1,0]
	v_pk_mul_f32 v[32:33], v[32:33], v[128:129] op_sel_hi:[1,0]
	v_pk_mul_f32 v[14:15], v[14:15], v[128:129] op_sel_hi:[1,0]
	v_pk_mul_f32 v[12:13], v[12:13], v[128:129] op_sel_hi:[1,0]
	v_pk_mul_f32 v[10:11], v[10:11], v[128:129] op_sel_hi:[1,0]
	v_pk_mul_f32 v[8:9], v[8:9], v[128:129] op_sel_hi:[1,0]
	v_pk_mul_f32 v[6:7], v[6:7], v[128:129] op_sel_hi:[1,0]
	v_pk_mul_f32 v[4:5], v[4:5], v[128:129] op_sel_hi:[1,0]
	v_pk_mul_f32 v[2:3], v[2:3], v[128:129] op_sel_hi:[1,0]
	v_pk_mul_f32 v[0:1], v[0:1], v[128:129] op_sel_hi:[1,0]
	v_add_f32_e32 v110, v143, v110
	v_add_f32_e32 v111, v98, v111
	s_waitcnt lgkmcnt(2)
	v_mfma_f32_32x32x16_bf16 v[32:47], v[120:123], v[106:109], v[32:47]
	v_add_f32_e32 v110, v113, v110
	v_add_f32_e32 v110, v147, v110
	v_add_f32_e32 v110, v114, v110
	v_mul_f32_e64 v62, v62, v130
	v_mul_f32_e64 v63, v63, v130
	v_pk_mul_f32 v[60:61], v[60:61], v[130:131] op_sel_hi:[1,0]
	v_pk_mul_f32 v[58:59], v[58:59], v[130:131] op_sel_hi:[1,0]
	v_pk_mul_f32 v[56:57], v[56:57], v[130:131] op_sel_hi:[1,0]
	s_waitcnt lgkmcnt(0)
	v_mfma_f32_32x32x16_bf16 v[0:15], v[124:127], v[106:109], v[0:15]
	v_add_f32_e32 v106, v138, v111
	v_add_f32_e32 v106, v99, v106
	v_add_f32_e32 v106, v140, v106
	v_add_f32_e32 v107, v139, v110
	v_add_f32_e32 v106, v100, v106
	v_add_f32_e32 v107, v115, v107
	v_add_f32_e32 v106, v142, v106
	v_pk_mul_f32 v[54:55], v[54:55], v[130:131] op_sel_hi:[1,0]
	v_pk_mul_f32 v[52:53], v[52:53], v[130:131] op_sel_hi:[1,0]
	v_pk_mul_f32 v[50:51], v[50:51], v[130:131] op_sel_hi:[1,0]
	v_pk_mul_f32 v[48:49], v[48:49], v[130:131] op_sel_hi:[1,0]
	v_pk_mul_f32 v[30:31], v[30:31], v[130:131] op_sel_hi:[1,0]
	v_pk_mul_f32 v[28:29], v[28:29], v[130:131] op_sel_hi:[1,0]
	v_pk_mul_f32 v[26:27], v[26:27], v[130:131] op_sel_hi:[1,0]
	v_pk_mul_f32 v[24:25], v[24:25], v[130:131] op_sel_hi:[1,0]
	v_pk_mul_f32 v[22:23], v[22:23], v[130:131] op_sel_hi:[1,0]
	v_pk_mul_f32 v[20:21], v[20:21], v[130:131] op_sel_hi:[1,0]
	v_pk_mul_f32 v[18:19], v[18:19], v[130:131] op_sel_hi:[1,0]
	v_pk_mul_f32 v[16:17], v[16:17], v[130:131] op_sel_hi:[1,0]
	v_lshl_add_u32 v143, v177, 1, v144
	v_add_f32_e32 v107, v141, v107
	v_add_f32_e32 v111, v101, v106
	v_lshl_add_u32 v106, v175, 1, v145
	v_lshl_add_u32 v108, v174, 1, v145
	v_exp_f32_e32 v64, v64
	v_mfma_f32_32x32x16_bf16 v[48:63], v[120:123], v[92:95], v[48:63]
	v_add_f32_e32 v110, v116, v107
	v_add_f32_e32 v110, v134, v110
	v_add_f32_e32 v110, v132, v110
	v_add_f32_e32 v110, v136, v110
	v_add_f32_e32 v111, v135, v111
	v_add_f32_e32 v111, v117, v111
	v_exp_f32_e32 v65, v65
	v_mfma_f32_32x32x16_bf16 v[16:31], v[124:127], v[92:95], v[16:31]
	v_cvt_pk_bf16_f32 v92, v103, v118
	v_cvt_pk_bf16_f32 v93, v119, v90
	v_cvt_pk_bf16_f32 v94, v74, v77
	v_cvt_pk_bf16_f32 v95, v78, v68
	v_cvt_pk_bf16_f32 v120, v104, v105
	v_cvt_pk_bf16_f32 v121, v89, v91
	v_cvt_pk_bf16_f32 v122, v76, v84
	v_cvt_pk_bf16_f32 v123, v66, v64
	ds_read_b64 v[146:147], v143 offset:27648
	ds_read_b64 v[106:107], v106 offset:27648
	ds_read_b64 v[108:109], v108 offset:27648
	v_lshl_add_u32 v143, v176, 1, v144
	ds_read_b64 v[148:149], v143 offset:27648
	v_add_f32_e32 v124, v133, v110
	s_waitcnt lgkmcnt(0)
; DI int vhalf() { int h = __builtin_amdgcn_readfirstlane(threadIdx.x >> 8); asm volatile("" : "+s"(h)); return h; }
; #define MFMA32(a, b, c) __builtin_amdgcn_mfma_f32_32x32x16_bf16((a), (b), (c), 0, 0, 0)
; DI void attn_pass_da(const bfr* __restrict__ P, int b, int tq_wave, int qcol, int kcol, int vcol, int key0, int nkt, char* smem, f32x16 (&o0)[2], f32x16 (&o1)[2]) {
;     ...
;           acc0[dt] = MFMA32(vf, pf0, acc0[dt]);
;           acc1[dt] = MFMA32(vf, pf1, acc1[dt]);
;         }
;       }
;   }
;   l0 += __shfl_xor(l0, 32); l1 += __shfl_xor(l1, 32);
;   const float i0 = 1.f / l0, i1 = 1.f / l1;
; #pragma unroll
;   for (int i = 0; i < 16; ++i) { o0[0][i] = acc0[0][i] * i0; o0[1][i] = acc0[1][i] * i0; o1[0][i] = acc1[0][i] * i1; o1[1][i] = acc1[1][i] * i1; }
; DN void da_item(const Params& p, int l, int b, int hd, int tq0, int key0, int nkt, char* smem) {
;     ...
;   float lam = expf(d01) - expf(d23) + lam_init;
;   f32x16 o0[2], o1[2];
;   int tqw = tq0 + vhalf() * 128 + w * 32;
;   attn_pass_da(P, b, tqw, 1152 + hd * 64, 1408 + hd * 64, 1664 + hd * 64, key0, nkt, smem, o0, o1);
;   float ss = 0.f;
; #pragma unroll
;   for (int dt = 0; dt < 2; ++dt)
; #pragma unroll
;     for (int i = 0; i < 16; ++i) { float v = o0[dt][i] - lam * o1[dt][i]; o0[dt][i] = v; ss += v * v; }
	v_mfma_f32_32x32x16_bf16 v[48:63], v[146:149], v[92:95], v[48:63]
	v_add_f32_e32 v125, v137, v111
	v_lshlrev_b32_e32 v152, 1, v154
	v_mfma_f32_32x32x16_bf16 v[16:31], v[106:109], v[92:95], v[16:31]
	v_cvt_pk_bf16_f32 v92, v131, v112
	v_cvt_pk_bf16_f32 v93, v113, v114
	v_cvt_pk_bf16_f32 v94, v115, v116
	v_cvt_pk_bf16_f32 v95, v132, v133
	v_cvt_pk_bf16_f32 v96, v96, v97
	v_cvt_pk_bf16_f32 v97, v98, v99
	v_cvt_pk_bf16_f32 v98, v100, v101
	v_add_f32_e32 v100, v103, v124
	v_add_f32_e32 v100, v71, v100
	v_cvt_pk_bf16_f32 v99, v117, v102
	ds_read_b64 v[110:111], v79 offset:27712
	v_lshl_add_u32 v79, v173, 1, v144
	v_add_f32_e32 v100, v118, v100
	ds_read_b64 v[112:113], v79 offset:27648
	v_add_f32_e32 v79, v102, v125
	v_add_f32_e32 v100, v73, v100
	v_add_f32_e32 v79, v104, v79
	v_add_f32_e32 v104, v119, v100
	v_lshl_add_u32 v100, v172, 1, v145
	v_lshl_add_u32 v102, v171, 1, v145
	ds_read_b64 v[100:101], v100 offset:27648
	ds_read_b64 v[102:103], v102 offset:27648
	v_add_f32_e32 v79, v70, v79
	v_add_f32_e32 v79, v105, v79
	v_add_f32_e32 v79, v72, v79
	v_add_f32_e32 v104, v81, v104
	v_add_f32_e32 v79, v89, v79
	v_add_f32_e32 v79, v80, v79
	v_add_f32_e32 v89, v90, v104
	v_add_f32_e32 v89, v87, v89
	v_add_f32_e32 v79, v91, v79
	v_add_f32_e32 v79, v86, v79
	v_add_f32_e32 v74, v74, v89
	s_waitcnt lgkmcnt(2)
	v_mfma_f32_32x32x16_bf16 v[48:63], v[110:113], v[92:95], v[48:63]
	v_cvt_pk_bf16_f32 v90, v71, v73
	v_cvt_pk_bf16_f32 v91, v81, v87
	v_add_f32_e32 v74, v75, v74
	v_add_f32_e32 v74, v77, v74
	v_add_f32_e32 v74, v83, v74
	v_add_f32_e32 v74, v78, v74
	v_add_f32_e32 v78, v88, v74
	s_waitcnt lgkmcnt(0)
	v_mfma_f32_32x32x16_bf16 v[16:31], v[100:103], v[92:95], v[16:31]
	v_cvt_pk_bf16_f32 v92, v75, v83
	v_add_f32_e32 v75, v76, v79
	v_add_f32_e32 v75, v82, v75
	v_add_f32_e32 v75, v84, v75
	v_add_f32_e32 v79, v85, v75
	v_add_f32_e32 v66, v66, v79
	v_cvt_pk_bf16_f32 v93, v88, v69
	v_mfma_f32_32x32x16_bf16 v[32:47], v[146:149], v[120:123], v[32:47]
	v_cvt_pk_bf16_f32 v70, v70, v72
	v_cvt_pk_bf16_f32 v71, v80, v86
	v_cvt_pk_bf16_f32 v72, v82, v85
	v_cvt_pk_bf16_f32 v73, v67, v65
	v_add_f32_e32 v66, v67, v66
	v_add_f32_e32 v67, v68, v78
	v_add_f32_e32 v67, v69, v67
	v_mfma_f32_32x32x16_bf16 v[0:15], v[106:109], v[120:123], v[0:15]
	v_fmac_f32_e32 v67, v156, v130
	ds_bpermute_b32 v68, v166, v67
	v_lshl_add_u32 v80, v169, 1, v144
	v_lshl_add_u32 v74, v168, 1, v145
	v_lshl_add_u32 v76, v167, 1, v145
	ds_read_b64 v[104:105], v80 offset:27648
	ds_read_b64 v[74:75], v74 offset:27648
	ds_read_b64 v[76:77], v76 offset:27648
	v_lshl_add_u32 v80, v170, 1, v144
	v_add_f32_e32 v64, v64, v66
	ds_read_b64 v[106:107], v80 offset:27648
	v_add_f32_e32 v65, v65, v64
	v_mfma_f32_32x32x16_bf16 v[32:47], v[110:113], v[96:99], v[32:47]
	v_fmac_f32_e32 v65, v157, v128
	s_waitcnt lgkmcnt(4)
	v_add_f32_e32 v66, v67, v68
	ds_bpermute_b32 v67, v166, v65
	v_div_scale_f32 v68, s[10:11], v66, v66, 1.0
	v_rcp_f32_e32 v69, v68
	v_add_f32_e32 v64, v155, v129
	v_mfma_f32_32x32x16_bf16 v[0:15], v[100:103], v[96:99], v[0:15]
	s_waitcnt lgkmcnt(0)
	v_add_f32_e32 v65, v65, v67
	v_fma_f32 v67, -v68, v69, 1.0
	v_fmac_f32_e32 v69, v67, v69
	v_div_scale_f32 v67, vcc, 1.0, v66, 1.0
	v_mfma_f32_32x32x16_bf16 v[32:47], v[104:107], v[70:73], v[32:47]
	v_mfma_f32_32x32x16_bf16 v[0:15], v[74:77], v[70:73], v[0:15]
	v_mul_f32_e32 v70, v67, v69
	v_fma_f32 v71, -v68, v70, v67
	v_fmac_f32_e32 v70, v71, v69
	v_fma_f32 v67, -v68, v70, v67
	v_div_scale_f32 v68, s[10:11], v65, v65, 1.0
	v_rcp_f32_e32 v71, v68
	v_div_fmas_f32 v67, v67, v69, v70
	v_div_fixup_f32 v66, v67, v66, 1.0
	v_mfma_f32_32x32x16_bf16 v[48:63], v[104:107], v[90:93], v[48:63]
	v_fma_f32 v67, -v68, v71, 1.0
	v_fmac_f32_e32 v71, v67, v71
	v_div_scale_f32 v67, vcc, 1.0, v65, 1.0
	v_mul_f32_e32 v69, v67, v71
	v_fma_f32 v70, -v68, v69, v67
	v_fmac_f32_e32 v69, v70, v71
	v_fma_f32 v67, -v68, v69, v67
	v_div_fmas_f32 v67, v67, v71, v69
	v_div_fixup_f32 v68, v67, v65, 1.0
	v_mul_f32_e32 v65, v0, v68
	v_mul_f32_e32 v0, v33, v68
	v_mul_f32_e32 v67, v1, v68
	v_mul_f32_e32 v1, v34, v68
	v_mul_f32_e32 v0, v64, v0
	v_mul_f32_e32 v32, v32, v68
	v_mul_f32_e32 v69, v2, v68
	v_mul_f32_e32 v2, v35, v68
	v_mul_f32_e32 v33, v37, v68
	v_mul_f32_e32 v37, v41, v68
	v_mul_f32_e32 v41, v45, v68
	v_fma_f32 v45, v49, v66, -v0
	v_mul_f32_e32 v0, v64, v1
	v_mul_f32_e32 v70, v3, v68
	v_mul_f32_e32 v3, v36, v68
	v_mul_f32_e32 v35, v39, v68
	v_mul_f32_e32 v39, v43, v68
	v_mul_f32_e32 v43, v47, v68
	v_mul_f32_e32 v32, v64, v32
	v_fma_f32 v47, v50, v66, -v0
	v_mul_f32_e32 v0, v64, v2
	v_mul_f32_e32 v36, v40, v68
	v_mul_f32_e32 v40, v44, v68
	v_fma_f32 v44, v48, v66, -v32
	v_fma_f32 v48, v51, v66, -v0
	v_mul_f32_e32 v0, v64, v3
	v_mul_f32_e32 v34, v38, v68
	v_fma_f32 v49, v52, v66, -v0
	v_mul_f32_e32 v0, v64, v33
	s_mov_b32 s10, 23
	v_fma_f32 v50, v53, v66, -v0
	v_mul_f32_e32 v0, v64, v34
	s_ashr_i32 s11, s10, 31
	v_fma_f32 v51, v54, v66, -v0
	v_mul_f32_e32 v0, v64, v35
	s_lshl_b64 s[10:11], s[10:11], 3
	v_fma_f32 v52, v55, v66, -v0
	v_mul_f32_e32 v0, v64, v36
	s_add_u32 s10, s0, s10
	v_mul_f32_e32 v38, v42, v68
	v_fma_f32 v53, v56, v66, -v0
	v_mul_f32_e32 v0, v64, v37
	s_addc_u32 s11, s1, s11
	v_fma_f32 v54, v57, v66, -v0
	v_mul_f32_e32 v0, v64, v38
	s_load_dwordx2 s[10:11], s[10:11], 0x0
	v_mul_f32_e32 v42, v46, v68
	v_mul_f32_e32 v46, v45, v45
	v_fma_f32 v55, v58, v66, -v0
	v_mul_f32_e32 v0, v64, v39
	v_fmac_f32_e32 v46, v44, v44
	v_fma_f32 v56, v59, v66, -v0
	v_mul_f32_e32 v0, v64, v40
	v_fmac_f32_e32 v46, v47, v47
	v_fma_f32 v57, v60, v66, -v0
	v_mul_f32_e32 v0, v64, v41
	v_fmac_f32_e32 v46, v48, v48
	v_fma_f32 v58, v61, v66, -v0
	s_lshl_b64 s[12:13], s[12:13], 2
	v_lshrrev_b32_e32 v0, 3, v164
	v_fmac_f32_e32 v46, v49, v49
	s_waitcnt lgkmcnt(0)
; DI int oidx(int i) { asm volatile("" : "+s"(i)); return i; }
; DN void da_item(const Params& p, int l, int b, int hd, int tq0, int key0, int nkt, char* smem) {
;     ...
;   float ss = 0.f;
; #pragma unroll
;   for (int dt = 0; dt < 2; ++dt)
; #pragma unroll
;     for (int i = 0; i < 16; ++i) { float v = o0[dt][i] - lam * o1[dt][i]; o0[dt][i] = v; ss += v * v; }
;   ss += __shfl_xor(ss, 32);
;   float rstd = rsqrtf(ss * (1.f / 64.f) + 1e-6f) * (1.f - lam_init);
;   const float* sg = p.in[oidx(23)] + l * 64;
; #pragma unroll
;   for (int dt = 0; dt < 2; ++dt)
; #pragma unroll
;     for (int i = 0; i < 16; ++i) { int dv = dt * 32 + 8 * (i >> 2) + 4 * h + (i & 3); o0[dt][i] = o0[dt][i] * rstd * sg[dv]; }
;   store_o(O, b * TT + tqw + r, 256 + hd * 64, h, o0);
	s_add_u32 s10, s10, s12
	v_and_b32_e32 v59, 4, v0
	v_fmac_f32_e32 v46, v50, v50
	s_addc_u32 s11, s11, s13
	v_lshlrev_b32_e32 v60, 2, v59
	v_mfma_f32_32x32x16_bf16 v[16:31], v[74:77], v[90:93], v[16:31]
	v_fmac_f32_e32 v46, v51, v51
	global_load_dwordx4 v[0:3], v60, s[10:11]
	v_fmac_f32_e32 v46, v52, v52
	v_fmac_f32_e32 v46, v53, v53
	v_mul_f32_e32 v32, v64, v42
	v_fmac_f32_e32 v46, v54, v54
	v_fma_f32 v61, v62, v66, -v32
	v_mul_f32_e32 v32, v64, v43
	v_fmac_f32_e32 v46, v55, v55
	v_fma_f32 v62, v63, v66, -v32
	global_load_dwordx4 v[32:35], v60, s[10:11] offset:32
	v_fmac_f32_e32 v46, v56, v56
	v_fmac_f32_e32 v46, v57, v57
	v_fmac_f32_e32 v46, v58, v58
	v_mul_f32_e32 v36, v64, v65
	v_fmac_f32_e32 v46, v61, v61
	v_fma_f32 v63, v16, v66, -v36
	v_mul_f32_e32 v16, v64, v67
	global_load_dwordx4 v[36:39], v60, s[10:11] offset:64
	v_mul_f32_e32 v4, v4, v68
	v_fmac_f32_e32 v46, v62, v62
	v_fma_f32 v65, v17, v66, -v16
	v_mul_f32_e32 v16, v64, v69
	v_mul_f32_e32 v5, v5, v68
	v_fmac_f32_e32 v46, v63, v63
	v_fma_f32 v67, v18, v66, -v16
	v_mul_f32_e32 v16, v64, v70
	v_mul_f32_e32 v4, v64, v4
	v_fmac_f32_e32 v46, v65, v65
	v_fma_f32 v69, v19, v66, -v16
	v_fma_f32 v70, v20, v66, -v4
	v_mul_f32_e32 v4, v64, v5
	v_fmac_f32_e32 v46, v67, v67
	global_load_dwordx4 v[16:19], v60, s[10:11] offset:96
	v_fma_f32 v71, v21, v66, -v4
	v_pk_mul_f32 v[4:5], v[6:7], v[68:69] op_sel_hi:[1,0]
	v_fmac_f32_e32 v46, v69, v69
	v_pk_mul_f32 v[4:5], v[64:65], v[4:5] op_sel_hi:[0,1]
	v_fmac_f32_e32 v46, v70, v70
	v_pk_fma_f32 v[40:41], v[22:23], v[66:67], v[4:5] op_sel_hi:[1,0,1] neg_lo:[0,0,1] neg_hi:[0,0,1]
	v_pk_mul_f32 v[8:9], v[8:9], v[68:69] op_sel_hi:[1,0]
	v_fmac_f32_e32 v46, v71, v71
	v_pk_mul_f32 v[20:21], v[40:41], v[40:41]
	v_pk_mul_f32 v[8:9], v[64:65], v[8:9] op_sel_hi:[0,1]
	global_load_dwordx4 v[4:7], v60, s[10:11] offset:128
	v_add_f32_e32 v20, v20, v46
	v_pk_fma_f32 v[24:25], v[24:25], v[66:67], v[8:9] op_sel_hi:[1,0,1] neg_lo:[0,0,1] neg_hi:[0,0,1]
	v_add_f32_e32 v20, v21, v20
	v_pk_mul_f32 v[8:9], v[24:25], v[24:25]
	v_pk_mul_f32 v[12:13], v[12:13], v[68:69] op_sel_hi:[1,0]
	v_add_f32_e32 v8, v8, v20
	v_add_f32_e32 v42, v9, v8
	v_pk_mul_f32 v[8:9], v[10:11], v[68:69] op_sel_hi:[1,0]
	global_load_dwordx4 v[20:23], v60, s[10:11] offset:160
	v_pk_mul_f32 v[8:9], v[64:65], v[8:9] op_sel_hi:[0,1]
	v_pk_fma_f32 v[26:27], v[26:27], v[66:67], v[8:9] op_sel_hi:[1,0,1] neg_lo:[0,0,1] neg_hi:[0,0,1]
	v_pk_mul_f32 v[12:13], v[64:65], v[12:13] op_sel_hi:[0,1]
	v_pk_mul_f32 v[8:9], v[26:27], v[26:27]
	v_pk_fma_f32 v[28:29], v[28:29], v[66:67], v[12:13] op_sel_hi:[1,0,1] neg_lo:[0,0,1] neg_hi:[0,0,1]
	v_add_f32_e32 v8, v8, v42
	v_add_f32_e32 v42, v9, v8
	global_load_dwordx4 v[8:11], v60, s[10:11] offset:192
	v_pk_mul_f32 v[12:13], v[28:29], v[28:29]
	s_load_dwordx4 s[12:15], s[0:1], 0x100
	v_add_f32_e32 v12, v12, v42
	v_add_f32_e32 v46, v13, v12
	v_pk_mul_f32 v[42:43], v[14:15], v[68:69] op_sel_hi:[1,0]
	global_load_dwordx4 v[12:15], v60, s[10:11] offset:224
	v_pk_mul_f32 v[42:43], v[64:65], v[42:43] op_sel_hi:[0,1]
	v_pk_fma_f32 v[30:31], v[30:31], v[66:67], v[42:43] op_sel_hi:[1,0,1] neg_lo:[0,0,1] neg_hi:[0,0,1]
	s_mov_b64 s[10:11], 0x2b7c300
	v_pk_mul_f32 v[42:43], v[30:31], v[30:31]
	s_nop 0
	v_add_f32_e32 v42, v42, v46
	v_add_f32_e32 v42, v43, v42
	ds_bpermute_b32 v43, v166, v42
	s_waitcnt lgkmcnt(0)
	v_add_f32_e32 v42, v42, v43
	v_fmamk_f32 v42, v42, 0x3c800000, v186
	v_cmp_gt_f32_e32 vcc, s33, v42
	v_mul_f32_e32 v43, 0x4b800000, v42
	s_nop 0
	v_cndmask_b32_e32 v42, v42, v43, vcc
	v_rsq_f32_e32 v42, v42
	s_nop 0
	v_mul_f32_e32 v43, 0x45800000, v42
	v_cndmask_b32_e32 v42, v42, v43, vcc
	v_mul_f32_e32 v42, v162, v42
	v_mul_f32_e32 v43, v44, v42
	s_waitcnt vmcnt(7)
	v_mul_f32_e32 v43, v0, v43
	v_mul_f32_e32 v0, v45, v42
	v_mul_f32_e32 v44, v1, v0
	v_mul_f32_e32 v0, v47, v42
	v_mul_f32_e32 v45, v2, v0
	v_mul_f32_e32 v0, v48, v42
	v_mul_f32_e32 v3, v3, v0
	v_mul_f32_e32 v0, v49, v42
	s_waitcnt vmcnt(6)
	v_mul_f32_e32 v32, v32, v0
	v_mul_f32_e32 v0, v50, v42
	v_mul_f32_e32 v33, v33, v0
	v_mul_f32_e32 v0, v51, v42
	v_mul_f32_e32 v34, v34, v0
	v_mul_f32_e32 v0, v52, v42
	v_mul_f32_e32 v35, v35, v0
	v_mul_f32_e32 v0, v53, v42
	s_waitcnt vmcnt(5)
	v_mul_f32_e32 v36, v36, v0
	v_mul_f32_e32 v0, v54, v42
	v_mul_f32_e32 v37, v37, v0
	v_mul_f32_e32 v0, v55, v42
	v_mul_f32_e32 v38, v38, v0
	v_mul_f32_e32 v0, v56, v42
	v_mul_f32_e32 v39, v39, v0
	v_mul_f32_e32 v0, v57, v42
	s_waitcnt vmcnt(4)
	v_mul_f32_e32 v16, v16, v0
	v_mul_f32_e32 v0, v58, v42
	v_mul_f32_e32 v17, v17, v0
	v_mul_f32_e32 v0, v61, v42
	v_mul_f32_e32 v18, v18, v0
	v_mul_f32_e32 v0, v62, v42
	v_mul_f32_e32 v19, v19, v0
	v_mul_f32_e32 v0, v63, v42
	s_waitcnt vmcnt(3)
	v_mul_f32_e32 v46, v4, v0
	v_mul_f32_e32 v0, v65, v42
	v_mul_f32_e32 v47, v5, v0
	v_mul_f32_e32 v0, v67, v42
	v_mul_f32_e32 v6, v6, v0
	v_mul_f32_e32 v0, v69, v42
	v_mul_f32_e32 v7, v7, v0
	v_mul_f32_e32 v0, v70, v42
	s_waitcnt vmcnt(2)
	v_mul_f32_e32 v20, v20, v0
	v_mul_f32_e32 v0, v71, v42
	v_mul_f32_e32 v21, v21, v0
	v_mul_f32_e32 v0, v40, v42
	v_mul_f32_e32 v22, v22, v0
	v_mul_f32_e32 v0, v41, v42
	v_mul_f32_e32 v23, v23, v0
	v_mul_f32_e32 v0, v24, v42
	s_waitcnt vmcnt(1)
	v_mul_f32_e32 v8, v8, v0
	v_mul_f32_e32 v0, v25, v42
	v_mul_f32_e32 v9, v9, v0
	v_mul_f32_e32 v0, v26, v42
	v_mul_f32_e32 v10, v10, v0
	v_mul_f32_e32 v0, v27, v42
	v_mul_f32_e32 v11, v11, v0
	v_mul_f32_e32 v0, v28, v42
	s_waitcnt vmcnt(0)
	v_mul_f32_e32 v12, v12, v0
	v_mul_f32_e32 v0, v29, v42
	v_mul_f32_e32 v13, v13, v0
	v_mul_f32_e32 v0, v30, v42
	v_mul_f32_e32 v14, v14, v0
	v_mul_f32_e32 v0, v31, v42
	v_mul_f32_e32 v15, v15, v0
	v_and_or_b32 v0, v164, 31, v165
	v_ashrrev_i32_e32 v1, 31, v0
	v_lshlrev_b64 v[0:1], 11, v[0:1]
	v_lshl_add_u64 v[0:1], s[14:15], 0, v[0:1]
	v_lshl_add_u64 v[0:1], v[0:1], 0, v[152:153]
	v_lshlrev_b32_e32 v152, 1, v59
	v_lshl_add_u64 v[0:1], v[0:1], 0, v[152:153]
	v_lshl_add_u64 v[4:5], v[0:1], 0, s[10:11]
	s_mov_b32 s10, 0x2b7c000
	v_add_co_u32_e32 v0, vcc, s10, v0
	v_cvt_pk_bf16_f32 v2, v43, v44
	v_cvt_pk_bf16_f32 v3, v45, v3
	s_nop 1
	v_addc_co_u32_e32 v1, vcc, 0, v1, vcc
	global_store_dwordx2 v[0:1], v[2:3], off offset:768
	v_cvt_pk_bf16_f32 v0, v32, v33
	v_cvt_pk_bf16_f32 v1, v34, v35
	global_store_dwordx2 v[4:5], v[0:1], off offset:16
	v_cvt_pk_bf16_f32 v0, v36, v37
	v_cvt_pk_bf16_f32 v1, v38, v39
	global_store_dwordx2 v[4:5], v[0:1], off offset:32
	v_cvt_pk_bf16_f32 v0, v16, v17
	v_cvt_pk_bf16_f32 v1, v18, v19
	global_store_dwordx2 v[4:5], v[0:1], off offset:48
	v_cvt_pk_bf16_f32 v0, v46, v47
	v_cvt_pk_bf16_f32 v1, v6, v7
	global_store_dwordx2 v[4:5], v[0:1], off offset:64
	v_cvt_pk_bf16_f32 v0, v20, v21
	v_cvt_pk_bf16_f32 v1, v22, v23
	global_store_dwordx2 v[4:5], v[0:1], off offset:80
	v_cvt_pk_bf16_f32 v0, v8, v9
	v_cvt_pk_bf16_f32 v1, v10, v11
	global_store_dwordx2 v[4:5], v[0:1], off offset:96
	v_cvt_pk_bf16_f32 v0, v12, v13
	v_cvt_pk_bf16_f32 v1, v14, v15
	global_store_dwordx2 v[4:5], v[0:1], off offset:112
	s_or_b64 exec, exec, s[8:9]

; #define MFMA32(a, b, c) __builtin_amdgcn_mfma_f32_32x32x16_bf16((a), (b), (c), 0, 0, 0)
; template <int D>
; DI void attn_pass(const bfr* __restrict__ P, int b, int tq_wave, int qcol, int kcol, int vcol, int key0, int nkt, char* smem, f32x16 (&o)[2]) {
;     ...
;   for (int kt = 0; kt < nkt; ++kt) {
;     bfr* sK = sbase + (kt & 1) * 9216;
;     bfr* sV = sK + 64 * 72;
;     { int c = gt, row = c >> 3, kc = c & 7; *(u32x4*)(sK + row * KP + kc * 8) = kreg[0]; }
;     for (int i = 0; i < 1; ++i) {
;       int c = gt, row = c >> 3, kc = c & 7;
;       unsigned wds[4] = {vreg[i].x, vreg[i].y, vreg[i].z, vreg[i].w};
; #pragma unroll
;       for (int e = 0; e < 4; ++e) {
;         sV[(kc * 8 + 2 * e) * 72 + (row ^ (kc << 3))] = (bfr)(wds[e] & 0xffffu);
;         sV[(kc * 8 + 2 * e + 1) * 72 + (row ^ (kc << 3))] = (bfr)(wds[e] >> 16);
;       }
;     }
;     __syncthreads();
;     if (kt + 1 < nkt) {
;       const bfr* Pn = Pb + (size_t)(kt + 1) * 64 * PW;
;       { int c = gt, row = c >> 3, kc = c & 7; kreg[0] = *(const u32x4*)(Pn + (size_t)row * PW + kcol + kc * 8); vreg[0] = *(const u32x4*)(Pn + (size_t)row * PW + vcol + kc * 8); }
;     }
;     f32x16 s[2];
; #pragma unroll
;     for (int t2 = 0; t2 < 2; ++t2) {
; #pragma unroll
;       for (int i = 0; i < 16; ++i) s[t2][i] = 0.f;
; #pragma unroll
;       for (int ks = 0; ks < KS; ++ks) {
;         bf16x8 a = *(const bf16x8*)(sK + (t2 * 32 + r) * KP + ks * 16 + h * 8);
;         s[t2] = MFMA32(a, qf[ks], s[t2]);
;       }
;     }
;     float mx = s[0][0];
; #pragma unroll
;     for (int i = 0; i < 16; ++i) { mx = fmaxf(mx, s[0][i]); mx = fmaxf(mx, s[1][i]); }
;     mx = fmaxf(mx, __shfl_xor(mx, 32));
;     float mnew = fmaxf(mrun, mx);
;     float alpha = __builtin_amdgcn_exp2f(mrun - mnew);
;     mrun = mnew;
;     float ps = 0.f;
; #pragma unroll
;     for (int i = 0; i < 16; ++i) {
;       s[0][i] = __builtin_amdgcn_exp2f(s[0][i] - mnew); ps += s[0][i];
;       s[1][i] = __builtin_amdgcn_exp2f(s[1][i] - mnew); ps += s[1][i];
;     }
.LBB0_412:
	s_bitcmp1_b32 s8, 0
	s_cselect_b32 s9, 0x4800, 0
	s_add_i32 s9, s9, 0
	v_add3_u32 v32, s9, v115, v90
	v_add_u32_e32 v121, s9, v114
	v_mov_b32_e32 v120, v113
	s_waitcnt vmcnt(1)
	ds_write_b128 v32, v[84:87]
	v_add3_u32 v32, s9, v117, v118
	v_add3_u32 v33, s9, v118, v117
	v_add_u32_e32 v113, v121, v152
	s_waitcnt vmcnt(0)
	ds_write_b16 v32, v80 offset:9216
	ds_write_b16_d16_hi v33, v80 offset:9360
	ds_write_b16 v32, v81 offset:9504
	ds_write_b16_d16_hi v33, v81 offset:9648
	ds_write_b16 v32, v82 offset:9792
	ds_write_b16_d16_hi v33, v82 offset:9936
	ds_write_b16 v32, v83 offset:10080
	ds_write_b16_d16_hi v33, v83 offset:10224
	s_waitcnt lgkmcnt(0)
	s_barrier
	global_load_dwordx4 v[84:87], v[92:93], off
	global_load_dwordx4 v[80:83], v[94:95], off
	ds_read_b128 v[126:129], v113
	ds_read_b128 v[130:133], v113 offset:32
	ds_read_b128 v[134:137], v113 offset:64
	ds_read_b128 v[138:141], v113 offset:96
	ds_read_b128 v[142:145], v113 offset:4608
	ds_read_b128 v[146:149], v113 offset:4640
	ds_read_b128 v[156:159], v113 offset:4672
	ds_read_b128 v[164:167], v113 offset:4704
	v_mov_b32_e32 v96, v119
	s_waitcnt lgkmcnt(7)
	v_mfma_f32_32x32x16_bf16 v[32:47], v[126:129], v[76:79], 0
	s_add_i32 s8, s8, 1
	s_waitcnt lgkmcnt(6)
	v_mfma_f32_32x32x16_bf16 v[32:47], v[130:133], v[72:75], v[32:47]
	v_lshl_add_u64 v[92:93], v[92:93], 0, s[10:11]
	s_waitcnt lgkmcnt(5)
	v_mfma_f32_32x32x16_bf16 v[32:47], v[134:137], v[68:71], v[32:47]
	v_lshl_add_u64 v[94:95], v[94:95], 0, s[10:11]
	s_waitcnt lgkmcnt(4)
	v_mfma_f32_32x32x16_bf16 v[32:47], v[138:141], v[64:67], v[32:47]
	s_cmp_lg_u32 s8, 35
	s_waitcnt lgkmcnt(3)
	v_mfma_f32_32x32x16_bf16 v[48:63], v[142:145], v[76:79], 0
	s_waitcnt lgkmcnt(2)
	v_mfma_f32_32x32x16_bf16 v[48:63], v[146:149], v[72:75], v[48:63]
	s_waitcnt lgkmcnt(1)
	v_mfma_f32_32x32x16_bf16 v[48:63], v[156:159], v[68:71], v[48:63]
	s_waitcnt lgkmcnt(0)
	v_mfma_f32_32x32x16_bf16 v[48:63], v[164:167], v[64:67], v[48:63]
	v_add_u32_e32 v154, s9, v116
	v_lshl_add_u32 v168, v112, 1, v121
	v_lshl_add_u32 v169, v111, 1, v121
	v_lshl_add_u32 v170, v110, 1, v154
	v_lshl_add_u32 v171, v109, 1, v154
	v_lshl_add_u32 v172, v108, 1, v121
	v_lshl_add_u32 v173, v107, 1, v121
	v_lshl_add_u32 v174, v106, 1, v154
	v_lshl_add_u32 v175, v105, 1, v154
	v_lshl_add_u32 v176, v104, 1, v121
	v_lshl_add_u32 v177, v103, 1, v154
	v_lshl_add_u32 v178, v102, 1, v154
	v_lshl_add_u32 v179, v100, 1, v121
	v_lshl_add_u32 v180, v101, 1, v121
	v_lshl_add_u32 v181, v99, 1, v154
	v_lshl_add_u32 v160, v98, 1, v154
	v_max_f32_e32 v119, v32, v32
	v_max_f32_e32 v113, v48, v48
	v_max_f32_e32 v113, v119, v113
	v_max3_f32 v113, v113, v33, v49
	v_max3_f32 v113, v113, v34, v50
	v_max3_f32 v113, v113, v35, v51
	v_max3_f32 v113, v113, v36, v52
	v_max3_f32 v113, v113, v37, v53
	v_max3_f32 v113, v113, v38, v54
	v_max3_f32 v113, v113, v39, v55
	v_max3_f32 v113, v113, v40, v56
	v_max3_f32 v113, v113, v41, v57
	v_max3_f32 v113, v113, v42, v58
	v_max3_f32 v113, v113, v43, v59
	v_max3_f32 v113, v113, v44, v60
	v_max3_f32 v113, v113, v45, v61
	v_max3_f32 v113, v113, v46, v62
	v_max3_f32 v113, v113, v47, v63
	ds_bpermute_b32 v119, v91, v113
	s_waitcnt lgkmcnt(0)
	ds_read_b64 v[126:127], v168 offset:9216
	ds_read_b64 v[128:129], v169 offset:9216
	ds_read_b64 v[130:131], v170 offset:9216
	ds_read_b64 v[132:133], v171 offset:9216
	ds_read_b64 v[134:135], v172 offset:9216
	ds_read_b64 v[136:137], v173 offset:9216
	ds_read_b64 v[138:139], v174 offset:9216
	ds_read_b64 v[140:141], v175 offset:9216
	v_max3_f32 v119, v96, v113, v119
	v_sub_f32_e32 v32, v32, v119
	v_sub_f32_e32 v38, v38, v119
	v_exp_f32_e32 v32, v32
	v_sub_f32_e32 v48, v48, v119
	v_sub_f32_e32 v36, v36, v119
	v_exp_f32_e32 v124, v38
	v_sub_f32_e32 v38, v54, v119
	v_exp_f32_e32 v48, v48
	v_sub_f32_e32 v33, v33, v119
	v_exp_f32_e32 v122, v36
	v_sub_f32_e32 v36, v52, v119
	v_exp_f32_e32 v52, v38
	v_sub_f32_e32 v38, v39, v119
	v_exp_f32_e32 v33, v33
	v_sub_f32_e32 v49, v49, v119
	v_sub_f32_e32 v37, v37, v119
	v_exp_f32_e32 v125, v38
	v_sub_f32_e32 v38, v55, v119
	v_exp_f32_e32 v49, v49
	v_sub_f32_e32 v34, v34, v119
	v_exp_f32_e32 v123, v37
	v_sub_f32_e32 v37, v53, v119
	v_exp_f32_e32 v53, v38
	v_sub_f32_e32 v38, v40, v119
	v_sub_f32_e32 v40, v42, v119
	v_sub_f32_e32 v42, v44, v119
	v_exp_f32_e32 v34, v34
	v_sub_f32_e32 v50, v50, v119
	v_exp_f32_e32 v54, v38
	v_sub_f32_e32 v38, v56, v119
	v_exp_f32_e32 v56, v40
	v_sub_f32_e32 v40, v58, v119
	v_exp_f32_e32 v58, v42
	v_sub_f32_e32 v42, v60, v119
	s_waitcnt lgkmcnt(4)
; #define MFMA32(a, b, c) __builtin_amdgcn_mfma_f32_32x32x16_bf16((a), (b), (c), 0, 0, 0)
; DI unsigned pack2(float a, float b) { unsigned r; asm volatile("v_cvt_pk_bf16_f32 %0, %1, %2" : "=v"(r) : "v"(a), "v"(b)); return r; }
; template <int D>
; DI void attn_pass(const bfr* __restrict__ P, int b, int tq_wave, int qcol, int kcol, int vcol, int key0, int nkt, char* smem, f32x16 (&o)[2]) {
;     ...
;   for (int kt = 0; kt < nkt; ++kt) {
;     bfr* sK = sbase + (kt & 1) * 9216;
;     bfr* sV = sK + 64 * 72;
;     { int c = gt, row = c >> 3, kc = c & 7; *(u32x4*)(sK + row * KP + kc * 8) = kreg[0]; }
;     for (int i = 0; i < 1; ++i) {
;       int c = gt, row = c >> 3, kc = c & 7;
;       unsigned wds[4] = {vreg[i].x, vreg[i].y, vreg[i].z, vreg[i].w};
; #pragma unroll
;       for (int e = 0; e < 4; ++e) {
;         sV[(kc * 8 + 2 * e) * 72 + (row ^ (kc << 3))] = (bfr)(wds[e] & 0xffffu);
;         sV[(kc * 8 + 2 * e + 1) * 72 + (row ^ (kc << 3))] = (bfr)(wds[e] >> 16);
;       }
;     }
;     __syncthreads();
;     ...
;     for (int i = 0; i < 16; ++i) {
;       s[0][i] = __builtin_amdgcn_exp2f(s[0][i] - mnew); ps += s[0][i];
;       s[1][i] = __builtin_amdgcn_exp2f(s[1][i] - mnew); ps += s[1][i];
;     }
;     lsum = lsum * alpha + ps;
; #pragma unroll
;     for (int i = 0; i < 16; ++i) { accO[0][i] *= alpha; accO[1][i] *= alpha; }
; #pragma unroll
;     for (int t2 = 0; t2 < 2; ++t2)
; #pragma unroll
;       for (int j = 0; j < 2; ++j) {
;         unsigned pk[4];
; #pragma unroll
;         for (int e = 0; e < 4; ++e) pk[e] = pack2(s[t2][8 * j + 2 * e], s[t2][8 * j + 2 * e + 1]);
;         u32x4 pku = {pk[0], pk[1], pk[2], pk[3]};
;         bf16x8 pf = __builtin_bit_cast(bf16x8, pku);
; #pragma unroll
;         for (int dt = 0; dt < 2; ++dt) {
;           const int vsw = (((dt * 32 + r) >> 3) & 7) << 3;
;           const bfr* vrow = sV + (dt * 32 + r) * 72;
;           s16x4 lo = *(const s16x4*)(vrow + ((t2 * 32 + 16 * j + 4 * h) ^ vsw));
;           s16x4 hi = *(const s16x4*)(vrow + ((t2 * 32 + 16 * j + 4 * h + 8) ^ vsw));
;           bf16x8 vf = __builtin_shufflevector(lo, hi, 0, 1, 2, 3, 4, 5, 6, 7);
;           accO[dt] = MFMA32(vf, pf, accO[dt]);
;         }
;       }
;   }
	ds_read_b64 v[142:143], v168 offset:9280
	ds_read_b64 v[144:145], v176 offset:9216
	ds_read_b64 v[146:147], v177 offset:9216
	ds_read_b64 v[148:149], v178 offset:9216
	ds_read_b64 v[156:157], v179 offset:9216
	ds_read_b64 v[158:159], v180 offset:9216
	ds_read_b64 v[164:165], v181 offset:9216
	ds_read_b64 v[166:167], v160 offset:9216
	v_add_f32_e32 v60, 0, v32
	v_exp_f32_e32 v50, v50
	v_sub_f32_e32 v35, v35, v119
	v_add_f32_e32 v60, v48, v60
	v_exp_f32_e32 v35, v35
	v_sub_f32_e32 v51, v51, v119
	v_add_f32_e32 v60, v33, v60
	v_exp_f32_e32 v51, v51
	v_add_f32_e32 v60, v49, v60
	v_add_f32_e32 v60, v34, v60
	v_exp_f32_e32 v36, v36
	v_add_f32_e32 v60, v50, v60
	v_add_f32_e32 v60, v35, v60
	v_exp_f32_e32 v37, v37
	v_add_f32_e32 v60, v51, v60
	v_add_f32_e32 v60, v122, v60
	v_add_f32_e32 v60, v36, v60
	v_add_f32_e32 v60, v123, v60
	v_add_f32_e32 v60, v37, v60
	v_add_f32_e32 v60, v124, v60
	v_exp_f32_e32 v38, v38
	v_sub_f32_e32 v39, v41, v119
	v_add_f32_e32 v60, v52, v60
	v_exp_f32_e32 v55, v39
	v_sub_f32_e32 v39, v57, v119
	v_add_f32_e32 v60, v125, v60
	v_exp_f32_e32 v39, v39
	v_add_f32_e32 v60, v53, v60
	v_add_f32_e32 v60, v54, v60
	v_exp_f32_e32 v40, v40
	v_sub_f32_e32 v41, v43, v119
	v_add_f32_e32 v60, v38, v60
	v_exp_f32_e32 v57, v41
	v_sub_f32_e32 v41, v59, v119
	v_add_f32_e32 v60, v55, v60
	v_exp_f32_e32 v41, v41
	v_add_f32_e32 v60, v39, v60
	v_add_f32_e32 v60, v56, v60
	v_exp_f32_e32 v42, v42
	v_sub_f32_e32 v43, v45, v119
	v_add_f32_e32 v60, v40, v60
	v_exp_f32_e32 v59, v43
	v_sub_f32_e32 v43, v61, v119
	v_add_f32_e32 v60, v57, v60
	v_exp_f32_e32 v43, v43
	v_sub_f32_e32 v44, v46, v119
	v_add_f32_e32 v60, v41, v60
	v_exp_f32_e32 v46, v44
	v_sub_f32_e32 v44, v62, v119
	v_add_f32_e32 v60, v58, v60
	v_exp_f32_e32 v44, v44
	v_sub_f32_e32 v45, v47, v119
	v_add_f32_e32 v60, v42, v60
	v_exp_f32_e32 v47, v45
	v_sub_f32_e32 v45, v63, v119
	v_add_f32_e32 v60, v59, v60
	v_exp_f32_e32 v45, v45
	v_add_f32_e32 v60, v43, v60
	v_add_f32_e32 v60, v46, v60
	v_add_f32_e32 v60, v44, v60
	v_add_f32_e32 v60, v47, v60
	v_add_f32_e32 v113, v45, v60
	v_cvt_pk_bf16_f32 v32, v32, v33
	v_cvt_pk_bf16_f32 v33, v34, v35
	v_cvt_pk_bf16_f32 v34, v122, v123
	v_cvt_pk_bf16_f32 v35, v124, v125
	v_sub_f32_e32 v96, v96, v119
	v_exp_f32_e32 v96, v96
	s_nop 1
	v_mul_f32_e32 v30, v30, v96
	v_mul_f32_e32 v31, v31, v96
	v_mul_f32_e32 v28, v28, v96
	v_mul_f32_e32 v29, v29, v96
	v_mul_f32_e32 v26, v26, v96
	v_mul_f32_e32 v27, v27, v96
	v_mul_f32_e32 v24, v24, v96
	v_mul_f32_e32 v25, v25, v96
	v_mul_f32_e32 v22, v22, v96
	v_mul_f32_e32 v23, v23, v96
	v_mul_f32_e32 v20, v20, v96
	v_mul_f32_e32 v21, v21, v96
	v_mul_f32_e32 v18, v18, v96
	v_mul_f32_e32 v19, v19, v96
	v_mul_f32_e32 v16, v16, v96
	v_mul_f32_e32 v17, v17, v96
	v_mul_f32_e32 v14, v14, v96
	v_mul_f32_e32 v15, v15, v96
	v_mul_f32_e32 v12, v12, v96
	v_mul_f32_e32 v13, v13, v96
	s_waitcnt lgkmcnt(0)
	v_mfma_f32_32x32x16_bf16 v[16:31], v[126:129], v[32:35], v[16:31]
	v_mul_f32_e64 v10, v10, v96
	v_mul_f32_e64 v11, v11, v96
	v_mul_f32_e32 v8, v8, v96
	v_mul_f32_e32 v9, v9, v96
	v_mul_f32_e32 v6, v6, v96
	v_mul_f32_e32 v7, v7, v96
	v_mul_f32_e32 v4, v4, v96
	v_mul_f32_e32 v5, v5, v96
	v_mul_f32_e32 v2, v2, v96
	v_mul_f32_e32 v3, v3, v96
	v_mul_f32_e32 v0, v0, v96
	v_mul_f32_e32 v1, v1, v96
	v_fmac_f32_e32 v113, v120, v96
	s_nop 1
	v_mfma_f32_32x32x16_bf16 v[0:15], v[130:133], v[32:35], v[0:15]
	v_cvt_pk_bf16_f32 v32, v54, v55
	v_cvt_pk_bf16_f32 v33, v56, v57
	v_cvt_pk_bf16_f32 v34, v58, v59
	v_cvt_pk_bf16_f32 v35, v46, v47
	s_nop 1
	v_mfma_f32_32x32x16_bf16 v[16:31], v[134:137], v[32:35], v[16:31]
	s_nop 1
	v_mfma_f32_32x32x16_bf16 v[0:15], v[138:141], v[32:35], v[0:15]
	v_cvt_pk_bf16_f32 v32, v48, v49
	v_cvt_pk_bf16_f32 v33, v50, v51
	v_cvt_pk_bf16_f32 v34, v36, v37
	v_cvt_pk_bf16_f32 v35, v52, v53
	s_nop 1
	v_mfma_f32_32x32x16_bf16 v[16:31], v[142:145], v[32:35], v[16:31]
	s_nop 1
	v_mfma_f32_32x32x16_bf16 v[0:15], v[146:149], v[32:35], v[0:15]
	v_cvt_pk_bf16_f32 v32, v38, v39
	v_cvt_pk_bf16_f32 v33, v40, v41
	v_cvt_pk_bf16_f32 v34, v42, v43
	v_cvt_pk_bf16_f32 v35, v44, v45
	s_nop 1
	v_mfma_f32_32x32x16_bf16 v[16:31], v[156:159], v[32:35], v[16:31]
	s_nop 1
	v_mfma_f32_32x32x16_bf16 v[0:15], v[164:167], v[32:35], v[0:15]
	s_cbranch_scc1 .LBB0_412
	v_add3_u32 v32, 0, v115, v90
	s_waitcnt vmcnt(1)
	ds_write_b128 v32, v[84:87] offset:18432
	v_add3_u32 v32, 0, v117, v118
	v_add3_u32 v33, 0, v118, v117
	s_waitcnt vmcnt(0)
	ds_write_b16 v32, v80 offset:27648
	ds_write_b16_d16_hi v33, v80 offset:27792
	ds_write_b16 v32, v81 offset:27936
	ds_write_b16_d16_hi v33, v81 offset:28080
	ds_write_b16 v32, v82 offset:28224
	ds_write_b16_d16_hi v33, v82 offset:28368
	ds_write_b16 v32, v83 offset:28512
	ds_write_b16_d16_hi v33, v83 offset:28656
	v_add_u32_e32 v80, 0, v114
	v_add_u32_e32 v81, v80, v152
	s_waitcnt lgkmcnt(0)
	s_barrier
; #define MFMA32(a, b, c) __builtin_amdgcn_mfma_f32_32x32x16_bf16((a), (b), (c), 0, 0, 0)
; template <int D>
; DI void attn_pass(const bfr* __restrict__ P, int b, int tq_wave, int qcol, int kcol, int vcol, int key0, int nkt, char* smem, f32x16 (&o)[2]) {
;     ...
;     f32x16 s[2];
; #pragma unroll
;     for (int t2 = 0; t2 < 2; ++t2) {
; #pragma unroll
;       for (int i = 0; i < 16; ++i) s[t2][i] = 0.f;
; #pragma unroll
;       for (int ks = 0; ks < KS; ++ks) {
;         bf16x8 a = *(const bf16x8*)(sK + (t2 * 32 + r) * KP + ks * 16 + h * 8);
;         s[t2] = MFMA32(a, qf[ks], s[t2]);
;       }
;     }
;     float mx = s[0][0];
; #pragma unroll
;     for (int i = 0; i < 16; ++i) { mx = fmaxf(mx, s[0][i]); mx = fmaxf(mx, s[1][i]); }
;     mx = fmaxf(mx, __shfl_xor(mx, 32));
;     float mnew = fmaxf(mrun, mx);
;     float alpha = __builtin_amdgcn_exp2f(mrun - mnew);
;     mrun = mnew;
;     float ps = 0.f;
; #pragma unroll
;     for (int i = 0; i < 16; ++i) {
;       s[0][i] = __builtin_amdgcn_exp2f(s[0][i] - mnew); ps += s[0][i];
;       s[1][i] = __builtin_amdgcn_exp2f(s[1][i] - mnew); ps += s[1][i];
;     }
;     lsum = lsum * alpha + ps;
; #pragma unroll
;     for (int i = 0; i < 16; ++i) { accO[0][i] *= alpha; accO[1][i] *= alpha; }
	ds_read_b128 v[32:35], v81 offset:18432
	ds_read_b128 v[48:51], v81 offset:18464
	s_waitcnt lgkmcnt(1)
	v_mfma_f32_32x32x16_bf16 v[32:47], v[32:35], v[76:79], 0
	v_lshlrev_b32_e32 v152, 1, v88
	s_waitcnt lgkmcnt(0)
	v_mfma_f32_32x32x16_bf16 v[32:47], v[48:51], v[72:75], v[32:47]
	ds_read_b128 v[48:51], v81 offset:18496
	s_waitcnt lgkmcnt(0)
	v_mfma_f32_32x32x16_bf16 v[32:47], v[48:51], v[68:71], v[32:47]
	ds_read_b128 v[48:51], v81 offset:18528
	s_waitcnt lgkmcnt(0)
	v_mfma_f32_32x32x16_bf16 v[32:47], v[48:51], v[64:67], v[32:47]
	ds_read_b128 v[48:51], v81 offset:23040
	s_waitcnt lgkmcnt(0)
	v_mfma_f32_32x32x16_bf16 v[48:63], v[48:51], v[76:79], 0
	ds_read_b128 v[76:79], v81 offset:23072
	s_waitcnt lgkmcnt(0)
	v_mfma_f32_32x32x16_bf16 v[48:63], v[76:79], v[72:75], v[48:63]
	ds_read_b128 v[72:75], v81 offset:23104
	s_waitcnt lgkmcnt(0)
	v_mfma_f32_32x32x16_bf16 v[48:63], v[72:75], v[68:71], v[48:63]
	ds_read_b128 v[68:71], v81 offset:23136
	s_waitcnt lgkmcnt(0)
	v_mfma_f32_32x32x16_bf16 v[48:63], v[68:71], v[64:67], v[48:63]
	v_max_f32_e32 v65, v32, v32
	v_lshl_add_u32 v66, v112, 1, v80
	v_add_u32_e32 v67, 0x1200, v80
	s_nop 8
	v_max_f32_e32 v64, v48, v48
	v_max_f32_e32 v64, v65, v64
	v_max3_f32 v64, v64, v33, v49
	v_max3_f32 v64, v64, v34, v50
	v_max3_f32 v64, v64, v35, v51
	v_max3_f32 v64, v64, v36, v52
	v_max3_f32 v64, v64, v37, v53
	v_max3_f32 v64, v64, v38, v54
	v_max3_f32 v64, v64, v39, v55
	v_max3_f32 v64, v64, v40, v56
	v_max3_f32 v64, v64, v41, v57
	v_max3_f32 v64, v64, v42, v58
	v_max3_f32 v64, v64, v43, v59
	v_max3_f32 v64, v64, v44, v60
	v_max3_f32 v64, v64, v45, v61
	v_max3_f32 v64, v64, v46, v62
	v_max3_f32 v64, v64, v47, v63
	ds_bpermute_b32 v65, v91, v64
	s_waitcnt lgkmcnt(0)
	v_max3_f32 v65, v119, v64, v65
	v_sub_f32_e32 v64, v119, v65
	v_sub_f32_e32 v32, v32, v65
	v_exp_f32_e32 v64, v64
	v_exp_f32_e32 v32, v32
	v_sub_f32_e32 v48, v48, v65
	v_exp_f32_e32 v48, v48
	v_sub_f32_e32 v33, v33, v65
	v_exp_f32_e32 v33, v33
	v_sub_f32_e32 v49, v49, v65
	v_exp_f32_e32 v49, v49
	v_sub_f32_e32 v34, v34, v65
	v_exp_f32_e32 v34, v34
	v_sub_f32_e32 v50, v50, v65
	v_sub_f32_e32 v35, v35, v65
	v_sub_f32_e32 v51, v51, v65
	v_sub_f32_e32 v36, v36, v65
	v_sub_f32_e32 v52, v52, v65
	v_sub_f32_e32 v37, v37, v65
	v_sub_f32_e32 v53, v53, v65
	v_sub_f32_e32 v38, v38, v65
	v_sub_f32_e32 v54, v54, v65
	v_sub_f32_e32 v39, v39, v65
	v_sub_f32_e32 v55, v55, v65
	v_sub_f32_e32 v40, v40, v65
	v_sub_f32_e32 v56, v56, v65
	v_sub_f32_e32 v41, v41, v65
	v_sub_f32_e32 v57, v57, v65
	v_sub_f32_e32 v42, v42, v65
	v_sub_f32_e32 v58, v58, v65
	v_sub_f32_e32 v43, v43, v65
	v_sub_f32_e32 v59, v59, v65
	v_sub_f32_e32 v44, v44, v65
	v_sub_f32_e32 v60, v60, v65
	v_sub_f32_e32 v45, v45, v65
	v_sub_f32_e32 v61, v61, v65
	v_sub_f32_e32 v46, v46, v65
	v_sub_f32_e32 v62, v62, v65
	v_sub_f32_e32 v47, v47, v65
	v_sub_f32_e32 v63, v63, v65
	v_pk_mul_f32 v[30:31], v[30:31], v[64:65] op_sel_hi:[1,0]
	v_pk_mul_f32 v[28:29], v[28:29], v[64:65] op_sel_hi:[1,0]
	v_pk_mul_f32 v[26:27], v[26:27], v[64:65] op_sel_hi:[1,0]
	v_pk_mul_f32 v[24:25], v[24:25], v[64:65] op_sel_hi:[1,0]
	v_pk_mul_f32 v[22:23], v[22:23], v[64:65] op_sel_hi:[1,0]
	v_pk_mul_f32 v[20:21], v[20:21], v[64:65] op_sel_hi:[1,0]
	v_pk_mul_f32 v[18:19], v[18:19], v[64:65] op_sel_hi:[1,0]
	v_pk_mul_f32 v[16:17], v[16:17], v[64:65] op_sel_hi:[1,0]
	v_pk_mul_f32 v[14:15], v[14:15], v[64:65] op_sel_hi:[1,0]
	v_pk_mul_f32 v[12:13], v[12:13], v[64:65] op_sel_hi:[1,0]
	v_pk_mul_f32 v[10:11], v[10:11], v[64:65] op_sel_hi:[1,0]
	v_pk_mul_f32 v[8:9], v[8:9], v[64:65] op_sel_hi:[1,0]
	v_pk_mul_f32 v[6:7], v[6:7], v[64:65] op_sel_hi:[1,0]
	v_pk_mul_f32 v[4:5], v[4:5], v[64:65] op_sel_hi:[1,0]
	v_pk_mul_f32 v[2:3], v[2:3], v[64:65] op_sel_hi:[1,0]
	v_pk_mul_f32 v[0:1], v[0:1], v[64:65] op_sel_hi:[1,0]
	v_add_f32_e32 v65, 0, v32
	v_exp_f32_e32 v50, v50
	v_add_f32_e32 v65, v48, v65
	v_exp_f32_e32 v35, v35
	v_add_f32_e32 v65, v33, v65
	v_exp_f32_e32 v51, v51
	v_add_f32_e32 v65, v49, v65
	v_exp_f32_e32 v36, v36
	v_add_f32_e32 v65, v34, v65
	v_exp_f32_e32 v52, v52
	v_add_f32_e32 v65, v50, v65
	v_exp_f32_e32 v37, v37
	v_add_f32_e32 v65, v35, v65
	v_exp_f32_e32 v53, v53
	v_add_f32_e32 v65, v51, v65
	v_exp_f32_e32 v38, v38
	v_add_f32_e32 v65, v36, v65
	v_exp_f32_e32 v54, v54
	v_add_f32_e32 v65, v52, v65
	v_exp_f32_e32 v39, v39
	v_add_f32_e32 v65, v37, v65
	v_add_f32_e32 v65, v53, v65
	v_add_f32_e32 v65, v38, v65
	v_add_f32_e32 v65, v54, v65
	v_cvt_pk_bf16_f32 v32, v32, v33
	v_cvt_pk_bf16_f32 v33, v34, v35
	v_cvt_pk_bf16_f32 v34, v36, v37
	v_cvt_pk_bf16_f32 v35, v38, v39
	v_lshl_add_u32 v38, v111, 1, v80
	v_add_f32_e32 v65, v39, v65
	ds_read_b64 v[36:37], v66 offset:27648
	ds_read_b64 v[38:39], v38 offset:27648
	s_waitcnt lgkmcnt(0)
	v_mfma_f32_32x32x16_bf16 v[16:31], v[36:39], v[32:35], v[16:31]
	v_lshl_add_u32 v36, v110, 1, v67
	v_lshl_add_u32 v38, v109, 1, v67
	ds_read_b64 v[36:37], v36 offset:27648
	ds_read_b64 v[38:39], v38 offset:27648
	v_exp_f32_e32 v40, v40
	v_exp_f32_e32 v41, v41
	v_exp_f32_e32 v42, v42
	s_waitcnt lgkmcnt(0)
; #define MFMA32(a, b, c) __builtin_amdgcn_mfma_f32_32x32x16_bf16((a), (b), (c), 0, 0, 0)
; DI unsigned pack2(float a, float b) { unsigned r; asm volatile("v_cvt_pk_bf16_f32 %0, %1, %2" : "=v"(r) : "v"(a), "v"(b)); return r; }
; template <int D>
; DI void attn_pass(const bfr* __restrict__ P, int b, int tq_wave, int qcol, int kcol, int vcol, int key0, int nkt, char* smem, f32x16 (&o)[2]) {
;     ...
; #pragma unroll
;     for (int t2 = 0; t2 < 2; ++t2)
; #pragma unroll
;       for (int j = 0; j < 2; ++j) {
;         unsigned pk[4];
; #pragma unroll
;         for (int e = 0; e < 4; ++e) pk[e] = pack2(s[t2][8 * j + 2 * e], s[t2][8 * j + 2 * e + 1]);
;         u32x4 pku = {pk[0], pk[1], pk[2], pk[3]};
;         bf16x8 pf = __builtin_bit_cast(bf16x8, pku);
; #pragma unroll
;         for (int dt = 0; dt < 2; ++dt) {
;           const int vsw = (((dt * 32 + r) >> 3) & 7) << 3;
;           const bfr* vrow = sV + (dt * 32 + r) * 72;
;           s16x4 lo = *(const s16x4*)(vrow + ((t2 * 32 + 16 * j + 4 * h) ^ vsw));
;           s16x4 hi = *(const s16x4*)(vrow + ((t2 * 32 + 16 * j + 4 * h + 8) ^ vsw));
;           bf16x8 vf = __builtin_shufflevector(lo, hi, 0, 1, 2, 3, 4, 5, 6, 7);
;           accO[dt] = MFMA32(vf, pf, accO[dt]);
;         }
;       }
;   }
;   lsum += __shfl_xor(lsum, 32);
;   float inv = 1.f / lsum;
; #pragma unroll
;   for (int i = 0; i < 16; ++i) { o[0][i] = accO[0][i] * inv; o[1][i] = accO[1][i] * inv; }
; DI void store_o(bfr* O, int m, int colbase, int h, const f32x16 (&o)[2]) {
; #pragma unroll
;   for (int dt = 0; dt < 2; ++dt)
; #pragma unroll
;     for (int g4 = 0; g4 < 4; ++g4) {
;       int dv = dt * 32 + 8 * g4 + 4 * h;
;       uint2 pk; pk.x = pack2(o[dt][4 * g4], o[dt][4 * g4 + 1]); pk.y = pack2(o[dt][4 * g4 + 2], o[dt][4 * g4 + 3]);
;       *(uint2*)(O + (size_t)m * DM + colbase + dv) = pk;
;     }
	v_mfma_f32_32x32x16_bf16 v[0:15], v[36:39], v[32:35], v[0:15]
	v_lshl_add_u32 v36, v108, 1, v80
	v_lshl_add_u32 v38, v107, 1, v80
	v_exp_f32_e32 v43, v43
	v_exp_f32_e32 v44, v44
	v_exp_f32_e32 v45, v45
	v_exp_f32_e32 v46, v46
	v_exp_f32_e32 v47, v47
	v_cvt_pk_bf16_f32 v32, v40, v41
	v_cvt_pk_bf16_f32 v33, v42, v43
	v_cvt_pk_bf16_f32 v34, v44, v45
	v_cvt_pk_bf16_f32 v35, v46, v47
	ds_read_b64 v[36:37], v36 offset:27648
	ds_read_b64 v[38:39], v38 offset:27648
	s_waitcnt lgkmcnt(0)
	v_mfma_f32_32x32x16_bf16 v[16:31], v[36:39], v[32:35], v[16:31]
	v_lshl_add_u32 v36, v106, 1, v67
	v_lshl_add_u32 v38, v105, 1, v67
	ds_read_b64 v[36:37], v36 offset:27648
	ds_read_b64 v[38:39], v38 offset:27648
	v_exp_f32_e32 v55, v55
	v_exp_f32_e32 v56, v56
	v_exp_f32_e32 v57, v57
	s_waitcnt lgkmcnt(0)
	v_mfma_f32_32x32x16_bf16 v[0:15], v[36:39], v[32:35], v[0:15]
	v_lshl_add_u32 v38, v104, 1, v80
	v_cvt_pk_bf16_f32 v32, v48, v49
	v_cvt_pk_bf16_f32 v33, v50, v51
	v_cvt_pk_bf16_f32 v34, v52, v53
	v_cvt_pk_bf16_f32 v35, v54, v55
	ds_read_b64 v[36:37], v66 offset:27712
	ds_read_b64 v[38:39], v38 offset:27648
	s_waitcnt lgkmcnt(0)
	v_mfma_f32_32x32x16_bf16 v[16:31], v[36:39], v[32:35], v[16:31]
	v_lshl_add_u32 v36, v103, 1, v67
	v_lshl_add_u32 v38, v102, 1, v67
	ds_read_b64 v[36:37], v36 offset:27648
	ds_read_b64 v[38:39], v38 offset:27648
	v_exp_f32_e32 v58, v58
	v_exp_f32_e32 v59, v59
	v_exp_f32_e32 v60, v60
	s_waitcnt lgkmcnt(0)
	v_mfma_f32_32x32x16_bf16 v[0:15], v[36:39], v[32:35], v[0:15]
	v_lshl_add_u32 v36, v100, 1, v80
	v_lshl_add_u32 v38, v101, 1, v80
	v_exp_f32_e32 v61, v61
	v_exp_f32_e32 v62, v62
	v_exp_f32_e32 v63, v63
	v_cvt_pk_bf16_f32 v32, v56, v57
	v_cvt_pk_bf16_f32 v33, v58, v59
	v_cvt_pk_bf16_f32 v34, v60, v61
	v_cvt_pk_bf16_f32 v35, v62, v63
	ds_read_b64 v[36:37], v36 offset:27648
	ds_read_b64 v[38:39], v38 offset:27648
	v_add_f32_e32 v65, v55, v65
	v_add_f32_e32 v65, v40, v65
	v_add_f32_e32 v65, v56, v65
	v_add_f32_e32 v65, v41, v65
	v_add_f32_e32 v65, v57, v65
	v_add_f32_e32 v65, v42, v65
	v_add_f32_e32 v65, v58, v65
	v_add_f32_e32 v65, v43, v65
	v_add_f32_e32 v65, v59, v65
	s_waitcnt lgkmcnt(0)
	v_mfma_f32_32x32x16_bf16 v[16:31], v[36:39], v[32:35], v[16:31]
	v_lshl_add_u32 v36, v99, 1, v67
	v_lshl_add_u32 v38, v98, 1, v67
	v_add_f32_e32 v65, v44, v65
	ds_read_b64 v[36:37], v36 offset:27648
	ds_read_b64 v[38:39], v38 offset:27648
	v_add_f32_e32 v65, v60, v65
	v_add_f32_e32 v65, v45, v65
	v_add_f32_e32 v65, v61, v65
	v_add_f32_e32 v65, v46, v65
	v_add_f32_e32 v65, v62, v65
	v_add_f32_e32 v65, v47, v65
	v_add_f32_e32 v65, v63, v65
	v_fmac_f32_e32 v65, v113, v64
	s_waitcnt lgkmcnt(0)
	v_mfma_f32_32x32x16_bf16 v[0:15], v[36:39], v[32:35], v[0:15]
	ds_bpermute_b32 v32, v91, v65
	s_waitcnt lgkmcnt(0)
	v_add_f32_e32 v32, v65, v32
	v_div_scale_f32 v33, s[8:9], v32, v32, 1.0
	v_rcp_f32_e32 v34, v33
	s_load_dwordx4 s[8:11], s[0:1], 0x100
	s_waitcnt lgkmcnt(0)
	s_mov_b64 s[8:9], 0x2b7c700
	v_fma_f32 v35, -v33, v34, 1.0
	v_fmac_f32_e32 v34, v35, v34
	v_div_scale_f32 v35, vcc, 1.0, v32, 1.0
	v_mul_f32_e32 v36, v35, v34
	v_fma_f32 v37, -v33, v36, v35
	v_fmac_f32_e32 v36, v37, v34
	v_fma_f32 v33, -v33, v36, v35
	v_div_fmas_f32 v33, v33, v34, v36
	v_div_fixup_f32 v32, v33, v32, 1.0
	v_mul_f32_e32 v33, v0, v32
	v_and_or_b32 v0, v89, 31, v97
	v_mul_f32_e32 v34, v1, v32
	v_ashrrev_i32_e32 v1, 31, v0
	v_lshlrev_b64 v[0:1], 11, v[0:1]
	v_mul_f32_e32 v37, v4, v32
	v_lshl_add_u64 v[0:1], s[10:11], 0, v[0:1]
	v_lshrrev_b32_e32 v4, 2, v89
	v_lshl_add_u64 v[0:1], v[0:1], 0, v[152:153]
	v_and_b32_e32 v152, 8, v4
	v_lshl_add_u64 v[0:1], v[0:1], 0, v[152:153]
	v_mul_f32_e32 v38, v5, v32
	v_lshl_add_u64 v[4:5], v[0:1], 0, s[8:9]
	s_mov_b32 s8, 0x2b7c000
	v_add_co_u32_e32 v0, vcc, s8, v0
	v_mul_f32_e32 v16, v16, v32
	s_nop 0
	v_addc_co_u32_e32 v1, vcc, 0, v1, vcc
	v_mul_f32_e32 v17, v17, v32
	v_mul_f32_e32 v18, v18, v32
	v_mul_f32_e32 v35, v2, v32
	v_mul_f32_e32 v19, v19, v32
	v_mul_f32_e32 v36, v3, v32
	v_mul_f32_e32 v20, v20, v32
	v_mul_f32_e32 v21, v21, v32
	v_mul_f32_e32 v22, v22, v32
	v_mul_f32_e32 v23, v23, v32
	v_cvt_pk_bf16_f32 v2, v16, v17
	v_cvt_pk_bf16_f32 v3, v18, v19
	global_store_dwordx2 v[0:1], v[2:3], off offset:1792
	v_cvt_pk_bf16_f32 v0, v20, v21
	v_cvt_pk_bf16_f32 v1, v22, v23
	v_mul_f32_e32 v24, v24, v32
	v_mul_f32_e32 v25, v25, v32
	v_mul_f32_e32 v26, v26, v32
	v_mul_f32_e32 v27, v27, v32
	global_store_dwordx2 v[4:5], v[0:1], off offset:16
	v_cvt_pk_bf16_f32 v0, v24, v25
	v_cvt_pk_bf16_f32 v1, v26, v27
	v_mul_f32_e32 v28, v28, v32
	v_mul_f32_e32 v29, v29, v32
	v_mul_f32_e32 v30, v30, v32
	v_mul_f32_e32 v31, v31, v32
	global_store_dwordx2 v[4:5], v[0:1], off offset:32
	v_cvt_pk_bf16_f32 v0, v28, v29
	v_cvt_pk_bf16_f32 v1, v30, v31
	global_store_dwordx2 v[4:5], v[0:1], off offset:48
	v_cvt_pk_bf16_f32 v0, v33, v34
	v_cvt_pk_bf16_f32 v1, v35, v36
	v_mul_f32_e32 v6, v6, v32
	v_mul_f32_e32 v7, v7, v32
	global_store_dwordx2 v[4:5], v[0:1], off offset:64
	v_cvt_pk_bf16_f32 v0, v37, v38
	v_cvt_pk_bf16_f32 v1, v6, v7
	v_mul_f32_e32 v8, v8, v32
	v_mul_f32_e32 v9, v9, v32
	v_mul_f32_e32 v10, v10, v32
	v_mul_f32_e32 v11, v11, v32
	global_store_dwordx2 v[4:5], v[0:1], off offset:80
	v_cvt_pk_bf16_f32 v0, v8, v9
	v_cvt_pk_bf16_f32 v1, v10, v11
	v_mul_f32_e32 v12, v12, v32
	v_mul_f32_e32 v13, v13, v32
	v_mul_f32_e32 v14, v14, v32
	v_mul_f32_e32 v15, v15, v32
	global_store_dwordx2 v[4:5], v[0:1], off offset:96
	v_cvt_pk_bf16_f32 v0, v12, v13
	v_cvt_pk_bf16_f32 v1, v14, v15
	global_store_dwordx2 v[4:5], v[0:1], off offset:112

; DI void attn_pass_da(const bfr* __restrict__ P, int b, int tq_wave, int qcol, int kcol, int vcol, int key0, int nkt, char* smem, f32x16 (&o0)[2], f32x16 (&o1)[2]) {
;     ...
;   for (int kt = 0; kt < nkt; ++kt) {
;     bfr* sK = sbase + (kt & 1) * 9216;
;     bfr* sV = sK + 64 * 72;
;     { int c = gt, row = c >> 3, kc = c & 7; *(u32x4*)(sK + row * KP + kc * 8) = kreg[0]; }
;     for (int i = 0; i < 1; ++i) {
;       int c = gt, row = c >> 3, kc = c & 7;
;       unsigned wds[4] = {vreg[i].x, vreg[i].y, vreg[i].z, vreg[i].w};
; #pragma unroll
;       for (int e = 0; e < 4; ++e) {
;         sV[(kc * 8 + 2 * e) * 72 + (row ^ (kc << 3))] = (bfr)(wds[e] & 0xffffu);
;         sV[(kc * 8 + 2 * e + 1) * 72 + (row ^ (kc << 3))] = (bfr)(wds[e] >> 16);
;       }
;     }
;     __syncthreads();
;     if (kt + 1 < nkt) {
;       const bfr* Pn = Pb + (size_t)(kt + 1) * 64 * PW;
;       { int c = gt, row = c >> 3, kc = c & 7; kreg[0] = *(const u32x4*)(Pn + (size_t)row * PW + kcol + kc * 8); vreg[0] = *(const u32x4*)(Pn + (size_t)row * PW + vcol + kc * 8); }
;     }
;     f32x16 s0[2], s1[2];
; #pragma unroll
;     for (int t2 = 0; t2 < 2; ++t2) {
; #pragma unroll
;       for (int i = 0; i < 16; ++i) { s0[t2][i] = 0.f; s1[t2][i] = 0.f; }
; #pragma unroll
;       for (int ks = 0; ks < 2; ++ks) {
;         bf16x8 a0 = *(const bf16x8*)(sK + (t2 * 32 + r) * KP + ks * 16 + h * 8);
;         bf16x8 a1 = *(const bf16x8*)(sK + (t2 * 32 + r) * KP + 32 + ks * 16 + h * 8);
;         s0[t2] = MFMA32(a0, qf[ks], s0[t2]);
;         s1[t2] = MFMA32(a1, qf[2 + ks], s1[t2]);
;       }
;     }
;     float mx0 = s0[0][0], mx1 = s1[0][0];
; #pragma unroll
;     for (int i = 0; i < 16; ++i) { mx0 = fmaxf(mx0, fmaxf(s0[0][i], s0[1][i])); mx1 = fmaxf(mx1, fmaxf(s1[0][i], s1[1][i])); }
;     mx0 = fmaxf(mx0, __shfl_xor(mx0, 32)); mx1 = fmaxf(mx1, __shfl_xor(mx1, 32));
;     const float mn0 = fmaxf(m0, mx0), mn1 = fmaxf(m1, mx1);
;     const float al0 = __builtin_amdgcn_exp2f(m0 - mn0), al1 = __builtin_amdgcn_exp2f(m1 - mn1);
;     m0 = mn0; m1 = mn1;
;     float ps0 = 0.f, ps1 = 0.f;
; #pragma unroll
;     for (int i = 0; i < 16; ++i) {
;       s0[0][i] = __builtin_amdgcn_exp2f(s0[0][i] - mn0); ps0 += s0[0][i];
;       s0[1][i] = __builtin_amdgcn_exp2f(s0[1][i] - mn0); ps0 += s0[1][i];
;       s1[0][i] = __builtin_amdgcn_exp2f(s1[0][i] - mn1); ps1 += s1[0][i];
.LBB0_421:
	s_bitcmp1_b32 s10, 0
	s_cselect_b32 s11, 0x4800, 0
	s_add_i32 s11, s11, 0
	v_add3_u32 v64, s11, v206, v152
	v_add_u32_e32 v194, s11, v205
	s_waitcnt vmcnt(1)
	ds_write_b128 v64, v[148:151]
	v_add3_u32 v64, s11, v207, v208
	v_add3_u32 v65, s11, v208, v207
	v_add_u32_e32 v100, v194, v204
	s_waitcnt vmcnt(0)
	ds_write_b16 v64, v144 offset:9216
	ds_write_b16_d16_hi v65, v144 offset:9360
	ds_write_b16 v64, v145 offset:9504
	ds_write_b16_d16_hi v65, v145 offset:9648
	ds_write_b16 v64, v146 offset:9792
	ds_write_b16_d16_hi v65, v146 offset:9936
	ds_write_b16 v64, v147 offset:10080
	ds_write_b16_d16_hi v65, v147 offset:10224
	s_waitcnt lgkmcnt(0)
	s_barrier
	global_load_dwordx4 v[148:151], v[158:159], off
	global_load_dwordx4 v[144:147], v[158:159], off offset:512
	ds_read_b128 v[64:67], v100 offset:64
	ds_read_b128 v[68:71], v100
	ds_read_b128 v[96:99], v100 offset:32
	ds_read_b128 v[100:103], v100 offset:96
	s_waitcnt lgkmcnt(2)
	v_mfma_f32_32x32x16_bf16 v[80:95], v[68:71], v[140:143], 0
	v_add_u32_e32 v195, s11, v211
	v_add_u32_e32 v192, v195, v204
	v_mov_b32_e32 v160, v209
	v_mov_b32_e32 v161, v210
	s_add_i32 s10, s10, 1
	v_lshl_add_u64 v[158:159], v[158:159], 0, s[12:13]
	s_cmp_lg_u32 s10, 35
	v_mfma_f32_32x32x16_bf16 v[64:79], v[64:67], v[136:139], 0
	s_waitcnt lgkmcnt(1)
	v_mfma_f32_32x32x16_bf16 v[80:95], v[96:99], v[132:135], v[80:95]
	s_waitcnt lgkmcnt(0)
	v_mfma_f32_32x32x16_bf16 v[64:79], v[100:103], v[128:131], v[64:79]
	ds_read_b128 v[96:99], v192 offset:64
	ds_read_b128 v[100:103], v192
	ds_read_b128 v[212:215], v192 offset:32
	ds_read_b128 v[216:219], v192 offset:96
	s_nop 5
	v_max3_f32 v209, v80, v81, v82
	v_max3_f32 v209, v209, v83, v84
	v_max3_f32 v193, v64, v65, v66
	s_waitcnt lgkmcnt(2)
	v_mfma_f32_32x32x16_bf16 v[112:127], v[100:103], v[140:143], 0
	v_mfma_f32_32x32x16_bf16 v[96:111], v[96:99], v[136:139], 0
	s_waitcnt lgkmcnt(1)
	v_mfma_f32_32x32x16_bf16 v[112:127], v[212:215], v[132:135], v[112:127]
	v_max3_f32 v193, v193, v67, v68
	v_max3_f32 v209, v209, v85, v86
	s_waitcnt lgkmcnt(0)
	v_mfma_f32_32x32x16_bf16 v[96:111], v[216:219], v[128:131], v[96:111]
	v_max3_f32 v193, v193, v69, v70
	v_max3_f32 v209, v209, v87, v88
	v_max3_f32 v193, v193, v71, v72
	v_max3_f32 v209, v209, v89, v90
	v_max3_f32 v193, v193, v73, v74
	v_max3_f32 v209, v209, v91, v92
	v_max3_f32 v193, v193, v75, v76
	v_max3_f32 v209, v209, v93, v94
	v_max3_f32 v193, v193, v77, v78
	v_max3_f32 v209, v209, v95, v112
	v_max3_f32 v209, v209, v113, v114
	v_max3_f32 v209, v209, v115, v116
	v_max3_f32 v209, v209, v117, v118
	v_max3_f32 v209, v209, v119, v120
	v_max3_f32 v209, v209, v121, v122
	v_max3_f32 v209, v209, v123, v124
	v_max3_f32 v209, v209, v125, v126
	v_max_f32_e32 v192, v209, v127
	v_max3_f32 v193, v193, v79, v96
	v_max3_f32 v193, v193, v97, v98
	v_max3_f32 v193, v193, v99, v100
	v_max3_f32 v193, v193, v101, v102
	v_max3_f32 v193, v193, v103, v104
	v_max3_f32 v193, v193, v105, v106
	v_max3_f32 v193, v193, v107, v108
	v_max3_f32 v193, v193, v109, v110
	v_max_f32_e32 v193, v193, v111
	ds_bpermute_b32 v210, v166, v193
	ds_bpermute_b32 v209, v166, v192
	s_waitcnt lgkmcnt(1)
	v_max3_f32 v210, v161, v193, v210
	s_waitcnt lgkmcnt(0)
	v_max3_f32 v209, v160, v192, v209
	v_sub_f32_e32 v64, v64, v210
	v_sub_f32_e32 v80, v80, v209
	v_exp_f32_e32 v193, v64
	v_sub_f32_e32 v64, v96, v210
	v_exp_f32_e32 v192, v80
	v_sub_f32_e32 v80, v112, v209
	v_exp_f32_e32 v213, v64
	v_sub_f32_e32 v64, v81, v209
	v_exp_f32_e32 v212, v80
	v_exp_f32_e32 v80, v64
	v_sub_f32_e32 v64, v113, v209
	v_exp_f32_e32 v96, v64
	v_sub_f32_e32 v64, v65, v210
	v_exp_f32_e32 v81, v64
	v_sub_f32_e32 v64, v97, v210
	v_exp_f32_e32 v97, v64
	v_sub_f32_e32 v64, v82, v209
	v_exp_f32_e32 v112, v64
	v_sub_f32_e32 v64, v114, v209
	v_exp_f32_e32 v214, v64
	v_sub_f32_e32 v64, v66, v210
	v_exp_f32_e32 v113, v64
	v_sub_f32_e32 v64, v98, v210
	v_exp_f32_e32 v215, v64
	v_sub_f32_e32 v64, v83, v209
	v_exp_f32_e32 v82, v64
	v_sub_f32_e32 v64, v115, v209
	v_exp_f32_e32 v98, v64
	v_sub_f32_e32 v64, v67, v210
	v_exp_f32_e32 v83, v64
	v_sub_f32_e32 v64, v99, v210
	v_exp_f32_e32 v99, v64
	v_sub_f32_e32 v64, v84, v209
	v_exp_f32_e32 v114, v64
	v_sub_f32_e32 v64, v116, v209
	v_exp_f32_e32 v216, v64
	v_sub_f32_e32 v64, v68, v210
	v_exp_f32_e32 v115, v64
	v_sub_f32_e32 v64, v100, v210
	v_exp_f32_e32 v217, v64
	v_sub_f32_e32 v64, v85, v209
	v_exp_f32_e32 v84, v64
	v_sub_f32_e32 v64, v117, v209
	v_exp_f32_e32 v100, v64
	v_sub_f32_e32 v64, v69, v210
	v_exp_f32_e32 v85, v64
	v_sub_f32_e32 v64, v101, v210
	v_exp_f32_e32 v101, v64
	v_sub_f32_e32 v64, v86, v209
	v_exp_f32_e32 v116, v64
	v_sub_f32_e32 v64, v118, v209
	v_exp_f32_e32 v218, v64
	v_sub_f32_e32 v64, v70, v210
	v_exp_f32_e32 v117, v64
	v_sub_f32_e32 v64, v102, v210
	v_exp_f32_e32 v219, v64
	v_sub_f32_e32 v64, v87, v209
	v_exp_f32_e32 v70, v64
	v_sub_f32_e32 v64, v119, v209
	v_exp_f32_e32 v86, v64
	v_sub_f32_e32 v64, v71, v210
	v_exp_f32_e32 v71, v64
	v_sub_f32_e32 v64, v103, v210
	v_exp_f32_e32 v87, v64
	v_sub_f32_e32 v64, v88, v209
	v_exp_f32_e32 v102, v64
	v_sub_f32_e32 v64, v120, v209
	v_exp_f32_e32 v118, v64
	v_sub_f32_e32 v64, v72, v210
	v_exp_f32_e32 v103, v64
	v_sub_f32_e32 v64, v104, v210
	v_exp_f32_e32 v119, v64
	v_sub_f32_e32 v64, v89, v209
	v_exp_f32_e32 v88, v64
	v_sub_f32_e32 v64, v121, v209
	v_exp_f32_e32 v104, v64
	v_sub_f32_e32 v64, v73, v210
	v_exp_f32_e32 v89, v64
	v_sub_f32_e32 v64, v105, v210
	v_exp_f32_e32 v105, v64
	v_sub_f32_e32 v64, v90, v209
	v_exp_f32_e32 v120, v64
	v_sub_f32_e32 v64, v122, v209
	v_exp_f32_e32 v220, v64
	v_sub_f32_e32 v64, v74, v210
	v_exp_f32_e32 v121, v64
	v_sub_f32_e32 v64, v106, v210
	v_exp_f32_e32 v221, v64
; DI void attn_pass_da(const bfr* __restrict__ P, int b, int tq_wave, int qcol, int kcol, int vcol, int key0, int nkt, char* smem, f32x16 (&o0)[2], f32x16 (&o1)[2]) {
;     ...
;     const float mn0 = fmaxf(m0, mx0), mn1 = fmaxf(m1, mx1);
;     const float al0 = __builtin_amdgcn_exp2f(m0 - mn0), al1 = __builtin_amdgcn_exp2f(m1 - mn1);
;     m0 = mn0; m1 = mn1;
;     float ps0 = 0.f, ps1 = 0.f;
; #pragma unroll
;     for (int i = 0; i < 16; ++i) {
;       s0[0][i] = __builtin_amdgcn_exp2f(s0[0][i] - mn0); ps0 += s0[0][i];
;       s0[1][i] = __builtin_amdgcn_exp2f(s0[1][i] - mn0); ps0 += s0[1][i];
;       s1[0][i] = __builtin_amdgcn_exp2f(s1[0][i] - mn1); ps1 += s1[0][i];
;       s1[1][i] = __builtin_amdgcn_exp2f(s1[1][i] - mn1); ps1 += s1[1][i];
;     }
;     l0 = l0 * al0 + ps0; l1 = l1 * al1 + ps1;
; #pragma unroll
;     for (int i = 0; i < 16; ++i) { acc0[0][i] *= al0; acc0[1][i] *= al0; acc1[0][i] *= al1; acc1[1][i] *= al1; }
	v_sub_f32_e32 v64, v91, v209
	v_exp_f32_e32 v90, v64
	v_sub_f32_e32 v64, v123, v209
	v_exp_f32_e32 v106, v64
	v_sub_f32_e32 v64, v75, v210
	v_exp_f32_e32 v91, v64
	v_sub_f32_e32 v64, v107, v210
	v_exp_f32_e32 v107, v64
	v_sub_f32_e32 v64, v92, v209
	v_exp_f32_e32 v122, v64
	v_sub_f32_e32 v64, v124, v209
	v_exp_f32_e32 v222, v64
	v_sub_f32_e32 v64, v76, v210
	v_exp_f32_e32 v123, v64
	v_sub_f32_e32 v64, v108, v210
	v_exp_f32_e32 v223, v64
	v_sub_f32_e32 v64, v93, v209
	v_exp_f32_e32 v92, v64
	v_sub_f32_e32 v64, v125, v209
	v_exp_f32_e32 v108, v64
	v_sub_f32_e32 v64, v77, v210
	v_exp_f32_e32 v93, v64
	v_sub_f32_e32 v64, v109, v210
	v_exp_f32_e32 v109, v64
	v_sub_f32_e32 v64, v94, v209
	v_exp_f32_e32 v124, v64
	v_sub_f32_e32 v64, v126, v209
	v_exp_f32_e32 v224, v64
	v_sub_f32_e32 v64, v78, v210
	v_exp_f32_e32 v125, v64
	v_sub_f32_e32 v64, v110, v210
	v_exp_f32_e32 v225, v64
	v_sub_f32_e32 v64, v95, v209
	v_exp_f32_e32 v94, v64
	v_sub_f32_e32 v64, v127, v209
	v_exp_f32_e32 v110, v64
	v_sub_f32_e32 v64, v79, v210
	v_exp_f32_e32 v95, v64
	v_sub_f32_e32 v64, v111, v210
	v_exp_f32_e32 v111, v64
	v_add_f32_e32 v64, 0, v192
	v_add_f32_e32 v65, 0, v193
	v_sub_f32_e32 v161, v161, v210
	v_add_f32_e32 v64, v212, v64
	v_add_f32_e32 v65, v213, v65
	v_exp_f32_e32 v161, v161
	v_add_f32_e32 v64, v80, v64
	v_add_f32_e32 v65, v81, v65
	v_lshl_add_u32 v74, v180, 1, v194
	v_add_f32_e32 v64, v96, v64
	v_add_f32_e32 v65, v97, v65
	v_lshl_add_u32 v76, v179, 1, v195
	v_add_f32_e32 v64, v112, v64
	v_add_f32_e32 v65, v113, v65
	v_lshl_add_u32 v78, v178, 1, v195
	v_add_f32_e32 v64, v214, v64
	v_add_f32_e32 v65, v215, v65
	v_sub_f32_e32 v160, v160, v209
	v_add_f32_e32 v64, v82, v64
	v_add_f32_e32 v65, v83, v65
	v_exp_f32_e32 v160, v160
	v_add_f32_e32 v64, v98, v64
	v_add_f32_e32 v65, v99, v65
	v_mul_f32_e32 v62, v62, v160
	v_mul_f32_e32 v63, v63, v160
	v_add_f32_e32 v64, v114, v64
	v_add_f32_e32 v65, v115, v65
	v_mul_f32_e32 v60, v60, v160
	v_mul_f32_e32 v61, v61, v160
	v_add_f32_e32 v64, v216, v64
	v_add_f32_e32 v65, v217, v65
	v_mul_f32_e32 v58, v58, v160
	v_mul_f32_e32 v59, v59, v160
	v_add_f32_e32 v64, v84, v64
	v_add_f32_e32 v65, v85, v65
	v_mul_f32_e32 v56, v56, v160
	v_mul_f32_e32 v57, v57, v160
	v_add_f32_e32 v64, v100, v64
	v_add_f32_e32 v65, v101, v65
	v_mul_f32_e32 v54, v54, v160
	v_mul_f32_e32 v55, v55, v160
	v_add_f32_e32 v64, v116, v64
	v_add_f32_e32 v65, v117, v65
	v_mul_f32_e32 v52, v52, v160
	v_mul_f32_e32 v53, v53, v160
	v_add_f32_e32 v64, v218, v64
	v_add_f32_e32 v65, v219, v65
	v_mul_f32_e32 v50, v50, v160
	v_mul_f32_e32 v51, v51, v160
	v_add_f32_e32 v64, v70, v64
	v_add_f32_e32 v65, v71, v65
	v_mul_f32_e32 v48, v48, v160
	v_mul_f32_e32 v49, v49, v160
	v_add_f32_e32 v64, v86, v64
	v_add_f32_e32 v65, v87, v65
	v_mul_f32_e32 v30, v30, v160
	v_mul_f32_e32 v31, v31, v160
	v_add_f32_e32 v64, v102, v64
	v_add_f32_e32 v65, v103, v65
	v_mul_f32_e32 v28, v28, v160
	v_mul_f32_e32 v29, v29, v160
	v_add_f32_e32 v64, v118, v64
	v_add_f32_e32 v65, v119, v65
	v_mul_f32_e32 v26, v26, v160
	v_mul_f32_e32 v27, v27, v160
	v_add_f32_e32 v64, v88, v64
	v_add_f32_e32 v65, v89, v65
	v_mul_f32_e32 v24, v24, v160
	v_mul_f32_e32 v25, v25, v160
	v_add_f32_e32 v64, v104, v64
	v_add_f32_e32 v65, v105, v65
	v_mul_f32_e32 v22, v22, v160
	v_mul_f32_e32 v23, v23, v160
	v_add_f32_e32 v64, v120, v64
	v_add_f32_e32 v65, v121, v65
	v_mul_f32_e32 v20, v20, v160
	v_mul_f32_e32 v21, v21, v160
	v_add_f32_e32 v126, v220, v64
	v_add_f32_e32 v127, v221, v65
	v_cvt_pk_bf16_f32 v64, v192, v80
	v_cvt_pk_bf16_f32 v65, v112, v82
	v_lshl_add_u32 v112, v181, 1, v194
	v_cvt_pk_bf16_f32 v66, v114, v84
	v_cvt_pk_bf16_f32 v67, v116, v70
	v_cvt_pk_bf16_f32 v68, v193, v81
	v_cvt_pk_bf16_f32 v69, v113, v83
	v_cvt_pk_bf16_f32 v70, v115, v85
	v_cvt_pk_bf16_f32 v71, v117, v71
	ds_read_b64 v[72:73], v112 offset:9216
	ds_read_b64 v[74:75], v74 offset:9216
	ds_read_b64 v[76:77], v76 offset:9216
	ds_read_b64 v[78:79], v78 offset:9216
	v_mov_b32_e32 v82, v161
	v_mul_f32_e32 v46, v46, v82
	v_mul_f32_e32 v47, v47, v82
	v_mul_f32_e32 v44, v44, v82
	v_mul_f32_e32 v45, v45, v82
	v_mul_f32_e32 v42, v42, v82
	v_mul_f32_e32 v43, v43, v82
	v_mul_f32_e32 v40, v40, v82
	v_mul_f32_e32 v41, v41, v82
	v_mul_f32_e32 v38, v38, v82
	v_mul_f32_e32 v39, v39, v82
	v_mul_f32_e32 v36, v36, v82
	v_mul_f32_e32 v37, v37, v82
	v_mul_f32_e32 v34, v34, v82
	v_mul_f32_e32 v35, v35, v82
	v_mul_f32_e32 v32, v32, v82
	v_mul_f32_e32 v33, v33, v82
	v_mul_f32_e32 v14, v14, v82
	v_mul_f32_e32 v15, v15, v82
	v_mul_f32_e32 v12, v12, v82
	v_mul_f32_e32 v13, v13, v82
	v_mul_f32_e32 v10, v10, v82
	v_mul_f32_e32 v11, v11, v82
	v_mul_f32_e32 v8, v8, v82
	v_mul_f32_e32 v9, v9, v82
	v_mul_f32_e32 v6, v6, v82
	v_mul_f32_e32 v7, v7, v82
	v_mul_f32_e32 v4, v4, v82
	v_mul_f32_e32 v5, v5, v82
	v_mul_f32_e32 v2, v2, v82
	v_mul_f32_e32 v3, v3, v82
	v_mul_f32_e32 v0, v0, v82
	v_mul_f32_e32 v1, v1, v82
	v_add_f32_e32 v82, v90, v126
	v_add_f32_e32 v83, v91, v127
	s_waitcnt lgkmcnt(2)
	v_mfma_f32_32x32x16_bf16 v[48:63], v[72:75], v[64:67], v[48:63]
	v_add_f32_e64 v82, v106, v82
	v_add_f32_e64 v83, v107, v83
	v_cvt_pk_bf16_f32 v80, v102, v88
	v_lshl_add_u32 v88, v177, 1, v194
	v_add_f32_e64 v82, v122, v82
	v_add_f32_e64 v83, v123, v83
	v_mul_f32_e32 v18, v18, v160
	v_mul_f32_e32 v19, v19, v160
	v_add_f32_e32 v82, v222, v82
	v_add_f32_e32 v83, v223, v83
	v_mul_f32_e32 v16, v16, v160
	v_mul_f32_e32 v17, v17, v160
	v_add_f32_e32 v82, v92, v82
	v_add_f32_e32 v83, v93, v83
	v_mfma_f32_32x32x16_bf16 v[32:47], v[72:75], v[68:71], v[32:47]
	v_add_f32_e64 v82, v108, v82
	v_add_f32_e64 v83, v109, v83
	v_cvt_pk_bf16_f32 v81, v120, v90
	v_lshl_add_u32 v102, v176, 1, v194
	v_add_f32_e64 v82, v124, v82
	v_add_f32_e64 v83, v125, v83
	v_lshl_add_u32 v113, v175, 1, v195
	v_add_f32_e32 v82, v224, v82
	v_add_f32_e32 v83, v225, v83
	v_lshl_add_u32 v114, v174, 1, v195
	v_add_f32_e32 v82, v94, v82
	v_add_f32_e32 v83, v95, v83
	s_waitcnt lgkmcnt(0)
; DI void attn_pass_da(const bfr* __restrict__ P, int b, int tq_wave, int qcol, int kcol, int vcol, int key0, int nkt, char* smem, f32x16 (&o0)[2], f32x16 (&o1)[2]) {
;     ...
;   for (int kt = 0; kt < nkt; ++kt) {
;     bfr* sK = sbase + (kt & 1) * 9216;
;     bfr* sV = sK + 64 * 72;
;     { int c = gt, row = c >> 3, kc = c & 7; *(u32x4*)(sK + row * KP + kc * 8) = kreg[0]; }
;     for (int i = 0; i < 1; ++i) {
;       int c = gt, row = c >> 3, kc = c & 7;
;       unsigned wds[4] = {vreg[i].x, vreg[i].y, vreg[i].z, vreg[i].w};
; #pragma unroll
;       for (int e = 0; e < 4; ++e) {
;         sV[(kc * 8 + 2 * e) * 72 + (row ^ (kc << 3))] = (bfr)(wds[e] & 0xffffu);
;         sV[(kc * 8 + 2 * e + 1) * 72 + (row ^ (kc << 3))] = (bfr)(wds[e] >> 16);
;       }
;     }
;     __syncthreads();
;     if (kt + 1 < nkt) {
;       const bfr* Pn = Pb + (size_t)(kt + 1) * 64 * PW;
;       { int c = gt, row = c >> 3, kc = c & 7; kreg[0] = *(const u32x4*)(Pn + (size_t)row * PW + kcol + kc * 8); vreg[0] = *(const u32x4*)(Pn + (size_t)row * PW + vcol + kc * 8); }
;     }
;     f32x16 s0[2], s1[2];
; #pragma unroll
;     for (int t2 = 0; t2 < 2; ++t2) {
; #pragma unroll
;     ...
;     for (int t2 = 0; t2 < 2; ++t2)
; #pragma unroll
;       for (int j = 0; j < 2; ++j) {
;         u32x4 pk0, pk1;
;         pk0.x = pack2(s0[t2][8 * j + 0], s0[t2][8 * j + 1]); pk0.y = pack2(s0[t2][8 * j + 2], s0[t2][8 * j + 3]);
;         pk0.z = pack2(s0[t2][8 * j + 4], s0[t2][8 * j + 5]); pk0.w = pack2(s0[t2][8 * j + 6], s0[t2][8 * j + 7]);
;         pk1.x = pack2(s1[t2][8 * j + 0], s1[t2][8 * j + 1]); pk1.y = pack2(s1[t2][8 * j + 2], s1[t2][8 * j + 3]);
;         pk1.z = pack2(s1[t2][8 * j + 4], s1[t2][8 * j + 5]); pk1.w = pack2(s1[t2][8 * j + 6], s1[t2][8 * j + 7]);
;         const bf16x8 pf0 = __builtin_bit_cast(bf16x8, pk0), pf1 = __builtin_bit_cast(bf16x8, pk1);
; #pragma unroll
;         for (int dt = 0; dt < 2; ++dt) {
;           const int vsw = (((dt * 32 + r) >> 3) & 7) << 3;
;           const bfr* vrow = sV + (dt * 32 + r) * 72;
;           s16x4 lo = *(const s16x4*)(vrow + ((t2 * 32 + 16 * j + 4 * h) ^ vsw));
;           s16x4 hi = *(const s16x4*)(vrow + ((t2 * 32 + 16 * j + 4 * h + 8) ^ vsw));
;           bf16x8 vf = __builtin_shufflevector(lo, hi, 0, 1, 2, 3, 4, 5, 6, 7);
;           acc0[dt] = MFMA32(vf, pf0, acc0[dt]);
;           acc1[dt] = MFMA32(vf, pf1, acc1[dt]);
;         }
;       }
	v_mfma_f32_32x32x16_bf16 v[16:31], v[76:79], v[64:67], v[16:31]
	v_add_f32_e64 v84, v110, v82
	v_add_f32_e64 v85, v111, v83
	v_cvt_pk_bf16_f32 v82, v122, v92
	v_cvt_pk_bf16_f32 v83, v124, v94
	v_cvt_pk_bf16_f32 v64, v103, v89
	v_cvt_pk_bf16_f32 v65, v121, v91
	v_cvt_pk_bf16_f32 v66, v123, v93
	v_cvt_pk_bf16_f32 v67, v125, v95
	v_mfma_f32_32x32x16_bf16 v[0:15], v[76:79], v[68:71], v[0:15]
	ds_read_b64 v[68:69], v88 offset:9216
	ds_read_b64 v[70:71], v102 offset:9216
	v_lshl_add_u32 v115, v173, 1, v194
	v_lshl_add_u32 v116, v172, 1, v195
	v_lshl_add_u32 v117, v171, 1, v195
	v_lshl_add_u32 v120, v169, 1, v194
	v_lshl_add_u32 v192, v170, 1, v194
	v_lshl_add_u32 v193, v168, 1, v195
	s_waitcnt lgkmcnt(0)
	v_mfma_f32_32x32x16_bf16 v[48:63], v[68:71], v[80:83], v[48:63]
	v_lshl_add_u32 v194, v167, 1, v195
	v_fma_f32 v156, v156, v160, v84
	v_fma_f32 v157, v157, v161, v85
	v_mfma_f32_32x32x16_bf16 v[32:47], v[68:71], v[64:67], v[32:47]
	ds_read_b64 v[68:69], v113 offset:9216
	ds_read_b64 v[70:71], v114 offset:9216
	s_waitcnt lgkmcnt(0)
	v_mfma_f32_32x32x16_bf16 v[16:31], v[68:71], v[80:83], v[16:31]
	v_mfma_f32_32x32x16_bf16 v[0:15], v[68:71], v[64:67], v[0:15]
	v_cvt_pk_bf16_f32 v64, v212, v96
	v_cvt_pk_bf16_f32 v65, v214, v98
	v_cvt_pk_bf16_f32 v66, v216, v100
	v_cvt_pk_bf16_f32 v67, v218, v86
	v_cvt_pk_bf16_f32 v68, v213, v97
	v_cvt_pk_bf16_f32 v69, v215, v99
	v_cvt_pk_bf16_f32 v70, v217, v101
	v_cvt_pk_bf16_f32 v71, v219, v87
	ds_read_b64 v[72:73], v112 offset:9280
	ds_read_b64 v[74:75], v115 offset:9216
	s_waitcnt lgkmcnt(0)
	v_mfma_f32_32x32x16_bf16 v[48:63], v[72:75], v[64:67], v[48:63]
	v_mfma_f32_32x32x16_bf16 v[32:47], v[72:75], v[68:71], v[32:47]
	ds_read_b64 v[72:73], v116 offset:9216
	ds_read_b64 v[74:75], v117 offset:9216
	s_waitcnt lgkmcnt(0)
	v_mfma_f32_32x32x16_bf16 v[16:31], v[72:75], v[64:67], v[16:31]
	v_cvt_pk_bf16_f32 v64, v118, v104
	v_cvt_pk_bf16_f32 v65, v220, v106
	v_cvt_pk_bf16_f32 v66, v222, v108
	v_cvt_pk_bf16_f32 v67, v224, v110
	v_mfma_f32_32x32x16_bf16 v[0:15], v[72:75], v[68:71], v[0:15]
	v_cvt_pk_bf16_f32 v68, v119, v105
	v_cvt_pk_bf16_f32 v69, v221, v107
	v_cvt_pk_bf16_f32 v70, v223, v109
	v_cvt_pk_bf16_f32 v71, v225, v111
	ds_read_b64 v[72:73], v120 offset:9216
	ds_read_b64 v[74:75], v192 offset:9216
	s_waitcnt lgkmcnt(0)
	v_mfma_f32_32x32x16_bf16 v[48:63], v[72:75], v[64:67], v[48:63]
	v_mfma_f32_32x32x16_bf16 v[32:47], v[72:75], v[68:71], v[32:47]
	ds_read_b64 v[72:73], v193 offset:9216
	ds_read_b64 v[74:75], v194 offset:9216
	s_waitcnt lgkmcnt(0)
	v_mfma_f32_32x32x16_bf16 v[16:31], v[72:75], v[64:67], v[16:31]
	v_mfma_f32_32x32x16_bf16 v[0:15], v[72:75], v[68:71], v[0:15]
	s_cbranch_scc1 .LBB0_421
	v_add3_u32 v64, 0, v206, v152
	s_waitcnt vmcnt(1)
	ds_write_b128 v64, v[148:151] offset:18432
	v_add3_u32 v64, 0, v207, v208
	v_add3_u32 v65, 0, v208, v207
	s_waitcnt vmcnt(0)
	ds_write_b16 v64, v144 offset:27648
	ds_write_b16_d16_hi v65, v144 offset:27792
	ds_write_b16 v64, v145 offset:27936
	ds_write_b16_d16_hi v65, v145 offset:28080
	ds_write_b16 v64, v146 offset:28224
	ds_write_b16_d16_hi v65, v146 offset:28368
	ds_write_b16 v64, v147 offset:28512
	ds_write_b16_d16_hi v65, v147 offset:28656
	v_add_u32_e32 v144, 0, v205
	v_add_u32_e32 v102, v144, v204
	s_waitcnt lgkmcnt(0)
	s_barrier
	ds_read_b128 v[64:67], v102 offset:18432
	ds_read_b128 v[96:99], v102 offset:18464
	s_waitcnt lgkmcnt(1)
	v_mfma_f32_32x32x16_bf16 v[64:79], v[64:67], v[140:143], 0
	ds_read_b128 v[80:83], v102 offset:18496
	v_readlane_b32 s10, v203, 16
	v_readlane_b32 s11, v203, 48
	v_add_u32_e32 v145, 0x1200, v144
	v_mov_b32_e32 v100, s10
	v_mov_b32_e32 v101, s11
	v_pk_add_f32 v[100:101], s[8:9], v[100:101]
	s_mov_b32 s10, 0x3fb8aa3b
	v_add_f32_e32 v146, v100, v101
	v_mul_f32_e32 v104, 0x3fb8aa3b, v146
	v_fma_f32 v105, v146, s10, -v104
	v_rndne_f32_e32 v106, v104
	s_waitcnt lgkmcnt(1)
	v_mfma_f32_32x32x16_bf16 v[64:79], v[96:99], v[132:135], v[64:79]
	v_fmac_f32_e32 v105, 0x32a5705f, v146
	v_sub_f32_e32 v96, v104, v106
	v_add_u32_e32 v147, v145, v204
	v_add_f32_e32 v104, v96, v105
	ds_read_b128 v[96:99], v147 offset:18432
	ds_read_b128 v[100:103], v102 offset:18528
	ds_read_b128 v[112:115], v147 offset:18496
	s_waitcnt lgkmcnt(3)
	v_mfma_f32_32x32x16_bf16 v[80:95], v[80:83], v[136:139], 0
	v_readlane_b32 s8, v202, 16
	v_readlane_b32 s9, v202, 48
	s_mov_b32 s11, 0xc2ce8ed0
	v_mov_b32_e32 v116, s8
	v_mov_b32_e32 v117, s9
	v_pk_add_f32 v[116:117], s[6:7], v[116:117]
	v_cmp_ngt_f32_e32 vcc, s11, v146
	s_waitcnt lgkmcnt(1)
	v_mfma_f32_32x32x16_bf16 v[80:95], v[100:103], v[128:131], v[80:95]
	v_exp_f32_e32 v100, v104
	v_cvt_i32_f32_e32 v101, v106
	v_add_f32_e32 v149, v116, v117
	v_mul_f32_e32 v150, 0x3fb8aa3b, v149
	v_rndne_f32_e32 v151, v150
	v_ldexp_f32 v148, v100, v101
	s_mov_b32 s6, 0x42b17218
	s_waitcnt lgkmcnt(0)
	v_mfma_f32_32x32x16_bf16 v[112:127], v[112:115], v[136:139], 0
	v_fma_f32 v136, v149, s10, -v150
	v_fmac_f32_e32 v136, 0x32a5705f, v149
	v_sub_f32_e32 v137, v150, v151
	v_add_f32_e32 v136, v137, v136
	v_exp_f32_e32 v150, v136
	ds_read_b128 v[136:139], v147 offset:18528
	v_readlane_b32 s8, v253, 28
	v_mfma_f32_32x32x16_bf16 v[96:111], v[96:99], v[140:143], 0
	ds_read_b128 v[140:143], v147 offset:18464
	v_readlane_b32 s9, v253, 29
	s_waitcnt lgkmcnt(0)
; DI void attn_pass_da(const bfr* __restrict__ P, int b, int tq_wave, int qcol, int kcol, int vcol, int key0, int nkt, char* smem, f32x16 (&o0)[2], f32x16 (&o1)[2]) {
;     ...
;     float mx0 = s0[0][0], mx1 = s1[0][0];
; #pragma unroll
;     for (int i = 0; i < 16; ++i) { mx0 = fmaxf(mx0, fmaxf(s0[0][i], s0[1][i])); mx1 = fmaxf(mx1, fmaxf(s1[0][i], s1[1][i])); }
;     mx0 = fmaxf(mx0, __shfl_xor(mx0, 32)); mx1 = fmaxf(mx1, __shfl_xor(mx1, 32));
;     const float mn0 = fmaxf(m0, mx0), mn1 = fmaxf(m1, mx1);
;     const float al0 = __builtin_amdgcn_exp2f(m0 - mn0), al1 = __builtin_amdgcn_exp2f(m1 - mn1);
;     m0 = mn0; m1 = mn1;
;     float ps0 = 0.f, ps1 = 0.f;
; #pragma unroll
;     for (int i = 0; i < 16; ++i) {
;       s0[0][i] = __builtin_amdgcn_exp2f(s0[0][i] - mn0); ps0 += s0[0][i];
;       s0[1][i] = __builtin_amdgcn_exp2f(s0[1][i] - mn0); ps0 += s0[1][i];
;       s1[0][i] = __builtin_amdgcn_exp2f(s1[0][i] - mn1); ps1 += s1[0][i];
;       s1[1][i] = __builtin_amdgcn_exp2f(s1[1][i] - mn1); ps1 += s1[1][i];
;     }
	v_mfma_f32_32x32x16_bf16 v[96:111], v[140:143], v[132:135], v[96:111]
	v_max_f32_e32 v134, v82, v82
	v_max_f32_e32 v135, v67, v67
	v_cvt_i32_f32_e32 v132, v151
	v_cndmask_b32_e32 v133, 0, v148, vcc
	v_cmp_nlt_f32_e32 vcc, s6, v146
	v_ldexp_f32 v132, v150, v132
	v_mfma_f32_32x32x16_bf16 v[112:127], v[136:139], v[128:131], v[112:127]
	s_nop 4
	v_max_f32_e32 v128, v97, v97
	v_max_f32_e32 v129, v65, v65
	v_max_f32_e32 v128, v129, v128
	v_max_f32_e32 v130, v81, v81
	v_max_f32_e32 v131, v66, v66
	v_max3_f32 v128, v64, v96, v128
	v_cndmask_b32_e32 v133, v201, v133, vcc
	v_max_f32_e32 v129, v113, v113
	v_max_f32_e32 v129, v130, v129
	v_max_f32_e32 v130, v98, v98
	v_max_f32_e32 v130, v131, v130
	v_max_f32_e32 v131, v114, v114
	v_max_f32_e32 v131, v134, v131
	v_max_f32_e32 v134, v99, v99
	v_max_f32_e32 v134, v135, v134
	v_max3_f32 v128, v128, v130, v134
	v_max_f32_e32 v130, v115, v115
	v_max_f32_e32 v134, v83, v83
	v_max3_f32 v129, v80, v112, v129
	v_max_f32_e32 v130, v134, v130
	v_max3_f32 v129, v129, v131, v130
	v_max_f32_e32 v130, v100, v100
	v_max_f32_e32 v131, v68, v68
	v_max_f32_e32 v130, v131, v130
	v_max_f32_e32 v131, v116, v116
	v_max_f32_e32 v134, v84, v84
	v_max_f32_e32 v131, v134, v131
	v_max_f32_e32 v134, v101, v101
	v_max_f32_e32 v135, v69, v69
	v_max_f32_e32 v134, v135, v134
	v_max3_f32 v128, v128, v130, v134
	v_max_f32_e32 v130, v117, v117
	v_max_f32_e32 v134, v85, v85
	v_max_f32_e32 v130, v134, v130
	v_max3_f32 v129, v129, v131, v130
	v_max_f32_e32 v130, v102, v102
	v_max_f32_e32 v131, v70, v70
	v_max_f32_e32 v130, v131, v130
	v_max_f32_e32 v131, v118, v118
	v_max_f32_e32 v134, v86, v86
	v_max_f32_e32 v131, v134, v131
	v_max_f32_e32 v134, v103, v103
	v_max_f32_e32 v135, v71, v71
	v_max_f32_e32 v134, v135, v134
	v_max3_f32 v128, v128, v130, v134
	v_max_f32_e32 v130, v119, v119
	v_max_f32_e32 v134, v87, v87
	v_max_f32_e32 v130, v134, v130
	v_max3_f32 v129, v129, v131, v130
	v_max_f32_e32 v130, v104, v104
	v_max_f32_e32 v131, v72, v72
	v_max_f32_e32 v130, v131, v130
	v_max_f32_e32 v131, v120, v120
	v_max_f32_e32 v134, v88, v88
	v_max_f32_e32 v131, v134, v131
	v_max_f32_e32 v134, v105, v105
	v_max_f32_e32 v135, v73, v73
	v_max_f32_e32 v134, v135, v134
	v_max3_f32 v128, v128, v130, v134
	v_max_f32_e32 v130, v121, v121
	v_max_f32_e32 v134, v89, v89
	v_max_f32_e32 v130, v134, v130
	v_max3_f32 v129, v129, v131, v130
	v_max_f32_e32 v130, v106, v106
	v_max_f32_e32 v131, v74, v74
	v_max_f32_e32 v130, v131, v130
	v_max_f32_e32 v131, v122, v122
	v_max_f32_e32 v134, v90, v90
	v_max_f32_e32 v131, v134, v131
	v_max_f32_e32 v134, v107, v107
	v_max_f32_e32 v135, v75, v75
	v_max_f32_e32 v134, v135, v134
	v_max3_f32 v128, v128, v130, v134
	v_max_f32_e32 v130, v123, v123
	v_max_f32_e32 v134, v91, v91
	v_max_f32_e32 v130, v134, v130
	v_max3_f32 v129, v129, v131, v130
	v_max_f32_e32 v130, v108, v108
	v_max_f32_e32 v131, v76, v76
	v_max_f32_e32 v130, v131, v130
	v_max_f32_e32 v131, v124, v124
	v_max_f32_e32 v134, v92, v92
	v_max_f32_e32 v131, v134, v131
	v_max_f32_e32 v134, v109, v109
	v_max_f32_e32 v135, v77, v77
	v_max_f32_e32 v134, v135, v134
	v_max3_f32 v128, v128, v130, v134
	v_max_f32_e32 v130, v125, v125
	v_max_f32_e32 v134, v93, v93
	v_max_f32_e32 v130, v134, v130
	v_max3_f32 v129, v129, v131, v130
	v_max_f32_e32 v130, v110, v110
	v_max_f32_e32 v131, v78, v78
	v_max_f32_e32 v130, v131, v130
	v_max_f32_e32 v131, v126, v126
	v_max_f32_e32 v134, v94, v94
	v_max_f32_e32 v131, v134, v131
	v_max_f32_e32 v134, v111, v111
	v_max_f32_e32 v135, v79, v79
	v_max_f32_e32 v134, v135, v134
	v_max3_f32 v128, v128, v130, v134
	v_max_f32_e32 v130, v127, v127
	v_max_f32_e32 v134, v95, v95
	v_max_f32_e32 v130, v134, v130
	v_max3_f32 v130, v129, v131, v130
	ds_bpermute_b32 v131, v166, v128
	ds_bpermute_b32 v134, v166, v130
	v_cmp_ngt_f32_e32 vcc, s11, v149
	s_waitcnt lgkmcnt(0)
	v_max3_f32 v150, v210, v130, v134
	v_cndmask_b32_e32 v132, 0, v132, vcc
	v_cmp_nlt_f32_e32 vcc, s6, v149
	v_max3_f32 v149, v209, v128, v131
	v_sub_f32_e32 v64, v64, v149
	v_exp_f32_e32 v148, v64
	v_sub_f32_e32 v64, v96, v149
	v_exp_f32_e32 v131, v64
	v_sub_f32_e32 v64, v80, v150
	v_exp_f32_e32 v151, v64
	v_sub_f32_e32 v64, v112, v150
	v_exp_f32_e32 v96, v64
	v_sub_f32_e32 v64, v65, v149
	v_exp_f32_e32 v152, v64
	v_sub_f32_e32 v64, v97, v149
	v_exp_f32_e32 v112, v64
	v_sub_f32_e32 v64, v81, v150
	v_exp_f32_e32 v158, v64
	v_sub_f32_e32 v64, v113, v150
	v_exp_f32_e32 v97, v64
	v_sub_f32_e32 v64, v66, v149
	v_exp_f32_e32 v143, v64
	v_sub_f32_e32 v64, v98, v149
	v_exp_f32_e32 v113, v64
	v_sub_f32_e32 v64, v82, v150
	v_exp_f32_e32 v146, v64
	v_sub_f32_e32 v64, v114, v150
	v_exp_f32_e32 v98, v64
	v_sub_f32_e32 v64, v67, v149
	v_exp_f32_e32 v147, v64
	v_sub_f32_e32 v64, v99, v149
	v_exp_f32_e32 v114, v64
	v_sub_f32_e32 v64, v83, v150
	v_exp_f32_e32 v138, v64
	v_sub_f32_e32 v64, v115, v150
	v_exp_f32_e32 v99, v64
	v_sub_f32_e32 v64, v68, v149
	v_exp_f32_e32 v139, v64
	v_sub_f32_e32 v64, v100, v149
	v_exp_f32_e32 v115, v64
	v_sub_f32_e32 v64, v84, v150
	v_exp_f32_e32 v140, v64
	v_sub_f32_e32 v64, v116, v150
	v_exp_f32_e32 v100, v64
	v_sub_f32_e32 v64, v69, v149
	v_exp_f32_e32 v141, v64
	v_sub_f32_e32 v64, v101, v149
	v_exp_f32_e32 v116, v64
	v_sub_f32_e32 v64, v85, v150
	v_exp_f32_e32 v142, v64
	v_sub_f32_e32 v64, v117, v150
	v_exp_f32_e32 v101, v64
	v_sub_f32_e32 v64, v70, v149
	v_exp_f32_e32 v134, v64
	v_sub_f32_e32 v64, v102, v149
	v_cndmask_b32_e32 v129, v201, v132, vcc
	v_exp_f32_e32 v132, v64
	v_sub_f32_e32 v64, v86, v150
	v_exp_f32_e32 v135, v64
	v_sub_f32_e32 v64, v118, v150
	v_exp_f32_e32 v117, v64
	v_sub_f32_e32 v64, v71, v149
	v_exp_f32_e32 v136, v64
	v_sub_f32_e32 v64, v103, v149
; #define MFMA32(a, b, c) __builtin_amdgcn_mfma_f32_32x32x16_bf16((a), (b), (c), 0, 0, 0)
; DI unsigned pack2(float a, float b) { unsigned r; asm volatile("v_cvt_pk_bf16_f32 %0, %1, %2" : "=v"(r) : "v"(a), "v"(b)); return r; }
; DI void attn_pass_da(const bfr* __restrict__ P, int b, int tq_wave, int qcol, int kcol, int vcol, int key0, int nkt, char* smem, f32x16 (&o0)[2], f32x16 (&o1)[2]) {
;     ...
;     for (int i = 0; i < 16; ++i) {
;       s0[0][i] = __builtin_amdgcn_exp2f(s0[0][i] - mn0); ps0 += s0[0][i];
;       s0[1][i] = __builtin_amdgcn_exp2f(s0[1][i] - mn0); ps0 += s0[1][i];
;       s1[0][i] = __builtin_amdgcn_exp2f(s1[0][i] - mn1); ps1 += s1[0][i];
;       s1[1][i] = __builtin_amdgcn_exp2f(s1[1][i] - mn1); ps1 += s1[1][i];
;     }
;     l0 = l0 * al0 + ps0; l1 = l1 * al1 + ps1;
; #pragma unroll
;     for (int i = 0; i < 16; ++i) { acc0[0][i] *= al0; acc0[1][i] *= al0; acc1[0][i] *= al1; acc1[1][i] *= al1; }
; #pragma unroll
;     for (int t2 = 0; t2 < 2; ++t2)
; #pragma unroll
;       for (int j = 0; j < 2; ++j) {
;         u32x4 pk0, pk1;
;         pk0.x = pack2(s0[t2][8 * j + 0], s0[t2][8 * j + 1]); pk0.y = pack2(s0[t2][8 * j + 2], s0[t2][8 * j + 3]);
;         pk0.z = pack2(s0[t2][8 * j + 4], s0[t2][8 * j + 5]); pk0.w = pack2(s0[t2][8 * j + 6], s0[t2][8 * j + 7]);
;         pk1.x = pack2(s1[t2][8 * j + 0], s1[t2][8 * j + 1]); pk1.y = pack2(s1[t2][8 * j + 2], s1[t2][8 * j + 3]);
;         pk1.z = pack2(s1[t2][8 * j + 4], s1[t2][8 * j + 5]); pk1.w = pack2(s1[t2][8 * j + 6], s1[t2][8 * j + 7]);
;         const bf16x8 pf0 = __builtin_bit_cast(bf16x8, pk0), pf1 = __builtin_bit_cast(bf16x8, pk1);
; #pragma unroll
;         for (int dt = 0; dt < 2; ++dt) {
;           const int vsw = (((dt * 32 + r) >> 3) & 7) << 3;
;           const bfr* vrow = sV + (dt * 32 + r) * 72;
;           s16x4 lo = *(const s16x4*)(vrow + ((t2 * 32 + 16 * j + 4 * h) ^ vsw));
;           s16x4 hi = *(const s16x4*)(vrow + ((t2 * 32 + 16 * j + 4 * h + 8) ^ vsw));
;           bf16x8 vf = __builtin_shufflevector(lo, hi, 0, 1, 2, 3, 4, 5, 6, 7);
;           acc0[dt] = MFMA32(vf, pf0, acc0[dt]);
;           acc1[dt] = MFMA32(vf, pf1, acc1[dt]);
;         }
	v_sub_f32_e32 v129, v133, v129
	v_exp_f32_e32 v133, v64
	v_sub_f32_e32 v64, v87, v150
	v_exp_f32_e32 v137, v64
	v_sub_f32_e32 v64, v119, v150
	v_exp_f32_e32 v102, v64
	v_sub_f32_e32 v64, v72, v149
	v_exp_f32_e32 v103, v64
	v_sub_f32_e32 v64, v104, v149
	v_exp_f32_e32 v71, v64
	v_sub_f32_e32 v64, v88, v150
	v_exp_f32_e32 v104, v64
	v_sub_f32_e32 v64, v120, v150
	v_exp_f32_e32 v70, v64
	v_sub_f32_e32 v64, v73, v149
	v_exp_f32_e32 v118, v64
	v_sub_f32_e32 v64, v105, v149
	v_exp_f32_e32 v73, v64
	v_sub_f32_e32 v64, v89, v150
	v_exp_f32_e32 v105, v64
	v_sub_f32_e32 v64, v121, v150
	v_exp_f32_e32 v72, v64
	v_sub_f32_e32 v64, v74, v149
	v_exp_f32_e32 v119, v64
	v_sub_f32_e32 v64, v106, v149
	v_exp_f32_e32 v81, v64
	v_sub_f32_e32 v64, v90, v150
	v_exp_f32_e32 v89, v64
	v_sub_f32_e32 v64, v122, v150
	v_exp_f32_e32 v80, v64
	v_sub_f32_e32 v64, v75, v149
	v_exp_f32_e32 v90, v64
	v_sub_f32_e32 v64, v107, v149
	v_exp_f32_e32 v87, v64
	v_sub_f32_e32 v64, v91, v150
	v_exp_f32_e32 v91, v64
	v_sub_f32_e32 v64, v123, v150
	v_exp_f32_e32 v86, v64
	v_sub_f32_e32 v64, v76, v149
	v_exp_f32_e32 v74, v64
	v_sub_f32_e32 v64, v108, v149
	v_exp_f32_e32 v75, v64
	v_sub_f32_e32 v64, v92, v150
	v_exp_f32_e32 v76, v64
	v_sub_f32_e32 v64, v124, v150
	v_exp_f32_e32 v82, v64
	v_sub_f32_e32 v64, v77, v149
	v_exp_f32_e32 v77, v64
	v_sub_f32_e32 v64, v109, v149
	v_exp_f32_e32 v83, v64
	v_sub_f32_e32 v64, v93, v150
	v_exp_f32_e32 v84, v64
	v_sub_f32_e32 v64, v125, v150
	v_exp_f32_e32 v85, v64
	v_sub_f32_e32 v64, v78, v149
	v_exp_f32_e32 v78, v64
	v_sub_f32_e32 v64, v110, v149
	v_exp_f32_e32 v88, v64
	v_sub_f32_e32 v64, v94, v150
	v_exp_f32_e32 v66, v64
	v_sub_f32_e32 v64, v126, v150
	v_exp_f32_e32 v67, v64
	v_sub_f32_e32 v64, v79, v149
	v_exp_f32_e32 v68, v64
	v_sub_f32_e32 v64, v111, v149
	v_lshl_add_u32 v79, v181, 1, v144
	v_lshl_add_u32 v110, v180, 1, v144
	v_lshl_add_u32 v124, v179, 1, v145
	v_lshl_add_u32 v126, v178, 1, v145
	v_exp_f32_e32 v69, v64
	v_sub_f32_e32 v64, v95, v150
	v_sub_f32_e32 v65, v127, v150
	v_cvt_pk_bf16_f32 v92, v148, v152
	v_cvt_pk_bf16_f32 v93, v143, v147
	v_cvt_pk_bf16_f32 v94, v139, v141
	v_cvt_pk_bf16_f32 v95, v134, v136
	v_cvt_pk_bf16_f32 v106, v151, v158
	v_cvt_pk_bf16_f32 v107, v146, v138
	v_cvt_pk_bf16_f32 v108, v140, v142
	v_cvt_pk_bf16_f32 v109, v135, v137
	ds_read_b64 v[120:121], v79 offset:27648
	ds_read_b64 v[122:123], v110 offset:27648
	ds_read_b64 v[124:125], v124 offset:27648
	ds_read_b64 v[126:127], v126 offset:27648
	v_sub_f32_e32 v128, v209, v149
	v_exp_f32_e32 v130, v128
	v_sub_f32_e32 v128, v210, v150
	v_add_f32_e32 v111, 0, v151
	v_exp_f32_e32 v128, v128
	v_add_f32_e32 v110, 0, v148
	v_add_f32_e32 v111, v96, v111
	v_add_f32_e32 v110, v131, v110
	v_add_f32_e32 v111, v158, v111
	v_add_f32_e32 v110, v152, v110
	v_add_f32_e32 v111, v97, v111
	v_add_f32_e32 v110, v112, v110
	v_add_f32_e32 v111, v146, v111
	v_pk_mul_f32 v[46:47], v[46:47], v[128:129] op_sel_hi:[1,0]
	v_pk_mul_f32 v[44:45], v[44:45], v[128:129] op_sel_hi:[1,0]
	v_pk_mul_f32 v[42:43], v[42:43], v[128:129] op_sel_hi:[1,0]
	v_pk_mul_f32 v[40:41], v[40:41], v[128:129] op_sel_hi:[1,0]
	v_pk_mul_f32 v[38:39], v[38:39], v[128:129] op_sel_hi:[1,0]
	v_pk_mul_f32 v[36:37], v[36:37], v[128:129] op_sel_hi:[1,0]
	v_pk_mul_f32 v[34:35], v[34:35], v[128:129] op_sel_hi:[1,0]
	v_pk_mul_f32 v[32:33], v[32:33], v[128:129] op_sel_hi:[1,0]
	v_pk_mul_f32 v[14:15], v[14:15], v[128:129] op_sel_hi:[1,0]
	v_pk_mul_f32 v[12:13], v[12:13], v[128:129] op_sel_hi:[1,0]
	v_pk_mul_f32 v[10:11], v[10:11], v[128:129] op_sel_hi:[1,0]
	v_pk_mul_f32 v[8:9], v[8:9], v[128:129] op_sel_hi:[1,0]
	v_pk_mul_f32 v[6:7], v[6:7], v[128:129] op_sel_hi:[1,0]
	v_pk_mul_f32 v[4:5], v[4:5], v[128:129] op_sel_hi:[1,0]
	v_pk_mul_f32 v[2:3], v[2:3], v[128:129] op_sel_hi:[1,0]
	v_pk_mul_f32 v[0:1], v[0:1], v[128:129] op_sel_hi:[1,0]
	v_add_f32_e32 v110, v143, v110
	v_add_f32_e32 v111, v98, v111
	s_waitcnt lgkmcnt(2)
	v_mfma_f32_32x32x16_bf16 v[32:47], v[120:123], v[106:109], v[32:47]
	v_add_f32_e32 v110, v113, v110
	v_add_f32_e32 v110, v147, v110
	v_add_f32_e32 v110, v114, v110
	v_mul_f32_e64 v62, v62, v130
	v_mul_f32_e64 v63, v63, v130
	v_pk_mul_f32 v[60:61], v[60:61], v[130:131] op_sel_hi:[1,0]
	v_pk_mul_f32 v[58:59], v[58:59], v[130:131] op_sel_hi:[1,0]
	v_pk_mul_f32 v[56:57], v[56:57], v[130:131] op_sel_hi:[1,0]
	s_waitcnt lgkmcnt(0)
	v_mfma_f32_32x32x16_bf16 v[0:15], v[124:127], v[106:109], v[0:15]
	v_add_f32_e32 v106, v138, v111
	v_add_f32_e32 v106, v99, v106
	v_add_f32_e32 v106, v140, v106
	v_add_f32_e32 v107, v139, v110
	v_add_f32_e32 v106, v100, v106
	v_add_f32_e32 v107, v115, v107
	v_add_f32_e32 v106, v142, v106
	v_pk_mul_f32 v[54:55], v[54:55], v[130:131] op_sel_hi:[1,0]
	v_pk_mul_f32 v[52:53], v[52:53], v[130:131] op_sel_hi:[1,0]
	v_pk_mul_f32 v[50:51], v[50:51], v[130:131] op_sel_hi:[1,0]
	v_pk_mul_f32 v[48:49], v[48:49], v[130:131] op_sel_hi:[1,0]
	v_pk_mul_f32 v[30:31], v[30:31], v[130:131] op_sel_hi:[1,0]
	v_pk_mul_f32 v[28:29], v[28:29], v[130:131] op_sel_hi:[1,0]
	v_pk_mul_f32 v[26:27], v[26:27], v[130:131] op_sel_hi:[1,0]
	v_pk_mul_f32 v[24:25], v[24:25], v[130:131] op_sel_hi:[1,0]
	v_pk_mul_f32 v[22:23], v[22:23], v[130:131] op_sel_hi:[1,0]
	v_pk_mul_f32 v[20:21], v[20:21], v[130:131] op_sel_hi:[1,0]
	v_pk_mul_f32 v[18:19], v[18:19], v[130:131] op_sel_hi:[1,0]
	v_pk_mul_f32 v[16:17], v[16:17], v[130:131] op_sel_hi:[1,0]
	v_lshl_add_u32 v143, v177, 1, v144
	v_add_f32_e32 v107, v141, v107
	v_add_f32_e32 v111, v101, v106
	v_lshl_add_u32 v106, v175, 1, v145
	v_lshl_add_u32 v108, v174, 1, v145
	v_exp_f32_e32 v64, v64
	v_mfma_f32_32x32x16_bf16 v[48:63], v[120:123], v[92:95], v[48:63]
	v_add_f32_e32 v110, v116, v107
	v_add_f32_e32 v110, v134, v110
	v_add_f32_e32 v110, v132, v110
	v_add_f32_e32 v110, v136, v110
	v_add_f32_e32 v111, v135, v111
	v_add_f32_e32 v111, v117, v111
	v_exp_f32_e32 v65, v65
	v_mfma_f32_32x32x16_bf16 v[16:31], v[124:127], v[92:95], v[16:31]
	v_cvt_pk_bf16_f32 v92, v103, v118
	v_cvt_pk_bf16_f32 v93, v119, v90
	v_cvt_pk_bf16_f32 v94, v74, v77
	v_cvt_pk_bf16_f32 v95, v78, v68
	v_cvt_pk_bf16_f32 v120, v104, v105
	v_cvt_pk_bf16_f32 v121, v89, v91
	v_cvt_pk_bf16_f32 v122, v76, v84
	v_cvt_pk_bf16_f32 v123, v66, v64
	ds_read_b64 v[146:147], v143 offset:27648
	ds_read_b64 v[106:107], v106 offset:27648
	ds_read_b64 v[108:109], v108 offset:27648
	v_lshl_add_u32 v143, v176, 1, v144
	ds_read_b64 v[148:149], v143 offset:27648
	v_add_f32_e32 v124, v133, v110
	s_waitcnt lgkmcnt(0)
; DI int otid() { int t = threadIdx.x & 255; asm volatile("" : "+v"(t)); return t; }
; DI int oidx(int i) { asm volatile("" : "+s"(i)); return i; }
; DI int vhalf() { int h = __builtin_amdgcn_readfirstlane(threadIdx.x >> 8); asm volatile("" : "+s"(h)); return h; }
; #define MFMA32(a, b, c) __builtin_amdgcn_mfma_f32_32x32x16_bf16((a), (b), (c), 0, 0, 0)
; DI void attn_pass_da(const bfr* __restrict__ P, int b, int tq_wave, int qcol, int kcol, int vcol, int key0, int nkt, char* smem, f32x16 (&o0)[2], f32x16 (&o1)[2]) {
;     ...
;           acc0[dt] = MFMA32(vf, pf0, acc0[dt]);
;           acc1[dt] = MFMA32(vf, pf1, acc1[dt]);
;         }
;       }
;   }
;   l0 += __shfl_xor(l0, 32); l1 += __shfl_xor(l1, 32);
;   const float i0 = 1.f / l0, i1 = 1.f / l1;
; #pragma unroll
;   for (int i = 0; i < 16; ++i) { o0[0][i] = acc0[0][i] * i0; o0[1][i] = acc0[1][i] * i0; o1[0][i] = acc1[0][i] * i1; o1[1][i] = acc1[1][i] * i1; }
; }
; DI void store_o(bfr* O, int m, int colbase, int h, const f32x16 (&o)[2]) {
; #pragma unroll
;   for (int dt = 0; dt < 2; ++dt)
; #pragma unroll
;     for (int g4 = 0; g4 < 4; ++g4) {
;       int dv = dt * 32 + 8 * g4 + 4 * h;
;       uint2 pk; pk.x = pack2(o[dt][4 * g4], o[dt][4 * g4 + 1]); pk.y = pack2(o[dt][4 * g4 + 2], o[dt][4 * g4 + 3]);
;       *(uint2*)(O + (size_t)m * DM + colbase + dv) = pk;
;     }
; }
; DN void da_item(const Params& p, int l, int b, int hd, int tq0, int key0, int nkt, char* smem) {
;   const bfr* P = (const bfr*)(p.ws + OFF_P);
;   bfr* O = (bfr*)(p.ws + OFF_HO);
;   const int tid = otid(), lane = tid & 63, w = tid >> 6, r = lane & 31, h = lane >> 5;
;   const float* lv = p.in[oidx(22)] + l * 128;
;   float d01 = (lane < 32) ? lv[lane] * lv[32 + lane] : 0.f;
;   float d23 = (lane < 32) ? lv[64 + lane] * lv[96 + lane] : 0.f;
;   d01 = wave_sum(d01); d23 = wave_sum(d23);
;   float lam_init = 0.8f - 0.6f * expf(-0.3f * (float)l);
;   float lam = expf(d01) - expf(d23) + lam_init;
;   f32x16 o0[2], o1[2];
;   int tqw = tq0 + vhalf() * 128 + w * 32;
;   attn_pass_da(P, b, tqw, 1152 + hd * 64, 1408 + hd * 64, 1664 + hd * 64, key0, nkt, smem, o0, o1);
;   float ss = 0.f;
; #pragma unroll
;   for (int dt = 0; dt < 2; ++dt)
; #pragma unroll
;     for (int i = 0; i < 16; ++i) { float v = o0[dt][i] - lam * o1[dt][i]; o0[dt][i] = v; ss += v * v; }
	v_mfma_f32_32x32x16_bf16 v[48:63], v[146:149], v[92:95], v[48:63]
	v_add_f32_e32 v125, v137, v111
	v_lshlrev_b32_e32 v152, 1, v154
	v_mfma_f32_32x32x16_bf16 v[16:31], v[106:109], v[92:95], v[16:31]
	v_cvt_pk_bf16_f32 v92, v131, v112
	v_cvt_pk_bf16_f32 v93, v113, v114
	v_cvt_pk_bf16_f32 v94, v115, v116
	v_cvt_pk_bf16_f32 v95, v132, v133
	v_cvt_pk_bf16_f32 v96, v96, v97
	v_cvt_pk_bf16_f32 v97, v98, v99
	v_cvt_pk_bf16_f32 v98, v100, v101
	v_add_f32_e32 v100, v103, v124
	v_add_f32_e32 v100, v71, v100
	v_cvt_pk_bf16_f32 v99, v117, v102
	ds_read_b64 v[110:111], v79 offset:27712
	v_lshl_add_u32 v79, v173, 1, v144
	v_add_f32_e32 v100, v118, v100
	ds_read_b64 v[112:113], v79 offset:27648
	v_add_f32_e32 v79, v102, v125
	v_add_f32_e32 v100, v73, v100
	v_add_f32_e32 v79, v104, v79
	v_add_f32_e32 v104, v119, v100
	v_lshl_add_u32 v100, v172, 1, v145
	v_lshl_add_u32 v102, v171, 1, v145
	ds_read_b64 v[100:101], v100 offset:27648
	ds_read_b64 v[102:103], v102 offset:27648
	v_add_f32_e32 v79, v70, v79
	v_add_f32_e32 v79, v105, v79
	v_add_f32_e32 v79, v72, v79
	v_add_f32_e32 v104, v81, v104
	v_add_f32_e32 v79, v89, v79
	v_add_f32_e32 v79, v80, v79
	v_add_f32_e32 v89, v90, v104
	v_add_f32_e32 v89, v87, v89
	v_add_f32_e32 v79, v91, v79
	v_add_f32_e32 v79, v86, v79
	v_add_f32_e32 v74, v74, v89
	s_waitcnt lgkmcnt(2)
	v_mfma_f32_32x32x16_bf16 v[48:63], v[110:113], v[92:95], v[48:63]
	v_cvt_pk_bf16_f32 v90, v71, v73
	v_cvt_pk_bf16_f32 v91, v81, v87
	v_add_f32_e32 v74, v75, v74
	v_add_f32_e32 v74, v77, v74
	v_add_f32_e32 v74, v83, v74
	v_add_f32_e32 v74, v78, v74
	v_add_f32_e32 v78, v88, v74
	s_waitcnt lgkmcnt(0)
	v_mfma_f32_32x32x16_bf16 v[16:31], v[100:103], v[92:95], v[16:31]
	v_cvt_pk_bf16_f32 v92, v75, v83
	v_add_f32_e32 v75, v76, v79
	v_add_f32_e32 v75, v82, v75
	v_add_f32_e32 v75, v84, v75
	v_add_f32_e32 v79, v85, v75
	v_add_f32_e32 v66, v66, v79
	v_cvt_pk_bf16_f32 v93, v88, v69
	v_mfma_f32_32x32x16_bf16 v[32:47], v[146:149], v[120:123], v[32:47]
	v_cvt_pk_bf16_f32 v70, v70, v72
	v_cvt_pk_bf16_f32 v71, v80, v86
	v_cvt_pk_bf16_f32 v72, v82, v85
	v_cvt_pk_bf16_f32 v73, v67, v65
	v_add_f32_e32 v66, v67, v66
	v_add_f32_e32 v67, v68, v78
	v_add_f32_e32 v67, v69, v67
	v_mfma_f32_32x32x16_bf16 v[0:15], v[106:109], v[120:123], v[0:15]
	v_fmac_f32_e32 v67, v156, v130
	ds_bpermute_b32 v68, v166, v67
	v_lshl_add_u32 v80, v169, 1, v144
	v_lshl_add_u32 v74, v168, 1, v145
	v_lshl_add_u32 v76, v167, 1, v145
	ds_read_b64 v[104:105], v80 offset:27648
	ds_read_b64 v[74:75], v74 offset:27648
	ds_read_b64 v[76:77], v76 offset:27648
	v_lshl_add_u32 v80, v170, 1, v144
	v_add_f32_e32 v64, v64, v66
	ds_read_b64 v[106:107], v80 offset:27648
	v_add_f32_e32 v65, v65, v64
	v_mfma_f32_32x32x16_bf16 v[32:47], v[110:113], v[96:99], v[32:47]
	v_fmac_f32_e32 v65, v157, v128
	s_waitcnt lgkmcnt(4)
	v_add_f32_e32 v66, v67, v68
	ds_bpermute_b32 v67, v166, v65
	v_div_scale_f32 v68, s[6:7], v66, v66, 1.0
	v_rcp_f32_e32 v69, v68
	v_add_f32_e32 v64, v155, v129
	v_mfma_f32_32x32x16_bf16 v[0:15], v[100:103], v[96:99], v[0:15]
	s_waitcnt lgkmcnt(0)
	v_add_f32_e32 v65, v65, v67
	v_fma_f32 v67, -v68, v69, 1.0
	v_fmac_f32_e32 v69, v67, v69
	v_div_scale_f32 v67, vcc, 1.0, v66, 1.0
	v_mfma_f32_32x32x16_bf16 v[32:47], v[104:107], v[70:73], v[32:47]
	v_mfma_f32_32x32x16_bf16 v[0:15], v[74:77], v[70:73], v[0:15]
	v_mul_f32_e32 v70, v67, v69
	v_fma_f32 v71, -v68, v70, v67
	v_fmac_f32_e32 v70, v71, v69
	v_fma_f32 v67, -v68, v70, v67
	v_div_scale_f32 v68, s[6:7], v65, v65, 1.0
	v_rcp_f32_e32 v71, v68
	v_div_fmas_f32 v67, v67, v69, v70
	v_div_fixup_f32 v66, v67, v66, 1.0
	v_mfma_f32_32x32x16_bf16 v[48:63], v[104:107], v[90:93], v[48:63]
	v_fma_f32 v67, -v68, v71, 1.0
	v_fmac_f32_e32 v71, v67, v71
	v_div_scale_f32 v67, vcc, 1.0, v65, 1.0
	v_mul_f32_e32 v69, v67, v71
	v_fma_f32 v70, -v68, v69, v67
	v_fmac_f32_e32 v69, v70, v71
	v_fma_f32 v67, -v68, v69, v67
	v_div_fmas_f32 v67, v67, v71, v69
	v_div_fixup_f32 v68, v67, v65, 1.0
	v_mul_f32_e32 v65, v0, v68
	v_mul_f32_e32 v0, v33, v68
	v_mul_f32_e32 v67, v1, v68
	v_mul_f32_e32 v1, v34, v68
	v_mul_f32_e32 v0, v64, v0
	v_mul_f32_e32 v32, v32, v68
	v_mul_f32_e32 v69, v2, v68
	v_mul_f32_e32 v2, v35, v68
	v_mul_f32_e32 v33, v37, v68
	v_mul_f32_e32 v37, v41, v68
	v_mul_f32_e32 v41, v45, v68
	v_fma_f32 v45, v49, v66, -v0
	v_mul_f32_e32 v0, v64, v1
	v_mul_f32_e32 v70, v3, v68
	v_mul_f32_e32 v3, v36, v68
	v_mul_f32_e32 v35, v39, v68
	v_mul_f32_e32 v39, v43, v68
	v_mul_f32_e32 v43, v47, v68
	v_mul_f32_e32 v32, v64, v32
	v_fma_f32 v47, v50, v66, -v0
	v_mul_f32_e32 v0, v64, v2
	v_mul_f32_e32 v36, v40, v68
	v_mul_f32_e32 v40, v44, v68
	v_fma_f32 v44, v48, v66, -v32
	v_fma_f32 v48, v51, v66, -v0
	v_mul_f32_e32 v0, v64, v3
	v_mul_f32_e32 v34, v38, v68
	v_fma_f32 v49, v52, v66, -v0
	v_mul_f32_e32 v0, v64, v33
	s_mov_b32 s6, 23
	v_fma_f32 v50, v53, v66, -v0
	v_mul_f32_e32 v0, v64, v34
	s_ashr_i32 s7, s6, 31
	v_fma_f32 v51, v54, v66, -v0
	v_mul_f32_e32 v0, v64, v35
	s_lshl_b64 s[6:7], s[6:7], 3
	v_fma_f32 v52, v55, v66, -v0
	v_mul_f32_e32 v0, v64, v36
	s_add_u32 s6, s0, s6
	v_mul_f32_e32 v38, v42, v68
	v_fma_f32 v53, v56, v66, -v0
	v_mul_f32_e32 v0, v64, v37
	s_addc_u32 s7, s1, s7
	v_fma_f32 v54, v57, v66, -v0
	v_mul_f32_e32 v0, v64, v38
	s_load_dwordx2 s[6:7], s[6:7], 0x0
	v_mul_f32_e32 v42, v46, v68
	v_mul_f32_e32 v46, v45, v45
	v_fma_f32 v55, v58, v66, -v0
	v_mul_f32_e32 v0, v64, v39
	v_fmac_f32_e32 v46, v44, v44
	v_fma_f32 v56, v59, v66, -v0
	v_mul_f32_e32 v0, v64, v40
	v_fmac_f32_e32 v46, v47, v47
	v_fma_f32 v57, v60, v66, -v0
	v_mul_f32_e32 v0, v64, v41
	v_fmac_f32_e32 v46, v48, v48
	v_fma_f32 v58, v61, v66, -v0
	s_lshl_b64 s[8:9], s[8:9], 2
	v_lshrrev_b32_e32 v0, 3, v164
	v_fmac_f32_e32 v46, v49, v49
	s_waitcnt lgkmcnt(0)
; DI int oidx(int i) { asm volatile("" : "+s"(i)); return i; }
; DN void da_item(const Params& p, int l, int b, int hd, int tq0, int key0, int nkt, char* smem) {
;     ...
;   float ss = 0.f;
; #pragma unroll
;   for (int dt = 0; dt < 2; ++dt)
; #pragma unroll
;     for (int i = 0; i < 16; ++i) { float v = o0[dt][i] - lam * o1[dt][i]; o0[dt][i] = v; ss += v * v; }
;   ss += __shfl_xor(ss, 32);
;   float rstd = rsqrtf(ss * (1.f / 64.f) + 1e-6f) * (1.f - lam_init);
;   const float* sg = p.in[oidx(23)] + l * 64;
; #pragma unroll
;   for (int dt = 0; dt < 2; ++dt)
; #pragma unroll
;     for (int i = 0; i < 16; ++i) { int dv = dt * 32 + 8 * (i >> 2) + 4 * h + (i & 3); o0[dt][i] = o0[dt][i] * rstd * sg[dv]; }
;   store_o(O, b * TT + tqw + r, 256 + hd * 64, h, o0);
	s_add_u32 s6, s6, s8
	v_and_b32_e32 v59, 4, v0
	v_fmac_f32_e32 v46, v50, v50
	s_addc_u32 s7, s7, s9
	v_lshlrev_b32_e32 v60, 2, v59
	v_mfma_f32_32x32x16_bf16 v[16:31], v[74:77], v[90:93], v[16:31]
	v_fmac_f32_e32 v46, v51, v51
	global_load_dwordx4 v[0:3], v60, s[6:7]
	v_fmac_f32_e32 v46, v52, v52
	v_fmac_f32_e32 v46, v53, v53
	v_mul_f32_e32 v32, v64, v42
	v_fmac_f32_e32 v46, v54, v54
	v_fma_f32 v61, v62, v66, -v32
	v_mul_f32_e32 v32, v64, v43
	v_fmac_f32_e32 v46, v55, v55
	v_fma_f32 v62, v63, v66, -v32
	global_load_dwordx4 v[32:35], v60, s[6:7] offset:32
	v_fmac_f32_e32 v46, v56, v56
	v_fmac_f32_e32 v46, v57, v57
	v_fmac_f32_e32 v46, v58, v58
	v_mul_f32_e32 v36, v64, v65
	v_fmac_f32_e32 v46, v61, v61
	v_fma_f32 v63, v16, v66, -v36
	v_mul_f32_e32 v16, v64, v67
	global_load_dwordx4 v[36:39], v60, s[6:7] offset:64
	v_mul_f32_e32 v4, v4, v68
	v_fmac_f32_e32 v46, v62, v62
	v_fma_f32 v65, v17, v66, -v16
	v_mul_f32_e32 v16, v64, v69
	v_mul_f32_e32 v5, v5, v68
	v_fmac_f32_e32 v46, v63, v63
	v_fma_f32 v67, v18, v66, -v16
	v_mul_f32_e32 v16, v64, v70
	v_mul_f32_e32 v4, v64, v4
	v_fmac_f32_e32 v46, v65, v65
	v_fma_f32 v69, v19, v66, -v16
	v_fma_f32 v70, v20, v66, -v4
	v_mul_f32_e32 v4, v64, v5
	v_fmac_f32_e32 v46, v67, v67
	global_load_dwordx4 v[16:19], v60, s[6:7] offset:96
	v_fma_f32 v71, v21, v66, -v4
	v_pk_mul_f32 v[4:5], v[6:7], v[68:69] op_sel_hi:[1,0]
	v_fmac_f32_e32 v46, v69, v69
	v_pk_mul_f32 v[4:5], v[64:65], v[4:5] op_sel_hi:[0,1]
	v_fmac_f32_e32 v46, v70, v70
	v_pk_fma_f32 v[40:41], v[22:23], v[66:67], v[4:5] op_sel_hi:[1,0,1] neg_lo:[0,0,1] neg_hi:[0,0,1]
	v_pk_mul_f32 v[8:9], v[8:9], v[68:69] op_sel_hi:[1,0]
	v_fmac_f32_e32 v46, v71, v71
	v_pk_mul_f32 v[20:21], v[40:41], v[40:41]
	v_pk_mul_f32 v[8:9], v[64:65], v[8:9] op_sel_hi:[0,1]
	global_load_dwordx4 v[4:7], v60, s[6:7] offset:128
	v_add_f32_e32 v20, v20, v46
	v_pk_fma_f32 v[24:25], v[24:25], v[66:67], v[8:9] op_sel_hi:[1,0,1] neg_lo:[0,0,1] neg_hi:[0,0,1]
	v_add_f32_e32 v20, v21, v20
	v_pk_mul_f32 v[8:9], v[24:25], v[24:25]
	v_pk_mul_f32 v[12:13], v[12:13], v[68:69] op_sel_hi:[1,0]
	v_add_f32_e32 v8, v8, v20
	v_add_f32_e32 v42, v9, v8
	v_pk_mul_f32 v[8:9], v[10:11], v[68:69] op_sel_hi:[1,0]
	global_load_dwordx4 v[20:23], v60, s[6:7] offset:160
	v_pk_mul_f32 v[8:9], v[64:65], v[8:9] op_sel_hi:[0,1]
	v_pk_fma_f32 v[26:27], v[26:27], v[66:67], v[8:9] op_sel_hi:[1,0,1] neg_lo:[0,0,1] neg_hi:[0,0,1]
	v_pk_mul_f32 v[12:13], v[64:65], v[12:13] op_sel_hi:[0,1]
	v_pk_mul_f32 v[8:9], v[26:27], v[26:27]
	v_pk_fma_f32 v[28:29], v[28:29], v[66:67], v[12:13] op_sel_hi:[1,0,1] neg_lo:[0,0,1] neg_hi:[0,0,1]
	v_add_f32_e32 v8, v8, v42
	v_add_f32_e32 v42, v9, v8
	global_load_dwordx4 v[8:11], v60, s[6:7] offset:192
	v_pk_mul_f32 v[12:13], v[28:29], v[28:29]
	s_load_dwordx4 s[8:11], s[0:1], 0x100
	v_add_f32_e32 v12, v12, v42
	v_add_f32_e32 v46, v13, v12
	v_pk_mul_f32 v[42:43], v[14:15], v[68:69] op_sel_hi:[1,0]
	global_load_dwordx4 v[12:15], v60, s[6:7] offset:224
	v_pk_mul_f32 v[42:43], v[64:65], v[42:43] op_sel_hi:[0,1]
	v_pk_fma_f32 v[30:31], v[30:31], v[66:67], v[42:43] op_sel_hi:[1,0,1] neg_lo:[0,0,1] neg_hi:[0,0,1]
	s_mov_b64 s[6:7], 0x2b7c300
	v_pk_mul_f32 v[42:43], v[30:31], v[30:31]
	s_nop 0
	v_add_f32_e32 v42, v42, v46
	v_add_f32_e32 v42, v43, v42
	ds_bpermute_b32 v43, v166, v42
	s_waitcnt lgkmcnt(0)
	v_add_f32_e32 v42, v42, v43
	v_fmamk_f32 v42, v42, 0x3c800000, v186
	v_cmp_gt_f32_e32 vcc, s33, v42
	v_mul_f32_e32 v43, 0x4b800000, v42
	s_nop 0
	v_cndmask_b32_e32 v42, v42, v43, vcc
	v_rsq_f32_e32 v42, v42
	s_nop 0
	v_mul_f32_e32 v43, 0x45800000, v42
	v_cndmask_b32_e32 v42, v42, v43, vcc
	v_mul_f32_e32 v42, v162, v42
	v_mul_f32_e32 v43, v44, v42
	s_waitcnt vmcnt(7)
	v_mul_f32_e32 v43, v0, v43
	v_mul_f32_e32 v0, v45, v42
	v_mul_f32_e32 v44, v1, v0
	v_mul_f32_e32 v0, v47, v42
	v_mul_f32_e32 v45, v2, v0
	v_mul_f32_e32 v0, v48, v42
	v_mul_f32_e32 v3, v3, v0
	v_mul_f32_e32 v0, v49, v42
	s_waitcnt vmcnt(6)
	v_mul_f32_e32 v32, v32, v0
	v_mul_f32_e32 v0, v50, v42
	v_mul_f32_e32 v33, v33, v0
	v_mul_f32_e32 v0, v51, v42
	v_mul_f32_e32 v34, v34, v0
	v_mul_f32_e32 v0, v52, v42
	v_mul_f32_e32 v35, v35, v0
	v_mul_f32_e32 v0, v53, v42
	s_waitcnt vmcnt(5)
	v_mul_f32_e32 v36, v36, v0
	v_mul_f32_e32 v0, v54, v42
	v_mul_f32_e32 v37, v37, v0
	v_mul_f32_e32 v0, v55, v42
	v_mul_f32_e32 v38, v38, v0
	v_mul_f32_e32 v0, v56, v42
	v_mul_f32_e32 v39, v39, v0
	v_mul_f32_e32 v0, v57, v42
	s_waitcnt vmcnt(4)
	v_mul_f32_e32 v16, v16, v0
	v_mul_f32_e32 v0, v58, v42
	v_mul_f32_e32 v17, v17, v0
	v_mul_f32_e32 v0, v61, v42
	v_mul_f32_e32 v18, v18, v0
	v_mul_f32_e32 v0, v62, v42
	v_mul_f32_e32 v19, v19, v0
	v_mul_f32_e32 v0, v63, v42
	s_waitcnt vmcnt(3)
	v_mul_f32_e32 v46, v4, v0
	v_mul_f32_e32 v0, v65, v42
	v_mul_f32_e32 v47, v5, v0
	v_mul_f32_e32 v0, v67, v42
	v_mul_f32_e32 v6, v6, v0
	v_mul_f32_e32 v0, v69, v42
	v_mul_f32_e32 v7, v7, v0
	v_mul_f32_e32 v0, v70, v42
	s_waitcnt vmcnt(2)
	v_mul_f32_e32 v20, v20, v0
	v_mul_f32_e32 v0, v71, v42
	v_mul_f32_e32 v21, v21, v0
	v_mul_f32_e32 v0, v40, v42
	v_mul_f32_e32 v22, v22, v0
	v_mul_f32_e32 v0, v41, v42
	v_mul_f32_e32 v23, v23, v0
	v_mul_f32_e32 v0, v24, v42
	s_waitcnt vmcnt(1)
	v_mul_f32_e32 v8, v8, v0
	v_mul_f32_e32 v0, v25, v42
	v_mul_f32_e32 v9, v9, v0
	v_mul_f32_e32 v0, v26, v42
	v_mul_f32_e32 v10, v10, v0
	v_mul_f32_e32 v0, v27, v42
	v_mul_f32_e32 v11, v11, v0
	v_mul_f32_e32 v0, v28, v42
	s_waitcnt vmcnt(0)
	v_mul_f32_e32 v12, v12, v0
	v_mul_f32_e32 v0, v29, v42
	v_mul_f32_e32 v13, v13, v0
	v_mul_f32_e32 v0, v30, v42
	v_mul_f32_e32 v14, v14, v0
	v_mul_f32_e32 v0, v31, v42
	v_mul_f32_e32 v15, v15, v0
	v_and_or_b32 v0, v164, 31, v165
	v_ashrrev_i32_e32 v1, 31, v0
	v_lshlrev_b64 v[0:1], 11, v[0:1]
	v_lshl_add_u64 v[0:1], s[10:11], 0, v[0:1]
	v_lshl_add_u64 v[0:1], v[0:1], 0, v[152:153]
	v_lshlrev_b32_e32 v152, 1, v59
	v_lshl_add_u64 v[0:1], v[0:1], 0, v[152:153]
	v_lshl_add_u64 v[4:5], v[0:1], 0, s[6:7]
	s_mov_b32 s6, 0x2b7c000
	v_add_co_u32_e32 v0, vcc, s6, v0
	v_cvt_pk_bf16_f32 v2, v43, v44
	v_cvt_pk_bf16_f32 v3, v45, v3
	s_nop 1
	v_addc_co_u32_e32 v1, vcc, 0, v1, vcc
	global_store_dwordx2 v[0:1], v[2:3], off offset:768
	v_cvt_pk_bf16_f32 v0, v32, v33
	v_cvt_pk_bf16_f32 v1, v34, v35
	global_store_dwordx2 v[4:5], v[0:1], off offset:16
	v_cvt_pk_bf16_f32 v0, v36, v37
	v_cvt_pk_bf16_f32 v1, v38, v39
	global_store_dwordx2 v[4:5], v[0:1], off offset:32
	v_cvt_pk_bf16_f32 v0, v16, v17
	v_cvt_pk_bf16_f32 v1, v18, v19
	global_store_dwordx2 v[4:5], v[0:1], off offset:48
	v_cvt_pk_bf16_f32 v0, v46, v47
	v_cvt_pk_bf16_f32 v1, v6, v7
	global_store_dwordx2 v[4:5], v[0:1], off offset:64
	v_cvt_pk_bf16_f32 v0, v20, v21
	v_cvt_pk_bf16_f32 v1, v22, v23
	global_store_dwordx2 v[4:5], v[0:1], off offset:80
	v_cvt_pk_bf16_f32 v0, v8, v9
	v_cvt_pk_bf16_f32 v1, v10, v11
	global_store_dwordx2 v[4:5], v[0:1], off offset:96
	v_cvt_pk_bf16_f32 v0, v12, v13
	v_cvt_pk_bf16_f32 v1, v14, v15
	global_store_dwordx2 v[4:5], v[0:1], off offset:112
